# Strategy: one static priority raise for the younger wave half - s_setprio 1 for waves 4-7 before each GEMM K-loop, s_setprio 0 behind it
# speedup vs baseline: 1.0081x; 1.0081x over previous
.LBB0_162:
	s_ashr_i32 s19, s18, 31
	s_lshl_b64 s[20:21], s[18:19], 19
	s_add_u32 s20, s8, s20
	s_addc_u32 s21, s9, s21
	s_and_b64 s[22:23], s[4:5], exec
	s_cselect_b32 s19, s21, s27
	s_cselect_b32 s51, s20, s26
	s_ashr_i32 s17, s16, 31
	s_lshl_b64 s[22:23], s[16:17], 19
	s_add_u32 s22, s31, s22
	s_addc_u32 s23, s34, s23
	s_and_b64 s[28:29], s[4:5], exec
	s_cselect_b32 s17, s23, s25
	s_cselect_b32 s52, s22, s24
	s_add_u32 s53, s24, 0x100
	s_addc_u32 s54, s25, 0
	s_add_u32 s24, s26, 0x40080
	v_mov_b32_e32 v0, 0
	s_addc_u32 s25, s27, 0
	s_mov_b32 s55, -2
	v_mov_b32_e32 v1, v0
	v_mov_b32_e32 v2, v0
	v_mov_b32_e32 v3, v0
	v_mov_b32_e32 v4, v0
	v_mov_b32_e32 v5, v0
	v_mov_b32_e32 v6, v0
	v_mov_b32_e32 v7, v0
	v_mov_b32_e32 v16, v0
	v_mov_b32_e32 v17, v0
	s_waitcnt vmcnt(0)
	v_mov_b32_e32 v18, v0
	v_mov_b32_e32 v19, v0
	v_mov_b32_e32 v20, v0
	v_mov_b32_e32 v21, v0
	v_mov_b32_e32 v22, v0
	v_mov_b32_e32 v23, v0
	v_mov_b32_e32 v32, v0
	v_mov_b32_e32 v33, v0
	v_mov_b32_e32 v34, v0
	v_mov_b32_e32 v35, v0
	v_mov_b32_e32 v36, v0
	v_mov_b32_e32 v37, v0
	v_mov_b32_e32 v38, v0
	v_mov_b32_e32 v39, v0
	v_mov_b32_e32 v48, v0
	v_mov_b32_e32 v49, v0
	v_mov_b32_e32 v50, v0
	v_mov_b32_e32 v51, v0
	v_mov_b32_e32 v52, v0
	v_mov_b32_e32 v53, v0
	v_mov_b32_e32 v54, v0
	v_mov_b32_e32 v55, v0
	v_mov_b32_e32 v8, v0
	v_mov_b32_e32 v9, v0
	v_mov_b32_e32 v10, v0
	v_mov_b32_e32 v11, v0
	v_mov_b32_e32 v12, v0
	v_mov_b32_e32 v13, v0
	v_mov_b32_e32 v14, v0
	v_mov_b32_e32 v15, v0
	v_mov_b32_e32 v24, v0
	v_mov_b32_e32 v25, v0
	v_mov_b32_e32 v26, v0
	v_mov_b32_e32 v27, v0
	v_mov_b32_e32 v28, v0
	v_mov_b32_e32 v29, v0
	v_mov_b32_e32 v30, v0
	v_mov_b32_e32 v31, v0
	v_mov_b32_e32 v40, v0
	v_mov_b32_e32 v41, v0
	v_mov_b32_e32 v42, v0
	v_mov_b32_e32 v43, v0
	v_mov_b32_e32 v44, v0
	v_mov_b32_e32 v45, v0
	v_mov_b32_e32 v46, v0
	v_mov_b32_e32 v47, v0
	v_mov_b32_e32 v56, v0
	v_mov_b32_e32 v57, v0
	v_mov_b32_e32 v58, v0
	v_mov_b32_e32 v59, v0
	v_mov_b32_e32 v60, v0
	v_mov_b32_e32 v61, v0
	v_mov_b32_e32 v62, v0
	v_mov_b32_e32 v63, v0
	v_mov_b32_e32 v64, v0
	v_mov_b32_e32 v65, v0
	v_mov_b32_e32 v66, v0
	v_mov_b32_e32 v67, v0
	v_mov_b32_e32 v68, v0
	v_mov_b32_e32 v69, v0
	v_mov_b32_e32 v70, v0
	v_mov_b32_e32 v71, v0
	v_mov_b32_e32 v80, v0
	v_mov_b32_e32 v81, v0
	v_mov_b32_e32 v82, v0
	v_mov_b32_e32 v83, v0
	v_mov_b32_e32 v84, v0
	v_mov_b32_e32 v85, v0
	v_mov_b32_e32 v86, v0
	v_mov_b32_e32 v87, v0
	v_mov_b32_e32 v96, v0
	v_mov_b32_e32 v97, v0
	v_mov_b32_e32 v98, v0
	v_mov_b32_e32 v99, v0
	v_mov_b32_e32 v100, v0
	v_mov_b32_e32 v101, v0
	v_mov_b32_e32 v102, v0
	v_mov_b32_e32 v103, v0
	v_mov_b32_e32 v112, v0
	v_mov_b32_e32 v113, v0
	v_mov_b32_e32 v114, v0
	v_mov_b32_e32 v115, v0
	v_mov_b32_e32 v116, v0
	v_mov_b32_e32 v117, v0
	v_mov_b32_e32 v118, v0
	v_mov_b32_e32 v119, v0
	v_mov_b32_e32 v72, v0
	v_mov_b32_e32 v73, v0
	v_mov_b32_e32 v74, v0
	v_mov_b32_e32 v75, v0
	v_mov_b32_e32 v76, v0
	v_mov_b32_e32 v77, v0
	v_mov_b32_e32 v78, v0
	v_mov_b32_e32 v79, v0
	v_mov_b32_e32 v88, v0
	v_mov_b32_e32 v89, v0
	v_mov_b32_e32 v90, v0
	v_mov_b32_e32 v91, v0
	v_mov_b32_e32 v92, v0
	v_mov_b32_e32 v93, v0
	v_mov_b32_e32 v94, v0
	v_mov_b32_e32 v95, v0
	v_mov_b32_e32 v104, v0
	v_mov_b32_e32 v105, v0
	v_mov_b32_e32 v106, v0
	v_mov_b32_e32 v107, v0
	v_mov_b32_e32 v108, v0
	v_mov_b32_e32 v109, v0
	v_mov_b32_e32 v110, v0
	v_mov_b32_e32 v111, v0
	v_mov_b32_e32 v120, v0
	v_mov_b32_e32 v121, v0
	v_mov_b32_e32 v122, v0
	v_mov_b32_e32 v123, v0
	v_mov_b32_e32 v124, v0
	v_mov_b32_e32 v125, v0
	v_mov_b32_e32 v126, v0
	v_mov_b32_e32 v127, v0
	v_add_u32_e32 v204, 0x80, v128
	v_add_u32_e32 v205, 0x80, v130
	v_add_u32_e32 v220, 0x80, v132
	v_add_u32_e32 v221, 0x80, v134
	v_readfirstlane_b32 s101, v206
	s_nop 3
	s_lshr_b32 s101, s101, 8
	s_cmp_eq_u32 s101, 1
	s_cbranch_scc0 .Lprio_skip_21
	s_setprio 1
.Lprio_skip_21:
	.p2align	3
	s_nop 0
.LBB0_163:
	ds_read_b128 v[144:147], v151
	ds_read_b128 v[156:159], v151 offset:1024
	ds_read_b128 v[160:163], v151 offset:2048
	ds_read_b128 v[164:167], v151 offset:3072
	ds_read_b128 v[168:171], v152
	ds_read_b128 v[172:175], v152 offset:1024
	ds_read_b128 v[176:179], v152 offset:2048
	ds_read_b128 v[180:183], v152 offset:3072
	s_add_u32 s26, s24, 0xfffc0080
	s_addc_u32 s27, s25, -1
	s_cmp_eq_u32 s55, 12
	s_cselect_b32 s29, s19, s27
	s_cselect_b32 s28, s51, s26
	s_cselect_b32 s27, s17, s54
	s_cselect_b32 s26, s52, s53
	s_add_i32 m0, s38, 0xc000
	ds_read_b128 v[184:187], v153
	ds_read_b128 v[188:191], v153 offset:1024
	ds_read_b128 v[192:195], v153 offset:2048
	ds_read_b128 v[196:199], v153 offset:3072
	ds_read_b128 v[200:203], v153 offset:4096
	ds_read_b128 v[208:211], v153 offset:5120
	ds_read_b128 v[212:215], v153 offset:6144
	ds_read_b128 v[216:219], v153 offset:7168
	global_load_lds_dwordx4 v138, s[24:25]
	s_add_i32 m0, s38, 0xe000
	s_nop 0
	global_load_lds_dwordx4 v136, s[24:25]
	s_waitcnt vmcnt(8)
	s_waitcnt lgkmcnt(0)
	s_barrier
	s_waitcnt lgkmcnt(0)
	v_mfma_f32_16x16x32_bf16 v[124:127], v[144:147], v[184:187], v[124:127]
	v_mfma_f32_16x16x32_bf16 v[120:123], v[160:163], v[184:187], v[120:123]
	v_mfma_f32_16x16x32_bf16 v[108:111], v[144:147], v[192:195], v[108:111]
	v_mfma_f32_16x16x32_bf16 v[104:107], v[160:163], v[192:195], v[104:107]
	v_mfma_f32_16x16x32_bf16 v[92:95], v[144:147], v[200:203], v[92:95]
	v_mfma_f32_16x16x32_bf16 v[88:91], v[160:163], v[200:203], v[88:91]
	v_mfma_f32_16x16x32_bf16 v[76:79], v[144:147], v[212:215], v[76:79]
	v_mfma_f32_16x16x32_bf16 v[72:75], v[160:163], v[212:215], v[72:75]
	v_mfma_f32_16x16x32_bf16 v[124:127], v[156:159], v[188:191], v[124:127]
	v_mfma_f32_16x16x32_bf16 v[120:123], v[164:167], v[188:191], v[120:123]
	v_mfma_f32_16x16x32_bf16 v[108:111], v[156:159], v[196:199], v[108:111]
	v_mfma_f32_16x16x32_bf16 v[104:107], v[164:167], v[196:199], v[104:107]
	v_mfma_f32_16x16x32_bf16 v[92:95], v[156:159], v[208:211], v[92:95]
	v_mfma_f32_16x16x32_bf16 v[88:91], v[164:167], v[208:211], v[88:91]
	v_mfma_f32_16x16x32_bf16 v[76:79], v[156:159], v[216:219], v[76:79]
	v_mfma_f32_16x16x32_bf16 v[72:75], v[164:167], v[216:219], v[72:75]
	v_mfma_f32_16x16x32_bf16 v[116:119], v[168:171], v[184:187], v[116:119]
	v_mfma_f32_16x16x32_bf16 v[112:115], v[176:179], v[184:187], v[112:115]
	v_mfma_f32_16x16x32_bf16 v[100:103], v[168:171], v[192:195], v[100:103]
	v_mfma_f32_16x16x32_bf16 v[96:99], v[176:179], v[192:195], v[96:99]
	v_mfma_f32_16x16x32_bf16 v[84:87], v[168:171], v[200:203], v[84:87]
	v_mfma_f32_16x16x32_bf16 v[80:83], v[176:179], v[200:203], v[80:83]
	v_mfma_f32_16x16x32_bf16 v[68:71], v[168:171], v[212:215], v[68:71]
	v_mfma_f32_16x16x32_bf16 v[64:67], v[176:179], v[212:215], v[64:67]
	v_mfma_f32_16x16x32_bf16 v[116:119], v[172:175], v[188:191], v[116:119]
	v_mfma_f32_16x16x32_bf16 v[112:115], v[180:183], v[188:191], v[112:115]
	v_mfma_f32_16x16x32_bf16 v[100:103], v[172:175], v[196:199], v[100:103]
	v_mfma_f32_16x16x32_bf16 v[96:99], v[180:183], v[196:199], v[96:99]
	v_mfma_f32_16x16x32_bf16 v[84:87], v[172:175], v[208:211], v[84:87]
	v_mfma_f32_16x16x32_bf16 v[80:83], v[180:183], v[208:211], v[80:83]
	v_mfma_f32_16x16x32_bf16 v[68:71], v[172:175], v[216:219], v[68:71]
	v_mfma_f32_16x16x32_bf16 v[64:67], v[180:183], v[216:219], v[64:67]
	s_barrier
	s_add_i32 s56, s48, s35
	s_mov_b32 m0, s56
	ds_read_b128 v[184:187], v153 offset:16384
	ds_read_b128 v[188:191], v153 offset:17408
	ds_read_b128 v[192:195], v153 offset:18432
	ds_read_b128 v[196:199], v153 offset:19456
	ds_read_b128 v[200:203], v153 offset:20480
	ds_read_b128 v[208:211], v153 offset:21504
	ds_read_b128 v[212:215], v153 offset:22528
	ds_read_b128 v[216:219], v153 offset:23552
	global_load_lds_dwordx4 v132, s[26:27]
	s_add_i32 m0, s56, 0x2000
	s_add_u32 s56, s26, 0x40000
	s_mov_b64 s[98:99], s[26:27]
	s_addc_u32 s57, s27, 0
	s_add_i32 s58, s49, s35
	global_load_lds_dwordx4 v128, s[26:27]
	s_mov_b32 m0, s58
	s_mov_b64 s[100:101], s[28:29]
	global_load_lds_dwordx4 v132, s[56:57]
	s_add_i32 m0, s58, 0x2000
	s_nop 0
	global_load_lds_dwordx4 v128, s[56:57]
	s_mov_b32 m0, s38
	s_nop 0
	global_load_lds_dwordx4 v134, s[28:29]
	s_mov_b32 m0, s39
	s_nop 0
	global_load_lds_dwordx4 v130, s[28:29]
	s_waitcnt vmcnt(8)
	s_waitcnt lgkmcnt(0)
	s_barrier
	s_waitcnt lgkmcnt(0)
	v_mfma_f32_16x16x32_bf16 v[60:63], v[144:147], v[184:187], v[60:63]
	v_mfma_f32_16x16x32_bf16 v[56:59], v[160:163], v[184:187], v[56:59]
	v_mfma_f32_16x16x32_bf16 v[44:47], v[144:147], v[192:195], v[44:47]
	v_mfma_f32_16x16x32_bf16 v[40:43], v[160:163], v[192:195], v[40:43]
	v_mfma_f32_16x16x32_bf16 v[28:31], v[144:147], v[200:203], v[28:31]
	v_mfma_f32_16x16x32_bf16 v[24:27], v[160:163], v[200:203], v[24:27]
	v_mfma_f32_16x16x32_bf16 v[12:15], v[144:147], v[212:215], v[12:15]
	v_mfma_f32_16x16x32_bf16 v[8:11], v[160:163], v[212:215], v[8:11]
	v_mfma_f32_16x16x32_bf16 v[60:63], v[156:159], v[188:191], v[60:63]
	v_mfma_f32_16x16x32_bf16 v[56:59], v[164:167], v[188:191], v[56:59]
	v_mfma_f32_16x16x32_bf16 v[44:47], v[156:159], v[196:199], v[44:47]
	v_mfma_f32_16x16x32_bf16 v[40:43], v[164:167], v[196:199], v[40:43]
	v_mfma_f32_16x16x32_bf16 v[28:31], v[156:159], v[208:211], v[28:31]
	v_mfma_f32_16x16x32_bf16 v[24:27], v[164:167], v[208:211], v[24:27]
	v_mfma_f32_16x16x32_bf16 v[12:15], v[156:159], v[216:219], v[12:15]
	v_mfma_f32_16x16x32_bf16 v[8:11], v[164:167], v[216:219], v[8:11]
	v_mfma_f32_16x16x32_bf16 v[52:55], v[168:171], v[184:187], v[52:55]
	v_mfma_f32_16x16x32_bf16 v[48:51], v[176:179], v[184:187], v[48:51]
	v_mfma_f32_16x16x32_bf16 v[36:39], v[168:171], v[192:195], v[36:39]
	v_mfma_f32_16x16x32_bf16 v[32:35], v[176:179], v[192:195], v[32:35]
	v_mfma_f32_16x16x32_bf16 v[20:23], v[168:171], v[200:203], v[20:23]
	v_mfma_f32_16x16x32_bf16 v[16:19], v[176:179], v[200:203], v[16:19]
	v_mfma_f32_16x16x32_bf16 v[4:7], v[168:171], v[212:215], v[4:7]
	v_mfma_f32_16x16x32_bf16 v[0:3], v[176:179], v[212:215], v[0:3]
	v_mfma_f32_16x16x32_bf16 v[52:55], v[172:175], v[188:191], v[52:55]
	v_mfma_f32_16x16x32_bf16 v[48:51], v[180:183], v[188:191], v[48:51]
	v_mfma_f32_16x16x32_bf16 v[36:39], v[172:175], v[196:199], v[36:39]
	v_mfma_f32_16x16x32_bf16 v[32:35], v[180:183], v[196:199], v[32:35]
	v_mfma_f32_16x16x32_bf16 v[20:23], v[172:175], v[208:211], v[20:23]
	v_mfma_f32_16x16x32_bf16 v[16:19], v[180:183], v[208:211], v[16:19]
	v_mfma_f32_16x16x32_bf16 v[4:7], v[172:175], v[216:219], v[4:7]
	v_mfma_f32_16x16x32_bf16 v[0:3], v[180:183], v[216:219], v[0:3]
	s_barrier
	s_add_i32 s56, 0, 0x18000
	s_add_i32 s57, 0, 0x1c000
	v_add_u32_e32 v164, s56, v149
	v_add_u32_e32 v180, s57, v149
	ds_read_b128 v[144:147], v164
	ds_read_b128 v[156:159], v164 offset:1024
	ds_read_b128 v[160:163], v164 offset:2048
	ds_read_b128 v[164:167], v164 offset:3072
	ds_read_b128 v[168:171], v180
	ds_read_b128 v[172:175], v180 offset:1024
	ds_read_b128 v[176:179], v180 offset:2048
	ds_read_b128 v[180:183], v180 offset:3072
	s_add_u32 s28, s28, 0x40000
	s_addc_u32 s29, s29, 0
	s_mov_b32 m0, s40
	ds_read_b128 v[184:187], v153 offset:32768
	ds_read_b128 v[188:191], v153 offset:33792
	ds_read_b128 v[192:195], v153 offset:34816
	ds_read_b128 v[196:199], v153 offset:35840
	ds_read_b128 v[200:203], v153 offset:36864
	ds_read_b128 v[208:211], v153 offset:37888
	ds_read_b128 v[212:215], v153 offset:38912
	ds_read_b128 v[216:219], v153 offset:39936
	global_load_lds_dwordx4 v134, s[28:29]
	s_mov_b32 m0, s41
	s_nop 0
	global_load_lds_dwordx4 v130, s[28:29]
	s_waitcnt vmcnt(8)
	s_waitcnt lgkmcnt(0)
	s_barrier
	s_waitcnt lgkmcnt(0)
	v_mfma_f32_16x16x32_bf16 v[124:127], v[144:147], v[184:187], v[124:127]
	v_mfma_f32_16x16x32_bf16 v[120:123], v[160:163], v[184:187], v[120:123]
	v_mfma_f32_16x16x32_bf16 v[108:111], v[144:147], v[192:195], v[108:111]
	v_mfma_f32_16x16x32_bf16 v[104:107], v[160:163], v[192:195], v[104:107]
	v_mfma_f32_16x16x32_bf16 v[92:95], v[144:147], v[200:203], v[92:95]
	v_mfma_f32_16x16x32_bf16 v[88:91], v[160:163], v[200:203], v[88:91]
	v_mfma_f32_16x16x32_bf16 v[76:79], v[144:147], v[212:215], v[76:79]
	v_mfma_f32_16x16x32_bf16 v[72:75], v[160:163], v[212:215], v[72:75]
	v_mfma_f32_16x16x32_bf16 v[124:127], v[156:159], v[188:191], v[124:127]
	v_mfma_f32_16x16x32_bf16 v[120:123], v[164:167], v[188:191], v[120:123]
	v_mfma_f32_16x16x32_bf16 v[108:111], v[156:159], v[196:199], v[108:111]
	v_mfma_f32_16x16x32_bf16 v[104:107], v[164:167], v[196:199], v[104:107]
	v_mfma_f32_16x16x32_bf16 v[92:95], v[156:159], v[208:211], v[92:95]
	v_mfma_f32_16x16x32_bf16 v[88:91], v[164:167], v[208:211], v[88:91]
	v_mfma_f32_16x16x32_bf16 v[76:79], v[156:159], v[216:219], v[76:79]
	v_mfma_f32_16x16x32_bf16 v[72:75], v[164:167], v[216:219], v[72:75]
	v_mfma_f32_16x16x32_bf16 v[116:119], v[168:171], v[184:187], v[116:119]
	v_mfma_f32_16x16x32_bf16 v[112:115], v[176:179], v[184:187], v[112:115]
	v_mfma_f32_16x16x32_bf16 v[100:103], v[168:171], v[192:195], v[100:103]
	v_mfma_f32_16x16x32_bf16 v[96:99], v[176:179], v[192:195], v[96:99]
	v_mfma_f32_16x16x32_bf16 v[84:87], v[168:171], v[200:203], v[84:87]
	v_mfma_f32_16x16x32_bf16 v[80:83], v[176:179], v[200:203], v[80:83]
	v_mfma_f32_16x16x32_bf16 v[68:71], v[168:171], v[212:215], v[68:71]
	v_mfma_f32_16x16x32_bf16 v[64:67], v[176:179], v[212:215], v[64:67]
	v_mfma_f32_16x16x32_bf16 v[116:119], v[172:175], v[188:191], v[116:119]
	v_mfma_f32_16x16x32_bf16 v[112:115], v[180:183], v[188:191], v[112:115]
	v_mfma_f32_16x16x32_bf16 v[100:103], v[172:175], v[196:199], v[100:103]
	v_mfma_f32_16x16x32_bf16 v[96:99], v[180:183], v[196:199], v[96:99]
	v_mfma_f32_16x16x32_bf16 v[84:87], v[172:175], v[208:211], v[84:87]
	v_mfma_f32_16x16x32_bf16 v[80:83], v[180:183], v[208:211], v[80:83]
	v_mfma_f32_16x16x32_bf16 v[68:71], v[172:175], v[216:219], v[68:71]
	v_mfma_f32_16x16x32_bf16 v[64:67], v[180:183], v[216:219], v[64:67]
	s_barrier
	s_add_i32 s28, s56, s35
	s_mov_b32 m0, s28
	ds_read_b128 v[184:187], v153 offset:49152
	ds_read_b128 v[188:191], v153 offset:50176
	ds_read_b128 v[192:195], v153 offset:51200
	ds_read_b128 v[196:199], v153 offset:52224
	ds_read_b128 v[200:203], v153 offset:53248
	ds_read_b128 v[208:211], v153 offset:54272
	ds_read_b128 v[212:215], v153 offset:55296
	ds_read_b128 v[216:219], v153 offset:56320
	global_load_lds_dwordx4 v220, s[26:27]
	s_add_i32 m0, s28, 0x2000
	s_add_u32 s26, s26, 0x40080
	s_addc_u32 s27, s27, 0
	s_add_i32 s28, s57, s35
	global_load_lds_dwordx4 v204, s[98:99]
	s_mov_b32 m0, s28
	s_nop 0
	global_load_lds_dwordx4 v132, s[26:27]
	s_add_i32 m0, s28, 0x2000
	s_nop 0
	global_load_lds_dwordx4 v128, s[26:27]
	s_mov_b32 m0, s45
	s_nop 0
	global_load_lds_dwordx4 v221, s[100:101]
	s_mov_b32 m0, s46
	s_nop 0
	global_load_lds_dwordx4 v205, s[100:101]
	s_waitcnt vmcnt(8)
	s_waitcnt lgkmcnt(0)
	s_barrier
	s_waitcnt lgkmcnt(0)
	v_mfma_f32_16x16x32_bf16 v[60:63], v[144:147], v[184:187], v[60:63]
	v_mfma_f32_16x16x32_bf16 v[56:59], v[160:163], v[184:187], v[56:59]
	v_mfma_f32_16x16x32_bf16 v[44:47], v[144:147], v[192:195], v[44:47]
	v_mfma_f32_16x16x32_bf16 v[40:43], v[160:163], v[192:195], v[40:43]
	v_mfma_f32_16x16x32_bf16 v[28:31], v[144:147], v[200:203], v[28:31]
	v_mfma_f32_16x16x32_bf16 v[24:27], v[160:163], v[200:203], v[24:27]
	v_mfma_f32_16x16x32_bf16 v[12:15], v[144:147], v[212:215], v[12:15]
	v_mfma_f32_16x16x32_bf16 v[8:11], v[160:163], v[212:215], v[8:11]
	v_mfma_f32_16x16x32_bf16 v[60:63], v[156:159], v[188:191], v[60:63]
	v_mfma_f32_16x16x32_bf16 v[56:59], v[164:167], v[188:191], v[56:59]
	v_mfma_f32_16x16x32_bf16 v[44:47], v[156:159], v[196:199], v[44:47]
	v_mfma_f32_16x16x32_bf16 v[40:43], v[164:167], v[196:199], v[40:43]
	v_mfma_f32_16x16x32_bf16 v[28:31], v[156:159], v[208:211], v[28:31]
	v_mfma_f32_16x16x32_bf16 v[24:27], v[164:167], v[208:211], v[24:27]
	v_mfma_f32_16x16x32_bf16 v[12:15], v[156:159], v[216:219], v[12:15]
	v_mfma_f32_16x16x32_bf16 v[8:11], v[164:167], v[216:219], v[8:11]
	v_mfma_f32_16x16x32_bf16 v[52:55], v[168:171], v[184:187], v[52:55]
	v_mfma_f32_16x16x32_bf16 v[48:51], v[176:179], v[184:187], v[48:51]
	v_mfma_f32_16x16x32_bf16 v[36:39], v[168:171], v[192:195], v[36:39]
	v_mfma_f32_16x16x32_bf16 v[32:35], v[176:179], v[192:195], v[32:35]
	v_mfma_f32_16x16x32_bf16 v[20:23], v[168:171], v[200:203], v[20:23]
	v_mfma_f32_16x16x32_bf16 v[16:19], v[176:179], v[200:203], v[16:19]
	v_mfma_f32_16x16x32_bf16 v[4:7], v[168:171], v[212:215], v[4:7]
	v_mfma_f32_16x16x32_bf16 v[0:3], v[176:179], v[212:215], v[0:3]
	v_mfma_f32_16x16x32_bf16 v[52:55], v[172:175], v[188:191], v[52:55]
	v_mfma_f32_16x16x32_bf16 v[48:51], v[180:183], v[188:191], v[48:51]
	v_mfma_f32_16x16x32_bf16 v[36:39], v[172:175], v[196:199], v[36:39]
	v_mfma_f32_16x16x32_bf16 v[32:35], v[180:183], v[196:199], v[32:35]
	v_mfma_f32_16x16x32_bf16 v[20:23], v[172:175], v[208:211], v[20:23]
	v_mfma_f32_16x16x32_bf16 v[16:19], v[180:183], v[208:211], v[16:19]
	v_mfma_f32_16x16x32_bf16 v[4:7], v[172:175], v[216:219], v[4:7]
	v_mfma_f32_16x16x32_bf16 v[0:3], v[180:183], v[216:219], v[0:3]
	s_barrier
	s_add_i32 s55, s55, 2
	s_add_u32 s53, s53, 0x100
	s_addc_u32 s54, s54, 0
	s_add_u32 s24, s24, 0x100
	s_addc_u32 s25, s25, 0
	s_cmp_gt_u32 s55, 13
	s_cbranch_scc0 .LBB0_163
	s_setprio 0
	s_and_b64 vcc, exec, s[14:15]
	s_cbranch_vccz .LBB0_166
	s_barrier

.LBB0_605:
	s_ashr_i32 s21, s20, 31
	s_lshl_b64 s[22:23], s[20:21], 19
	s_add_u32 s22, s39, s22
	s_addc_u32 s23, s40, s23
	s_and_b64 s[24:25], s[6:7], exec
	s_cselect_b32 s21, s23, s29
	s_cselect_b32 s27, s22, s28
	s_ashr_i32 s19, s18, 31
	s_lshl_b64 s[24:25], s[18:19], 19
	s_add_u32 s24, s41, s24
	s_addc_u32 s25, s42, s25
	s_and_b64 s[34:35], s[6:7], exec
	s_cselect_b32 s19, s25, s31
	s_cselect_b32 s55, s24, s30
	s_add_u32 s56, s30, 0x100
	v_mov_b32_e32 v0, 0
	s_addc_u32 s57, s31, 0
	s_mov_b32 s58, -2
	v_mov_b32_e32 v1, v0
	v_mov_b32_e32 v2, v0
	v_mov_b32_e32 v3, v0
	v_mov_b32_e32 v4, v0
	v_mov_b32_e32 v5, v0
	v_mov_b32_e32 v6, v0
	v_mov_b32_e32 v7, v0
	v_mov_b32_e32 v16, v0
	v_mov_b32_e32 v17, v0
	v_mov_b32_e32 v18, v0
	v_mov_b32_e32 v19, v0
	v_mov_b32_e32 v20, v0
	v_mov_b32_e32 v21, v0
	v_mov_b32_e32 v22, v0
	v_mov_b32_e32 v23, v0
	v_mov_b32_e32 v32, v0
	v_mov_b32_e32 v33, v0
	v_mov_b32_e32 v34, v0
	v_mov_b32_e32 v35, v0
	v_mov_b32_e32 v36, v0
	v_mov_b32_e32 v37, v0
	v_mov_b32_e32 v38, v0
	v_mov_b32_e32 v39, v0
	v_mov_b32_e32 v48, v0
	v_mov_b32_e32 v49, v0
	v_mov_b32_e32 v50, v0
	v_mov_b32_e32 v51, v0
	v_mov_b32_e32 v52, v0
	v_mov_b32_e32 v53, v0
	v_mov_b32_e32 v54, v0
	v_mov_b32_e32 v55, v0
	v_mov_b32_e32 v8, v0
	v_mov_b32_e32 v9, v0
	v_mov_b32_e32 v10, v0
	v_mov_b32_e32 v11, v0
	v_mov_b32_e32 v12, v0
	v_mov_b32_e32 v13, v0
	v_mov_b32_e32 v14, v0
	v_mov_b32_e32 v15, v0
	v_mov_b32_e32 v24, v0
	v_mov_b32_e32 v25, v0
	v_mov_b32_e32 v26, v0
	v_mov_b32_e32 v27, v0
	v_mov_b32_e32 v28, v0
	v_mov_b32_e32 v29, v0
	v_mov_b32_e32 v30, v0
	v_mov_b32_e32 v31, v0
	v_mov_b32_e32 v40, v0
	v_mov_b32_e32 v41, v0
	v_mov_b32_e32 v42, v0
	v_mov_b32_e32 v43, v0
	v_mov_b32_e32 v44, v0
	v_mov_b32_e32 v45, v0
	v_mov_b32_e32 v46, v0
	v_mov_b32_e32 v47, v0
	v_mov_b32_e32 v56, v0
	v_mov_b32_e32 v57, v0
	v_mov_b32_e32 v58, v0
	v_mov_b32_e32 v59, v0
	v_mov_b32_e32 v60, v0
	v_mov_b32_e32 v61, v0
	v_mov_b32_e32 v62, v0
	v_mov_b32_e32 v63, v0
	v_mov_b32_e32 v64, v0
	v_mov_b32_e32 v65, v0
	v_mov_b32_e32 v66, v0
	v_mov_b32_e32 v67, v0
	v_mov_b32_e32 v68, v0
	v_mov_b32_e32 v69, v0
	v_mov_b32_e32 v70, v0
	v_mov_b32_e32 v71, v0
	v_mov_b32_e32 v80, v0
	v_mov_b32_e32 v81, v0
	v_mov_b32_e32 v82, v0
	v_mov_b32_e32 v83, v0
	v_mov_b32_e32 v84, v0
	v_mov_b32_e32 v85, v0
	v_mov_b32_e32 v86, v0
	v_mov_b32_e32 v87, v0
	v_mov_b32_e32 v96, v0
	v_mov_b32_e32 v97, v0
	v_mov_b32_e32 v98, v0
	v_mov_b32_e32 v99, v0
	v_mov_b32_e32 v100, v0
	v_mov_b32_e32 v101, v0
	v_mov_b32_e32 v102, v0
	v_mov_b32_e32 v103, v0
	v_mov_b32_e32 v112, v0
	v_mov_b32_e32 v113, v0
	v_mov_b32_e32 v114, v0
	v_mov_b32_e32 v115, v0
	v_mov_b32_e32 v116, v0
	v_mov_b32_e32 v117, v0
	v_mov_b32_e32 v118, v0
	v_mov_b32_e32 v119, v0
	v_mov_b32_e32 v72, v0
	v_mov_b32_e32 v73, v0
	v_mov_b32_e32 v74, v0
	v_mov_b32_e32 v75, v0
	v_mov_b32_e32 v76, v0
	v_mov_b32_e32 v77, v0
	v_mov_b32_e32 v78, v0
	v_mov_b32_e32 v79, v0
	v_mov_b32_e32 v88, v0
	v_mov_b32_e32 v89, v0
	v_mov_b32_e32 v90, v0
	v_mov_b32_e32 v91, v0
	v_mov_b32_e32 v92, v0
	v_mov_b32_e32 v93, v0
	v_mov_b32_e32 v94, v0
	v_mov_b32_e32 v95, v0
	v_mov_b32_e32 v104, v0
	v_mov_b32_e32 v105, v0
	v_mov_b32_e32 v106, v0
	v_mov_b32_e32 v107, v0
	v_mov_b32_e32 v108, v0
	v_mov_b32_e32 v109, v0
	v_mov_b32_e32 v110, v0
	v_mov_b32_e32 v111, v0
	v_mov_b32_e32 v120, v0
	v_mov_b32_e32 v121, v0
	v_mov_b32_e32 v122, v0
	v_mov_b32_e32 v123, v0
	v_mov_b32_e32 v124, v0
	v_mov_b32_e32 v125, v0
	v_mov_b32_e32 v126, v0
	v_mov_b32_e32 v127, v0
	v_add_u32_e32 v212, 0x80, v128
	v_add_u32_e32 v213, 0x80, v130
	v_readfirstlane_b32 s101, v206
	s_nop 3
	s_lshr_b32 s101, s101, 8
	s_cmp_eq_u32 s101, 1
	s_cbranch_scc0 .Lprio_skip_20
	s_setprio 1

.LBB0_606:
	ds_read_b128 v[140:143], v147
	ds_read_b128 v[150:153], v147 offset:1024
	ds_read_b128 v[154:157], v147 offset:2048
	ds_read_b128 v[158:161], v147 offset:3072
	ds_read_b128 v[162:165], v148
	ds_read_b128 v[166:169], v148 offset:1024
	ds_read_b128 v[170:173], v148 offset:2048
	ds_read_b128 v[174:177], v148 offset:3072
	s_add_u32 s30, s28, 0x100
	s_addc_u32 s31, s29, 0
	s_cmp_eq_u32 s58, 12
	s_cselect_b32 s37, s21, s31
	s_cselect_b32 s36, s27, s30
	s_cselect_b32 s35, s19, s57
	s_cselect_b32 s34, s55, s56
	s_add_i32 m0, s44, 0xc000
	ds_read_b128 v[178:181], v149
	ds_read_b128 v[182:185], v149 offset:1024
	ds_read_b128 v[186:189], v149 offset:2048
	ds_read_b128 v[190:193], v149 offset:3072
	ds_read_b128 v[194:197], v149 offset:4096
	ds_read_b128 v[198:201], v149 offset:5120
	ds_read_b128 v[202:205], v149 offset:6144
	ds_read_b128 v[208:211], v149 offset:7168
	global_load_lds_dwordx4 v134, s[28:29]
	s_add_i32 m0, s44, 0xe000
	s_nop 0
	global_load_lds_dwordx4 v132, s[28:29]
	s_waitcnt vmcnt(8)
	s_waitcnt lgkmcnt(0)
	s_barrier
	s_waitcnt lgkmcnt(0)
	v_mfma_f32_16x16x32_bf16 v[124:127], v[140:143], v[178:181], v[124:127]
	v_mfma_f32_16x16x32_bf16 v[120:123], v[154:157], v[178:181], v[120:123]
	v_mfma_f32_16x16x32_bf16 v[108:111], v[140:143], v[186:189], v[108:111]
	v_mfma_f32_16x16x32_bf16 v[104:107], v[154:157], v[186:189], v[104:107]
	v_mfma_f32_16x16x32_bf16 v[92:95], v[140:143], v[194:197], v[92:95]
	v_mfma_f32_16x16x32_bf16 v[88:91], v[154:157], v[194:197], v[88:91]
	v_mfma_f32_16x16x32_bf16 v[76:79], v[140:143], v[202:205], v[76:79]
	v_mfma_f32_16x16x32_bf16 v[72:75], v[154:157], v[202:205], v[72:75]
	v_mfma_f32_16x16x32_bf16 v[124:127], v[150:153], v[182:185], v[124:127]
	v_mfma_f32_16x16x32_bf16 v[120:123], v[158:161], v[182:185], v[120:123]
	v_mfma_f32_16x16x32_bf16 v[108:111], v[150:153], v[190:193], v[108:111]
	v_mfma_f32_16x16x32_bf16 v[104:107], v[158:161], v[190:193], v[104:107]
	v_mfma_f32_16x16x32_bf16 v[92:95], v[150:153], v[198:201], v[92:95]
	v_mfma_f32_16x16x32_bf16 v[88:91], v[158:161], v[198:201], v[88:91]
	v_mfma_f32_16x16x32_bf16 v[76:79], v[150:153], v[208:211], v[76:79]
	v_mfma_f32_16x16x32_bf16 v[72:75], v[158:161], v[208:211], v[72:75]
	v_mfma_f32_16x16x32_bf16 v[116:119], v[162:165], v[178:181], v[116:119]
	v_mfma_f32_16x16x32_bf16 v[112:115], v[170:173], v[178:181], v[112:115]
	v_mfma_f32_16x16x32_bf16 v[100:103], v[162:165], v[186:189], v[100:103]
	v_mfma_f32_16x16x32_bf16 v[96:99], v[170:173], v[186:189], v[96:99]
	v_mfma_f32_16x16x32_bf16 v[84:87], v[162:165], v[194:197], v[84:87]
	v_mfma_f32_16x16x32_bf16 v[80:83], v[170:173], v[194:197], v[80:83]
	v_mfma_f32_16x16x32_bf16 v[68:71], v[162:165], v[202:205], v[68:71]
	v_mfma_f32_16x16x32_bf16 v[64:67], v[170:173], v[202:205], v[64:67]
	v_mfma_f32_16x16x32_bf16 v[116:119], v[166:169], v[182:185], v[116:119]
	v_mfma_f32_16x16x32_bf16 v[112:115], v[174:177], v[182:185], v[112:115]
	v_mfma_f32_16x16x32_bf16 v[100:103], v[166:169], v[190:193], v[100:103]
	v_mfma_f32_16x16x32_bf16 v[96:99], v[174:177], v[190:193], v[96:99]
	v_mfma_f32_16x16x32_bf16 v[84:87], v[166:169], v[198:201], v[84:87]
	v_mfma_f32_16x16x32_bf16 v[80:83], v[174:177], v[198:201], v[80:83]
	v_mfma_f32_16x16x32_bf16 v[68:71], v[166:169], v[208:211], v[68:71]
	v_mfma_f32_16x16x32_bf16 v[64:67], v[174:177], v[208:211], v[64:67]
	s_barrier
	s_add_i32 s28, s52, s43
	s_mov_b32 m0, s28
	ds_read_b128 v[178:181], v149 offset:16384
	ds_read_b128 v[182:185], v149 offset:17408
	ds_read_b128 v[186:189], v149 offset:18432
	ds_read_b128 v[190:193], v149 offset:19456
	ds_read_b128 v[194:197], v149 offset:20480
	ds_read_b128 v[198:201], v149 offset:21504
	ds_read_b128 v[202:205], v149 offset:22528
	ds_read_b128 v[208:211], v149 offset:23552
	global_load_lds_dwordx4 v128, s[34:35]
	s_add_i32 m0, s28, 0x2000
	s_add_u32 s28, s34, 0x40000
	s_mov_b64 s[98:99], s[34:35]
	s_addc_u32 s29, s35, 0
	s_add_i32 s59, s53, s43
	global_load_lds_dwordx4 v130, s[34:35]
	s_mov_b32 m0, s59
	s_nop 0
	global_load_lds_dwordx4 v128, s[28:29]
	s_add_i32 m0, s59, 0x2000
	s_nop 0
	global_load_lds_dwordx4 v130, s[28:29]
	s_mov_b32 m0, s44
	s_nop 0
	global_load_lds_dwordx4 v128, s[36:37]
	s_mov_b32 m0, s45
	s_nop 0
	global_load_lds_dwordx4 v130, s[36:37]
	s_waitcnt vmcnt(8)
	s_waitcnt lgkmcnt(0)
	s_barrier
	s_waitcnt lgkmcnt(0)
	v_mfma_f32_16x16x32_bf16 v[60:63], v[140:143], v[178:181], v[60:63]
	v_mfma_f32_16x16x32_bf16 v[56:59], v[154:157], v[178:181], v[56:59]
	v_mfma_f32_16x16x32_bf16 v[44:47], v[140:143], v[186:189], v[44:47]
	v_mfma_f32_16x16x32_bf16 v[40:43], v[154:157], v[186:189], v[40:43]
	v_mfma_f32_16x16x32_bf16 v[28:31], v[140:143], v[194:197], v[28:31]
	v_mfma_f32_16x16x32_bf16 v[24:27], v[154:157], v[194:197], v[24:27]
	v_mfma_f32_16x16x32_bf16 v[12:15], v[140:143], v[202:205], v[12:15]
	v_mfma_f32_16x16x32_bf16 v[8:11], v[154:157], v[202:205], v[8:11]
	v_mfma_f32_16x16x32_bf16 v[60:63], v[150:153], v[182:185], v[60:63]
	v_mfma_f32_16x16x32_bf16 v[56:59], v[158:161], v[182:185], v[56:59]
	v_mfma_f32_16x16x32_bf16 v[44:47], v[150:153], v[190:193], v[44:47]
	v_mfma_f32_16x16x32_bf16 v[40:43], v[158:161], v[190:193], v[40:43]
	v_mfma_f32_16x16x32_bf16 v[28:31], v[150:153], v[198:201], v[28:31]
	v_mfma_f32_16x16x32_bf16 v[24:27], v[158:161], v[198:201], v[24:27]
	v_mfma_f32_16x16x32_bf16 v[12:15], v[150:153], v[208:211], v[12:15]
	v_mfma_f32_16x16x32_bf16 v[8:11], v[158:161], v[208:211], v[8:11]
	v_mfma_f32_16x16x32_bf16 v[52:55], v[162:165], v[178:181], v[52:55]
	v_mfma_f32_16x16x32_bf16 v[48:51], v[170:173], v[178:181], v[48:51]
	v_mfma_f32_16x16x32_bf16 v[36:39], v[162:165], v[186:189], v[36:39]
	v_mfma_f32_16x16x32_bf16 v[32:35], v[170:173], v[186:189], v[32:35]
	v_mfma_f32_16x16x32_bf16 v[20:23], v[162:165], v[194:197], v[20:23]
	v_mfma_f32_16x16x32_bf16 v[16:19], v[170:173], v[194:197], v[16:19]
	v_mfma_f32_16x16x32_bf16 v[4:7], v[162:165], v[202:205], v[4:7]
	v_mfma_f32_16x16x32_bf16 v[0:3], v[170:173], v[202:205], v[0:3]
	v_mfma_f32_16x16x32_bf16 v[52:55], v[166:169], v[182:185], v[52:55]
	v_mfma_f32_16x16x32_bf16 v[48:51], v[174:177], v[182:185], v[48:51]
	v_mfma_f32_16x16x32_bf16 v[36:39], v[166:169], v[190:193], v[36:39]
	v_mfma_f32_16x16x32_bf16 v[32:35], v[174:177], v[190:193], v[32:35]
	v_mfma_f32_16x16x32_bf16 v[20:23], v[166:169], v[198:201], v[20:23]
	v_mfma_f32_16x16x32_bf16 v[16:19], v[174:177], v[198:201], v[16:19]
	v_mfma_f32_16x16x32_bf16 v[4:7], v[166:169], v[208:211], v[4:7]
	v_mfma_f32_16x16x32_bf16 v[0:3], v[174:177], v[208:211], v[0:3]
	s_barrier
	s_add_i32 s59, 0, 0x18000
	s_add_i32 s60, 0, 0x1c000
	v_add_u32_e32 v158, s59, v145
	v_add_u32_e32 v174, s60, v145
	ds_read_b128 v[140:143], v158
	ds_read_b128 v[150:153], v158 offset:1024
	ds_read_b128 v[154:157], v158 offset:2048
	ds_read_b128 v[158:161], v158 offset:3072
	ds_read_b128 v[162:165], v174
	ds_read_b128 v[166:169], v174 offset:1024
	ds_read_b128 v[170:173], v174 offset:2048
	ds_read_b128 v[174:177], v174 offset:3072
	s_add_u32 s28, s36, 0x40000
	s_addc_u32 s29, s37, 0
	s_mov_b32 m0, s46
	ds_read_b128 v[178:181], v149 offset:32768
	ds_read_b128 v[182:185], v149 offset:33792
	ds_read_b128 v[186:189], v149 offset:34816
	ds_read_b128 v[190:193], v149 offset:35840
	ds_read_b128 v[194:197], v149 offset:36864
	ds_read_b128 v[198:201], v149 offset:37888
	ds_read_b128 v[202:205], v149 offset:38912
	ds_read_b128 v[208:211], v149 offset:39936
	global_load_lds_dwordx4 v128, s[28:29]
	s_mov_b32 m0, s47
	s_nop 0
	global_load_lds_dwordx4 v130, s[28:29]
	s_waitcnt vmcnt(8)
	s_waitcnt lgkmcnt(0)
	s_barrier
	s_waitcnt lgkmcnt(0)
	v_mfma_f32_16x16x32_bf16 v[124:127], v[140:143], v[178:181], v[124:127]
	v_mfma_f32_16x16x32_bf16 v[120:123], v[154:157], v[178:181], v[120:123]
	v_mfma_f32_16x16x32_bf16 v[108:111], v[140:143], v[186:189], v[108:111]
	v_mfma_f32_16x16x32_bf16 v[104:107], v[154:157], v[186:189], v[104:107]
	v_mfma_f32_16x16x32_bf16 v[92:95], v[140:143], v[194:197], v[92:95]
	v_mfma_f32_16x16x32_bf16 v[88:91], v[154:157], v[194:197], v[88:91]
	v_mfma_f32_16x16x32_bf16 v[76:79], v[140:143], v[202:205], v[76:79]
	v_mfma_f32_16x16x32_bf16 v[72:75], v[154:157], v[202:205], v[72:75]
	v_mfma_f32_16x16x32_bf16 v[124:127], v[150:153], v[182:185], v[124:127]
	v_mfma_f32_16x16x32_bf16 v[120:123], v[158:161], v[182:185], v[120:123]
	v_mfma_f32_16x16x32_bf16 v[108:111], v[150:153], v[190:193], v[108:111]
	v_mfma_f32_16x16x32_bf16 v[104:107], v[158:161], v[190:193], v[104:107]
	v_mfma_f32_16x16x32_bf16 v[92:95], v[150:153], v[198:201], v[92:95]
	v_mfma_f32_16x16x32_bf16 v[88:91], v[158:161], v[198:201], v[88:91]
	v_mfma_f32_16x16x32_bf16 v[76:79], v[150:153], v[208:211], v[76:79]
	v_mfma_f32_16x16x32_bf16 v[72:75], v[158:161], v[208:211], v[72:75]
	v_mfma_f32_16x16x32_bf16 v[116:119], v[162:165], v[178:181], v[116:119]
	v_mfma_f32_16x16x32_bf16 v[112:115], v[170:173], v[178:181], v[112:115]
	v_mfma_f32_16x16x32_bf16 v[100:103], v[162:165], v[186:189], v[100:103]
	v_mfma_f32_16x16x32_bf16 v[96:99], v[170:173], v[186:189], v[96:99]
	v_mfma_f32_16x16x32_bf16 v[84:87], v[162:165], v[194:197], v[84:87]
	v_mfma_f32_16x16x32_bf16 v[80:83], v[170:173], v[194:197], v[80:83]
	v_mfma_f32_16x16x32_bf16 v[68:71], v[162:165], v[202:205], v[68:71]
	v_mfma_f32_16x16x32_bf16 v[64:67], v[170:173], v[202:205], v[64:67]
	v_mfma_f32_16x16x32_bf16 v[116:119], v[166:169], v[182:185], v[116:119]
	v_mfma_f32_16x16x32_bf16 v[112:115], v[174:177], v[182:185], v[112:115]
	v_mfma_f32_16x16x32_bf16 v[100:103], v[166:169], v[190:193], v[100:103]
	v_mfma_f32_16x16x32_bf16 v[96:99], v[174:177], v[190:193], v[96:99]
	v_mfma_f32_16x16x32_bf16 v[84:87], v[166:169], v[198:201], v[84:87]
	v_mfma_f32_16x16x32_bf16 v[80:83], v[174:177], v[198:201], v[80:83]
	v_mfma_f32_16x16x32_bf16 v[68:71], v[166:169], v[208:211], v[68:71]
	v_mfma_f32_16x16x32_bf16 v[64:67], v[174:177], v[208:211], v[64:67]
	s_barrier
	s_add_i32 s28, s59, s43
	s_mov_b32 m0, s28
	ds_read_b128 v[178:181], v149 offset:49152
	ds_read_b128 v[182:185], v149 offset:50176
	ds_read_b128 v[186:189], v149 offset:51200
	ds_read_b128 v[190:193], v149 offset:52224
	ds_read_b128 v[194:197], v149 offset:53248
	ds_read_b128 v[198:201], v149 offset:54272
	ds_read_b128 v[202:205], v149 offset:55296
	ds_read_b128 v[208:211], v149 offset:56320
	global_load_lds_dwordx4 v212, s[34:35]
	s_add_i32 m0, s28, 0x2000
	s_add_u32 s28, s34, 0x40080
	s_addc_u32 s29, s35, 0
	s_add_i32 s34, s60, s43
	global_load_lds_dwordx4 v213, s[98:99]
	s_mov_b32 m0, s34
	s_nop 0
	global_load_lds_dwordx4 v128, s[28:29]
	s_add_i32 m0, s34, 0x2000
	s_nop 0
	global_load_lds_dwordx4 v130, s[28:29]
	s_mov_b32 m0, s49
	s_nop 0
	global_load_lds_dwordx4 v212, s[36:37]
	s_mov_b32 m0, s50
	s_nop 0
	global_load_lds_dwordx4 v213, s[36:37]
	s_waitcnt vmcnt(8)
	s_waitcnt lgkmcnt(0)
	s_barrier
	s_waitcnt lgkmcnt(0)
	v_mfma_f32_16x16x32_bf16 v[60:63], v[140:143], v[178:181], v[60:63]
	v_mfma_f32_16x16x32_bf16 v[56:59], v[154:157], v[178:181], v[56:59]
	v_mfma_f32_16x16x32_bf16 v[44:47], v[140:143], v[186:189], v[44:47]
	v_mfma_f32_16x16x32_bf16 v[40:43], v[154:157], v[186:189], v[40:43]
	v_mfma_f32_16x16x32_bf16 v[28:31], v[140:143], v[194:197], v[28:31]
	v_mfma_f32_16x16x32_bf16 v[24:27], v[154:157], v[194:197], v[24:27]
	v_mfma_f32_16x16x32_bf16 v[12:15], v[140:143], v[202:205], v[12:15]
	v_mfma_f32_16x16x32_bf16 v[8:11], v[154:157], v[202:205], v[8:11]
	v_mfma_f32_16x16x32_bf16 v[60:63], v[150:153], v[182:185], v[60:63]
	v_mfma_f32_16x16x32_bf16 v[56:59], v[158:161], v[182:185], v[56:59]
	v_mfma_f32_16x16x32_bf16 v[44:47], v[150:153], v[190:193], v[44:47]
	v_mfma_f32_16x16x32_bf16 v[40:43], v[158:161], v[190:193], v[40:43]
	v_mfma_f32_16x16x32_bf16 v[28:31], v[150:153], v[198:201], v[28:31]
	v_mfma_f32_16x16x32_bf16 v[24:27], v[158:161], v[198:201], v[24:27]
	v_mfma_f32_16x16x32_bf16 v[12:15], v[150:153], v[208:211], v[12:15]
	v_mfma_f32_16x16x32_bf16 v[8:11], v[158:161], v[208:211], v[8:11]
	v_mfma_f32_16x16x32_bf16 v[52:55], v[162:165], v[178:181], v[52:55]
	v_mfma_f32_16x16x32_bf16 v[48:51], v[170:173], v[178:181], v[48:51]
	v_mfma_f32_16x16x32_bf16 v[36:39], v[162:165], v[186:189], v[36:39]
	v_mfma_f32_16x16x32_bf16 v[32:35], v[170:173], v[186:189], v[32:35]
	v_mfma_f32_16x16x32_bf16 v[20:23], v[162:165], v[194:197], v[20:23]
	v_mfma_f32_16x16x32_bf16 v[16:19], v[170:173], v[194:197], v[16:19]
	v_mfma_f32_16x16x32_bf16 v[4:7], v[162:165], v[202:205], v[4:7]
	v_mfma_f32_16x16x32_bf16 v[0:3], v[170:173], v[202:205], v[0:3]
	v_mfma_f32_16x16x32_bf16 v[52:55], v[166:169], v[182:185], v[52:55]
	v_mfma_f32_16x16x32_bf16 v[48:51], v[174:177], v[182:185], v[48:51]
	v_mfma_f32_16x16x32_bf16 v[36:39], v[166:169], v[190:193], v[36:39]
	v_mfma_f32_16x16x32_bf16 v[32:35], v[174:177], v[190:193], v[32:35]
	v_mfma_f32_16x16x32_bf16 v[20:23], v[166:169], v[198:201], v[20:23]
	v_mfma_f32_16x16x32_bf16 v[16:19], v[174:177], v[198:201], v[16:19]
	v_mfma_f32_16x16x32_bf16 v[4:7], v[166:169], v[208:211], v[4:7]
	v_mfma_f32_16x16x32_bf16 v[0:3], v[174:177], v[208:211], v[0:3]
	s_barrier
	s_add_i32 s58, s58, 2
	s_add_u32 s56, s56, 0x100
	s_addc_u32 s57, s57, 0
	s_cmp_gt_u32 s58, 13
	s_mov_b64 s[28:29], s[30:31]
	s_cbranch_scc0 .LBB0_606
	s_setprio 0
	s_and_b64 vcc, exec, s[16:17]
	s_cbranch_vccz .LBB0_609
	s_barrier

.LBB0_698:
	s_ashr_i32 s21, s20, 31
	s_lshl_b64 s[22:23], s[20:21], 19
	s_add_u32 s22, s8, s22
	s_addc_u32 s23, s9, s23
	s_and_b64 s[24:25], s[4:5], exec
	s_cselect_b32 s21, s23, s29
	s_cselect_b32 s49, s22, s28
	s_ashr_i32 s19, s18, 31
	s_lshl_b64 s[24:25], s[18:19], 19
	s_add_u32 s24, s36, s24
	s_addc_u32 s25, s37, s25
	s_and_b64 s[30:31], s[4:5], exec
	s_cselect_b32 s19, s25, s27
	s_cselect_b32 s50, s24, s26
	s_add_u32 s51, s26, 0x100
	s_addc_u32 s52, s27, 0
	s_add_u32 s26, s28, 0x40080
	v_mov_b32_e32 v0, 0
	s_addc_u32 s27, s29, 0
	s_mov_b32 s53, -2
	v_mov_b32_e32 v1, v0
	v_mov_b32_e32 v2, v0
	v_mov_b32_e32 v3, v0
	v_mov_b32_e32 v4, v0
	v_mov_b32_e32 v5, v0
	v_mov_b32_e32 v6, v0
	v_mov_b32_e32 v7, v0
	v_mov_b32_e32 v16, v0
	v_mov_b32_e32 v17, v0
	v_mov_b32_e32 v18, v0
	v_mov_b32_e32 v19, v0
	v_mov_b32_e32 v20, v0
	v_mov_b32_e32 v21, v0
	v_mov_b32_e32 v22, v0
	v_mov_b32_e32 v23, v0
	v_mov_b32_e32 v32, v0
	v_mov_b32_e32 v33, v0
	v_mov_b32_e32 v34, v0
	v_mov_b32_e32 v35, v0
	v_mov_b32_e32 v36, v0
	v_mov_b32_e32 v37, v0
	v_mov_b32_e32 v38, v0
	v_mov_b32_e32 v39, v0
	v_mov_b32_e32 v48, v0
	v_mov_b32_e32 v49, v0
	v_mov_b32_e32 v50, v0
	v_mov_b32_e32 v51, v0
	v_mov_b32_e32 v52, v0
	v_mov_b32_e32 v53, v0
	v_mov_b32_e32 v54, v0
	v_mov_b32_e32 v55, v0
	v_mov_b32_e32 v8, v0
	v_mov_b32_e32 v9, v0
	v_mov_b32_e32 v10, v0
	v_mov_b32_e32 v11, v0
	v_mov_b32_e32 v12, v0
	v_mov_b32_e32 v13, v0
	v_mov_b32_e32 v14, v0
	v_mov_b32_e32 v15, v0
	v_mov_b32_e32 v24, v0
	v_mov_b32_e32 v25, v0
	v_mov_b32_e32 v26, v0
	v_mov_b32_e32 v27, v0
	v_mov_b32_e32 v28, v0
	v_mov_b32_e32 v29, v0
	v_mov_b32_e32 v30, v0
	v_mov_b32_e32 v31, v0
	v_mov_b32_e32 v40, v0
	v_mov_b32_e32 v41, v0
	v_mov_b32_e32 v42, v0
	v_mov_b32_e32 v43, v0
	v_mov_b32_e32 v44, v0
	v_mov_b32_e32 v45, v0
	v_mov_b32_e32 v46, v0
	v_mov_b32_e32 v47, v0
	v_mov_b32_e32 v56, v0
	v_mov_b32_e32 v57, v0
	v_mov_b32_e32 v58, v0
	v_mov_b32_e32 v59, v0
	v_mov_b32_e32 v60, v0
	v_mov_b32_e32 v61, v0
	v_mov_b32_e32 v62, v0
	v_mov_b32_e32 v63, v0
	v_mov_b32_e32 v64, v0
	v_mov_b32_e32 v65, v0
	v_mov_b32_e32 v66, v0
	v_mov_b32_e32 v67, v0
	v_mov_b32_e32 v68, v0
	v_mov_b32_e32 v69, v0
	v_mov_b32_e32 v70, v0
	v_mov_b32_e32 v71, v0
	v_mov_b32_e32 v80, v0
	v_mov_b32_e32 v81, v0
	v_mov_b32_e32 v82, v0
	v_mov_b32_e32 v83, v0
	v_mov_b32_e32 v84, v0
	v_mov_b32_e32 v85, v0
	v_mov_b32_e32 v86, v0
	v_mov_b32_e32 v87, v0
	v_mov_b32_e32 v96, v0
	v_mov_b32_e32 v97, v0
	v_mov_b32_e32 v98, v0
	v_mov_b32_e32 v99, v0
	v_mov_b32_e32 v100, v0
	v_mov_b32_e32 v101, v0
	v_mov_b32_e32 v102, v0
	v_mov_b32_e32 v103, v0
	v_mov_b32_e32 v112, v0
	v_mov_b32_e32 v113, v0
	v_mov_b32_e32 v114, v0
	v_mov_b32_e32 v115, v0
	v_mov_b32_e32 v116, v0
	v_mov_b32_e32 v117, v0
	v_mov_b32_e32 v118, v0
	v_mov_b32_e32 v119, v0
	v_mov_b32_e32 v72, v0
	v_mov_b32_e32 v73, v0
	v_mov_b32_e32 v74, v0
	v_mov_b32_e32 v75, v0
	v_mov_b32_e32 v76, v0
	v_mov_b32_e32 v77, v0
	v_mov_b32_e32 v78, v0
	v_mov_b32_e32 v79, v0
	v_mov_b32_e32 v88, v0
	v_mov_b32_e32 v89, v0
	v_mov_b32_e32 v90, v0
	v_mov_b32_e32 v91, v0
	v_mov_b32_e32 v92, v0
	v_mov_b32_e32 v93, v0
	v_mov_b32_e32 v94, v0
	v_mov_b32_e32 v95, v0
	v_mov_b32_e32 v104, v0
	v_mov_b32_e32 v105, v0
	v_mov_b32_e32 v106, v0
	v_mov_b32_e32 v107, v0
	v_mov_b32_e32 v108, v0
	v_mov_b32_e32 v109, v0
	v_mov_b32_e32 v110, v0
	v_mov_b32_e32 v111, v0
	v_mov_b32_e32 v120, v0
	v_mov_b32_e32 v121, v0
	v_mov_b32_e32 v122, v0
	v_mov_b32_e32 v123, v0
	v_mov_b32_e32 v124, v0
	v_mov_b32_e32 v125, v0
	v_mov_b32_e32 v126, v0
	v_mov_b32_e32 v127, v0
	v_add_u32_e32 v204, 0x80, v128
	v_add_u32_e32 v205, 0x80, v130
	v_add_u32_e32 v220, 0x80, v132
	v_add_u32_e32 v221, 0x80, v134
	v_readfirstlane_b32 s101, v206
	s_nop 3
	s_lshr_b32 s101, s101, 8
	s_cmp_eq_u32 s101, 1
	s_cbranch_scc0 .Lprio_skip_19
	s_setprio 1

.LBB0_699:
	ds_read_b128 v[144:147], v151
	ds_read_b128 v[156:159], v151 offset:1024
	ds_read_b128 v[160:163], v151 offset:2048
	ds_read_b128 v[164:167], v151 offset:3072
	ds_read_b128 v[168:171], v152
	ds_read_b128 v[172:175], v152 offset:1024
	ds_read_b128 v[176:179], v152 offset:2048
	ds_read_b128 v[180:183], v152 offset:3072
	s_add_u32 s28, s26, 0xfffc0080
	s_addc_u32 s29, s27, -1
	s_cmp_eq_u32 s53, 12
	s_cselect_b32 s31, s21, s29
	s_cselect_b32 s30, s49, s28
	s_cselect_b32 s29, s19, s52
	s_cselect_b32 s28, s50, s51
	s_add_i32 m0, s39, 0xc000
	ds_read_b128 v[184:187], v153
	ds_read_b128 v[188:191], v153 offset:1024
	ds_read_b128 v[192:195], v153 offset:2048
	ds_read_b128 v[196:199], v153 offset:3072
	ds_read_b128 v[200:203], v153 offset:4096
	ds_read_b128 v[208:211], v153 offset:5120
	ds_read_b128 v[212:215], v153 offset:6144
	ds_read_b128 v[216:219], v153 offset:7168
	global_load_lds_dwordx4 v138, s[26:27]
	s_add_i32 m0, s39, 0xe000
	s_nop 0
	global_load_lds_dwordx4 v136, s[26:27]
	s_waitcnt vmcnt(8)
	s_waitcnt lgkmcnt(0)
	s_barrier
	s_waitcnt lgkmcnt(0)
	v_mfma_f32_16x16x32_bf16 v[124:127], v[144:147], v[184:187], v[124:127]
	v_mfma_f32_16x16x32_bf16 v[120:123], v[160:163], v[184:187], v[120:123]
	v_mfma_f32_16x16x32_bf16 v[108:111], v[144:147], v[192:195], v[108:111]
	v_mfma_f32_16x16x32_bf16 v[104:107], v[160:163], v[192:195], v[104:107]
	v_mfma_f32_16x16x32_bf16 v[92:95], v[144:147], v[200:203], v[92:95]
	v_mfma_f32_16x16x32_bf16 v[88:91], v[160:163], v[200:203], v[88:91]
	v_mfma_f32_16x16x32_bf16 v[76:79], v[144:147], v[212:215], v[76:79]
	v_mfma_f32_16x16x32_bf16 v[72:75], v[160:163], v[212:215], v[72:75]
	v_mfma_f32_16x16x32_bf16 v[124:127], v[156:159], v[188:191], v[124:127]
	v_mfma_f32_16x16x32_bf16 v[120:123], v[164:167], v[188:191], v[120:123]
	v_mfma_f32_16x16x32_bf16 v[108:111], v[156:159], v[196:199], v[108:111]
	v_mfma_f32_16x16x32_bf16 v[104:107], v[164:167], v[196:199], v[104:107]
	v_mfma_f32_16x16x32_bf16 v[92:95], v[156:159], v[208:211], v[92:95]
	v_mfma_f32_16x16x32_bf16 v[88:91], v[164:167], v[208:211], v[88:91]
	v_mfma_f32_16x16x32_bf16 v[76:79], v[156:159], v[216:219], v[76:79]
	v_mfma_f32_16x16x32_bf16 v[72:75], v[164:167], v[216:219], v[72:75]
	v_mfma_f32_16x16x32_bf16 v[116:119], v[168:171], v[184:187], v[116:119]
	v_mfma_f32_16x16x32_bf16 v[112:115], v[176:179], v[184:187], v[112:115]
	v_mfma_f32_16x16x32_bf16 v[100:103], v[168:171], v[192:195], v[100:103]
	v_mfma_f32_16x16x32_bf16 v[96:99], v[176:179], v[192:195], v[96:99]
	v_mfma_f32_16x16x32_bf16 v[84:87], v[168:171], v[200:203], v[84:87]
	v_mfma_f32_16x16x32_bf16 v[80:83], v[176:179], v[200:203], v[80:83]
	v_mfma_f32_16x16x32_bf16 v[68:71], v[168:171], v[212:215], v[68:71]
	v_mfma_f32_16x16x32_bf16 v[64:67], v[176:179], v[212:215], v[64:67]
	v_mfma_f32_16x16x32_bf16 v[116:119], v[172:175], v[188:191], v[116:119]
	v_mfma_f32_16x16x32_bf16 v[112:115], v[180:183], v[188:191], v[112:115]
	v_mfma_f32_16x16x32_bf16 v[100:103], v[172:175], v[196:199], v[100:103]
	v_mfma_f32_16x16x32_bf16 v[96:99], v[180:183], v[196:199], v[96:99]
	v_mfma_f32_16x16x32_bf16 v[84:87], v[172:175], v[208:211], v[84:87]
	v_mfma_f32_16x16x32_bf16 v[80:83], v[180:183], v[208:211], v[80:83]
	v_mfma_f32_16x16x32_bf16 v[68:71], v[172:175], v[216:219], v[68:71]
	v_mfma_f32_16x16x32_bf16 v[64:67], v[180:183], v[216:219], v[64:67]
	s_barrier
	s_add_i32 s54, s46, s38
	s_mov_b32 m0, s54
	ds_read_b128 v[184:187], v153 offset:16384
	ds_read_b128 v[188:191], v153 offset:17408
	ds_read_b128 v[192:195], v153 offset:18432
	ds_read_b128 v[196:199], v153 offset:19456
	ds_read_b128 v[200:203], v153 offset:20480
	ds_read_b128 v[208:211], v153 offset:21504
	ds_read_b128 v[212:215], v153 offset:22528
	ds_read_b128 v[216:219], v153 offset:23552
	global_load_lds_dwordx4 v130, s[28:29]
	s_add_i32 m0, s54, 0x2000
	s_add_u32 s54, s28, 0x40000
	s_mov_b64 s[98:99], s[28:29]
	s_addc_u32 s55, s29, 0
	s_add_i32 s56, s47, s38
	global_load_lds_dwordx4 v134, s[28:29]
	s_mov_b32 m0, s56
	s_mov_b64 s[100:101], s[30:31]
	global_load_lds_dwordx4 v130, s[54:55]
	s_add_i32 m0, s56, 0x2000
	s_nop 0
	global_load_lds_dwordx4 v134, s[54:55]
	s_mov_b32 m0, s39
	s_nop 0
	global_load_lds_dwordx4 v128, s[30:31]
	s_mov_b32 m0, s40
	s_nop 0
	global_load_lds_dwordx4 v132, s[30:31]
	s_waitcnt vmcnt(8)
	s_waitcnt lgkmcnt(0)
	s_barrier
	s_waitcnt lgkmcnt(0)
	v_mfma_f32_16x16x32_bf16 v[60:63], v[144:147], v[184:187], v[60:63]
	v_mfma_f32_16x16x32_bf16 v[56:59], v[160:163], v[184:187], v[56:59]
	v_mfma_f32_16x16x32_bf16 v[44:47], v[144:147], v[192:195], v[44:47]
	v_mfma_f32_16x16x32_bf16 v[40:43], v[160:163], v[192:195], v[40:43]
	v_mfma_f32_16x16x32_bf16 v[28:31], v[144:147], v[200:203], v[28:31]
	v_mfma_f32_16x16x32_bf16 v[24:27], v[160:163], v[200:203], v[24:27]
	v_mfma_f32_16x16x32_bf16 v[12:15], v[144:147], v[212:215], v[12:15]
	v_mfma_f32_16x16x32_bf16 v[8:11], v[160:163], v[212:215], v[8:11]
	v_mfma_f32_16x16x32_bf16 v[60:63], v[156:159], v[188:191], v[60:63]
	v_mfma_f32_16x16x32_bf16 v[56:59], v[164:167], v[188:191], v[56:59]
	v_mfma_f32_16x16x32_bf16 v[44:47], v[156:159], v[196:199], v[44:47]
	v_mfma_f32_16x16x32_bf16 v[40:43], v[164:167], v[196:199], v[40:43]
	v_mfma_f32_16x16x32_bf16 v[28:31], v[156:159], v[208:211], v[28:31]
	v_mfma_f32_16x16x32_bf16 v[24:27], v[164:167], v[208:211], v[24:27]
	v_mfma_f32_16x16x32_bf16 v[12:15], v[156:159], v[216:219], v[12:15]
	v_mfma_f32_16x16x32_bf16 v[8:11], v[164:167], v[216:219], v[8:11]
	v_mfma_f32_16x16x32_bf16 v[52:55], v[168:171], v[184:187], v[52:55]
	v_mfma_f32_16x16x32_bf16 v[48:51], v[176:179], v[184:187], v[48:51]
	v_mfma_f32_16x16x32_bf16 v[36:39], v[168:171], v[192:195], v[36:39]
	v_mfma_f32_16x16x32_bf16 v[32:35], v[176:179], v[192:195], v[32:35]
	v_mfma_f32_16x16x32_bf16 v[20:23], v[168:171], v[200:203], v[20:23]
	v_mfma_f32_16x16x32_bf16 v[16:19], v[176:179], v[200:203], v[16:19]
	v_mfma_f32_16x16x32_bf16 v[4:7], v[168:171], v[212:215], v[4:7]
	v_mfma_f32_16x16x32_bf16 v[0:3], v[176:179], v[212:215], v[0:3]
	v_mfma_f32_16x16x32_bf16 v[52:55], v[172:175], v[188:191], v[52:55]
	v_mfma_f32_16x16x32_bf16 v[48:51], v[180:183], v[188:191], v[48:51]
	v_mfma_f32_16x16x32_bf16 v[36:39], v[172:175], v[196:199], v[36:39]
	v_mfma_f32_16x16x32_bf16 v[32:35], v[180:183], v[196:199], v[32:35]
	v_mfma_f32_16x16x32_bf16 v[20:23], v[172:175], v[208:211], v[20:23]
	v_mfma_f32_16x16x32_bf16 v[16:19], v[180:183], v[208:211], v[16:19]
	v_mfma_f32_16x16x32_bf16 v[4:7], v[172:175], v[216:219], v[4:7]
	v_mfma_f32_16x16x32_bf16 v[0:3], v[180:183], v[216:219], v[0:3]
	s_barrier
	s_add_i32 s54, 0, 0x18000
	v_add_u32_e32 v155, s54, v149
	s_add_i32 s55, 0, 0x1c000
	ds_read_b128 v[144:147], v155
	ds_read_b128 v[156:159], v155 offset:1024
	ds_read_b128 v[160:163], v155 offset:2048
	ds_read_b128 v[164:167], v155 offset:3072
	v_add_u32_e32 v155, s55, v149
	ds_read_b128 v[168:171], v155
	ds_read_b128 v[172:175], v155 offset:1024
	ds_read_b128 v[176:179], v155 offset:2048
	ds_read_b128 v[180:183], v155 offset:3072
	s_add_u32 s30, s30, 0x40000
	s_addc_u32 s31, s31, 0
	s_mov_b32 m0, s41
	ds_read_b128 v[184:187], v153 offset:32768
	ds_read_b128 v[188:191], v153 offset:33792
	ds_read_b128 v[192:195], v153 offset:34816
	ds_read_b128 v[196:199], v153 offset:35840
	ds_read_b128 v[200:203], v153 offset:36864
	ds_read_b128 v[208:211], v153 offset:37888
	ds_read_b128 v[212:215], v153 offset:38912
	ds_read_b128 v[216:219], v153 offset:39936
	global_load_lds_dwordx4 v128, s[30:31]
	s_mov_b32 m0, s42
	s_nop 0
	global_load_lds_dwordx4 v132, s[30:31]
	s_waitcnt vmcnt(8)
	s_waitcnt lgkmcnt(0)
	s_barrier
	s_waitcnt lgkmcnt(0)
	v_mfma_f32_16x16x32_bf16 v[124:127], v[144:147], v[184:187], v[124:127]
	v_mfma_f32_16x16x32_bf16 v[120:123], v[160:163], v[184:187], v[120:123]
	v_mfma_f32_16x16x32_bf16 v[108:111], v[144:147], v[192:195], v[108:111]
	v_mfma_f32_16x16x32_bf16 v[104:107], v[160:163], v[192:195], v[104:107]
	v_mfma_f32_16x16x32_bf16 v[92:95], v[144:147], v[200:203], v[92:95]
	v_mfma_f32_16x16x32_bf16 v[88:91], v[160:163], v[200:203], v[88:91]
	v_mfma_f32_16x16x32_bf16 v[76:79], v[144:147], v[212:215], v[76:79]
	v_mfma_f32_16x16x32_bf16 v[72:75], v[160:163], v[212:215], v[72:75]
	v_mfma_f32_16x16x32_bf16 v[124:127], v[156:159], v[188:191], v[124:127]
	v_mfma_f32_16x16x32_bf16 v[120:123], v[164:167], v[188:191], v[120:123]
	v_mfma_f32_16x16x32_bf16 v[108:111], v[156:159], v[196:199], v[108:111]
	v_mfma_f32_16x16x32_bf16 v[104:107], v[164:167], v[196:199], v[104:107]
	v_mfma_f32_16x16x32_bf16 v[92:95], v[156:159], v[208:211], v[92:95]
	v_mfma_f32_16x16x32_bf16 v[88:91], v[164:167], v[208:211], v[88:91]
	v_mfma_f32_16x16x32_bf16 v[76:79], v[156:159], v[216:219], v[76:79]
	v_mfma_f32_16x16x32_bf16 v[72:75], v[164:167], v[216:219], v[72:75]
	v_mfma_f32_16x16x32_bf16 v[116:119], v[168:171], v[184:187], v[116:119]
	v_mfma_f32_16x16x32_bf16 v[112:115], v[176:179], v[184:187], v[112:115]
	v_mfma_f32_16x16x32_bf16 v[100:103], v[168:171], v[192:195], v[100:103]
	v_mfma_f32_16x16x32_bf16 v[96:99], v[176:179], v[192:195], v[96:99]
	v_mfma_f32_16x16x32_bf16 v[84:87], v[168:171], v[200:203], v[84:87]
	v_mfma_f32_16x16x32_bf16 v[80:83], v[176:179], v[200:203], v[80:83]
	v_mfma_f32_16x16x32_bf16 v[68:71], v[168:171], v[212:215], v[68:71]
	v_mfma_f32_16x16x32_bf16 v[64:67], v[176:179], v[212:215], v[64:67]
	v_mfma_f32_16x16x32_bf16 v[116:119], v[172:175], v[188:191], v[116:119]
	v_mfma_f32_16x16x32_bf16 v[112:115], v[180:183], v[188:191], v[112:115]
	v_mfma_f32_16x16x32_bf16 v[100:103], v[172:175], v[196:199], v[100:103]
	v_mfma_f32_16x16x32_bf16 v[96:99], v[180:183], v[196:199], v[96:99]
	v_mfma_f32_16x16x32_bf16 v[84:87], v[172:175], v[208:211], v[84:87]
	v_mfma_f32_16x16x32_bf16 v[80:83], v[180:183], v[208:211], v[80:83]
	v_mfma_f32_16x16x32_bf16 v[68:71], v[172:175], v[216:219], v[68:71]
	v_mfma_f32_16x16x32_bf16 v[64:67], v[180:183], v[216:219], v[64:67]
	s_barrier
	s_add_i32 s30, s54, s38
	s_mov_b32 m0, s30
	ds_read_b128 v[184:187], v153 offset:49152
	ds_read_b128 v[188:191], v153 offset:50176
	ds_read_b128 v[192:195], v153 offset:51200
	ds_read_b128 v[196:199], v153 offset:52224
	ds_read_b128 v[200:203], v153 offset:53248
	ds_read_b128 v[208:211], v153 offset:54272
	ds_read_b128 v[212:215], v153 offset:55296
	ds_read_b128 v[216:219], v153 offset:56320
	global_load_lds_dwordx4 v205, s[28:29]
	s_add_i32 m0, s30, 0x2000
	s_add_u32 s28, s28, 0x40080
	s_addc_u32 s29, s29, 0
	s_add_i32 s30, s55, s38
	global_load_lds_dwordx4 v221, s[98:99]
	s_mov_b32 m0, s30
	s_nop 0
	global_load_lds_dwordx4 v130, s[28:29]
	s_add_i32 m0, s30, 0x2000
	s_nop 0
	global_load_lds_dwordx4 v134, s[28:29]
	s_mov_b32 m0, s44
	s_nop 0
	global_load_lds_dwordx4 v204, s[100:101]
	s_mov_b32 m0, s45
	s_nop 0
	global_load_lds_dwordx4 v220, s[100:101]
	s_waitcnt vmcnt(8)
	s_waitcnt lgkmcnt(0)
	s_barrier
	s_waitcnt lgkmcnt(0)
	v_mfma_f32_16x16x32_bf16 v[60:63], v[144:147], v[184:187], v[60:63]
	v_mfma_f32_16x16x32_bf16 v[56:59], v[160:163], v[184:187], v[56:59]
	v_mfma_f32_16x16x32_bf16 v[44:47], v[144:147], v[192:195], v[44:47]
	v_mfma_f32_16x16x32_bf16 v[40:43], v[160:163], v[192:195], v[40:43]
	v_mfma_f32_16x16x32_bf16 v[28:31], v[144:147], v[200:203], v[28:31]
	v_mfma_f32_16x16x32_bf16 v[24:27], v[160:163], v[200:203], v[24:27]
	v_mfma_f32_16x16x32_bf16 v[12:15], v[144:147], v[212:215], v[12:15]
	v_mfma_f32_16x16x32_bf16 v[8:11], v[160:163], v[212:215], v[8:11]
	v_mfma_f32_16x16x32_bf16 v[60:63], v[156:159], v[188:191], v[60:63]
	v_mfma_f32_16x16x32_bf16 v[56:59], v[164:167], v[188:191], v[56:59]
	v_mfma_f32_16x16x32_bf16 v[44:47], v[156:159], v[196:199], v[44:47]
	v_mfma_f32_16x16x32_bf16 v[40:43], v[164:167], v[196:199], v[40:43]
	v_mfma_f32_16x16x32_bf16 v[28:31], v[156:159], v[208:211], v[28:31]
	v_mfma_f32_16x16x32_bf16 v[24:27], v[164:167], v[208:211], v[24:27]
	v_mfma_f32_16x16x32_bf16 v[12:15], v[156:159], v[216:219], v[12:15]
	v_mfma_f32_16x16x32_bf16 v[8:11], v[164:167], v[216:219], v[8:11]
	v_mfma_f32_16x16x32_bf16 v[52:55], v[168:171], v[184:187], v[52:55]
	v_mfma_f32_16x16x32_bf16 v[48:51], v[176:179], v[184:187], v[48:51]
	v_mfma_f32_16x16x32_bf16 v[36:39], v[168:171], v[192:195], v[36:39]
	v_mfma_f32_16x16x32_bf16 v[32:35], v[176:179], v[192:195], v[32:35]
	v_mfma_f32_16x16x32_bf16 v[20:23], v[168:171], v[200:203], v[20:23]
	v_mfma_f32_16x16x32_bf16 v[16:19], v[176:179], v[200:203], v[16:19]
	v_mfma_f32_16x16x32_bf16 v[4:7], v[168:171], v[212:215], v[4:7]
	v_mfma_f32_16x16x32_bf16 v[0:3], v[176:179], v[212:215], v[0:3]
	v_mfma_f32_16x16x32_bf16 v[52:55], v[172:175], v[188:191], v[52:55]
	v_mfma_f32_16x16x32_bf16 v[48:51], v[180:183], v[188:191], v[48:51]
	v_mfma_f32_16x16x32_bf16 v[36:39], v[172:175], v[196:199], v[36:39]
	v_mfma_f32_16x16x32_bf16 v[32:35], v[180:183], v[196:199], v[32:35]
	v_mfma_f32_16x16x32_bf16 v[20:23], v[172:175], v[208:211], v[20:23]
	v_mfma_f32_16x16x32_bf16 v[16:19], v[180:183], v[208:211], v[16:19]
	v_mfma_f32_16x16x32_bf16 v[4:7], v[172:175], v[216:219], v[4:7]
	v_mfma_f32_16x16x32_bf16 v[0:3], v[180:183], v[216:219], v[0:3]
	s_barrier
	s_add_i32 s53, s53, 2
	s_add_u32 s51, s51, 0x100
	s_addc_u32 s52, s52, 0
	s_add_u32 s26, s26, 0x100
	s_addc_u32 s27, s27, 0
	s_cmp_gt_u32 s53, 13
	s_cbranch_scc0 .LBB0_699
	s_setprio 0
	s_and_b64 vcc, exec, s[16:17]
	s_cbranch_vccz .LBB0_702
	s_barrier

.LBB0_777:
	s_ashr_i32 s21, s20, 31
	s_lshl_b64 s[22:23], s[20:21], 21
	s_add_u32 s22, s39, s22
	s_addc_u32 s23, s40, s23
	s_and_b64 s[24:25], s[6:7], exec
	s_cselect_b32 s21, s23, s29
	s_cselect_b32 s27, s22, s28
	s_ashr_i32 s19, s18, 31
	s_lshl_b64 s[24:25], s[18:19], 21
	s_add_u32 s24, s41, s24
	s_addc_u32 s25, s42, s25
	s_and_b64 s[34:35], s[6:7], exec
	s_cselect_b32 s19, s25, s31
	s_cselect_b32 s55, s24, s30
	s_add_u32 s56, s30, 0x100
	v_mov_b32_e32 v0, 0
	s_addc_u32 s57, s31, 0
	s_mov_b32 s58, -2
	v_mov_b32_e32 v1, v0
	v_mov_b32_e32 v2, v0
	v_mov_b32_e32 v3, v0
	v_mov_b32_e32 v4, v0
	v_mov_b32_e32 v5, v0
	v_mov_b32_e32 v6, v0
	v_mov_b32_e32 v7, v0
	v_mov_b32_e32 v16, v0
	v_mov_b32_e32 v17, v0
	v_mov_b32_e32 v18, v0
	v_mov_b32_e32 v19, v0
	v_mov_b32_e32 v20, v0
	v_mov_b32_e32 v21, v0
	v_mov_b32_e32 v22, v0
	v_mov_b32_e32 v23, v0
	v_mov_b32_e32 v32, v0
	v_mov_b32_e32 v33, v0
	v_mov_b32_e32 v34, v0
	v_mov_b32_e32 v35, v0
	v_mov_b32_e32 v36, v0
	v_mov_b32_e32 v37, v0
	v_mov_b32_e32 v38, v0
	v_mov_b32_e32 v39, v0
	v_mov_b32_e32 v48, v0
	v_mov_b32_e32 v49, v0
	v_mov_b32_e32 v50, v0
	v_mov_b32_e32 v51, v0
	v_mov_b32_e32 v52, v0
	v_mov_b32_e32 v53, v0
	v_mov_b32_e32 v54, v0
	v_mov_b32_e32 v55, v0
	v_mov_b32_e32 v8, v0
	v_mov_b32_e32 v9, v0
	v_mov_b32_e32 v10, v0
	v_mov_b32_e32 v11, v0
	v_mov_b32_e32 v12, v0
	v_mov_b32_e32 v13, v0
	v_mov_b32_e32 v14, v0
	v_mov_b32_e32 v15, v0
	v_mov_b32_e32 v24, v0
	v_mov_b32_e32 v25, v0
	v_mov_b32_e32 v26, v0
	v_mov_b32_e32 v27, v0
	v_mov_b32_e32 v28, v0
	v_mov_b32_e32 v29, v0
	v_mov_b32_e32 v30, v0
	v_mov_b32_e32 v31, v0
	v_mov_b32_e32 v40, v0
	v_mov_b32_e32 v41, v0
	v_mov_b32_e32 v42, v0
	v_mov_b32_e32 v43, v0
	v_mov_b32_e32 v44, v0
	v_mov_b32_e32 v45, v0
	v_mov_b32_e32 v46, v0
	v_mov_b32_e32 v47, v0
	v_mov_b32_e32 v56, v0
	v_mov_b32_e32 v57, v0
	v_mov_b32_e32 v58, v0
	v_mov_b32_e32 v59, v0
	v_mov_b32_e32 v60, v0
	v_mov_b32_e32 v61, v0
	v_mov_b32_e32 v62, v0
	v_mov_b32_e32 v63, v0
	v_mov_b32_e32 v64, v0
	v_mov_b32_e32 v65, v0
	v_mov_b32_e32 v66, v0
	v_mov_b32_e32 v67, v0
	v_mov_b32_e32 v68, v0
	v_mov_b32_e32 v69, v0
	v_mov_b32_e32 v70, v0
	v_mov_b32_e32 v71, v0
	v_mov_b32_e32 v80, v0
	v_mov_b32_e32 v81, v0
	v_mov_b32_e32 v82, v0
	v_mov_b32_e32 v83, v0
	v_mov_b32_e32 v84, v0
	v_mov_b32_e32 v85, v0
	v_mov_b32_e32 v86, v0
	v_mov_b32_e32 v87, v0
	v_mov_b32_e32 v96, v0
	v_mov_b32_e32 v97, v0
	v_mov_b32_e32 v98, v0
	v_mov_b32_e32 v99, v0
	v_mov_b32_e32 v100, v0
	v_mov_b32_e32 v101, v0
	v_mov_b32_e32 v102, v0
	v_mov_b32_e32 v103, v0
	v_mov_b32_e32 v112, v0
	v_mov_b32_e32 v113, v0
	v_mov_b32_e32 v114, v0
	v_mov_b32_e32 v115, v0
	v_mov_b32_e32 v116, v0
	v_mov_b32_e32 v117, v0
	v_mov_b32_e32 v118, v0
	v_mov_b32_e32 v119, v0
	v_mov_b32_e32 v72, v0
	v_mov_b32_e32 v73, v0
	v_mov_b32_e32 v74, v0
	v_mov_b32_e32 v75, v0
	v_mov_b32_e32 v76, v0
	v_mov_b32_e32 v77, v0
	v_mov_b32_e32 v78, v0
	v_mov_b32_e32 v79, v0
	v_mov_b32_e32 v88, v0
	v_mov_b32_e32 v89, v0
	v_mov_b32_e32 v90, v0
	v_mov_b32_e32 v91, v0
	v_mov_b32_e32 v92, v0
	v_mov_b32_e32 v93, v0
	v_mov_b32_e32 v94, v0
	v_mov_b32_e32 v95, v0
	v_mov_b32_e32 v104, v0
	v_mov_b32_e32 v105, v0
	v_mov_b32_e32 v106, v0
	v_mov_b32_e32 v107, v0
	v_mov_b32_e32 v108, v0
	v_mov_b32_e32 v109, v0
	v_mov_b32_e32 v110, v0
	v_mov_b32_e32 v111, v0
	v_mov_b32_e32 v120, v0
	v_mov_b32_e32 v121, v0
	v_mov_b32_e32 v122, v0
	v_mov_b32_e32 v123, v0
	v_mov_b32_e32 v124, v0
	v_mov_b32_e32 v125, v0
	v_mov_b32_e32 v126, v0
	v_mov_b32_e32 v127, v0
	v_add_u32_e32 v212, 0x80, v128
	v_add_u32_e32 v213, 0x80, v130
	v_readfirstlane_b32 s101, v206
	s_nop 3
	s_lshr_b32 s101, s101, 8
	s_cmp_eq_u32 s101, 1
	s_cbranch_scc0 .Lprio_skip_18
	s_setprio 1

.LBB0_778:
	ds_read_b128 v[140:143], v147
	ds_read_b128 v[150:153], v147 offset:1024
	ds_read_b128 v[154:157], v147 offset:2048
	ds_read_b128 v[158:161], v147 offset:3072
	ds_read_b128 v[162:165], v148
	ds_read_b128 v[166:169], v148 offset:1024
	ds_read_b128 v[170:173], v148 offset:2048
	ds_read_b128 v[174:177], v148 offset:3072
	s_add_u32 s30, s28, 0x100
	s_addc_u32 s31, s29, 0
	s_cmp_eq_u32 s58, 60
	s_cselect_b32 s37, s21, s31
	s_cselect_b32 s36, s27, s30
	s_cselect_b32 s35, s19, s57
	s_cselect_b32 s34, s55, s56
	s_add_i32 m0, s44, 0xc000
	ds_read_b128 v[178:181], v149
	ds_read_b128 v[182:185], v149 offset:1024
	ds_read_b128 v[186:189], v149 offset:2048
	ds_read_b128 v[190:193], v149 offset:3072
	ds_read_b128 v[194:197], v149 offset:4096
	ds_read_b128 v[198:201], v149 offset:5120
	ds_read_b128 v[202:205], v149 offset:6144
	ds_read_b128 v[208:211], v149 offset:7168
	global_load_lds_dwordx4 v134, s[28:29]
	s_add_i32 m0, s44, 0xe000
	s_nop 0
	global_load_lds_dwordx4 v132, s[28:29]
	s_waitcnt vmcnt(8)
	s_waitcnt lgkmcnt(0)
	s_barrier
	s_waitcnt lgkmcnt(0)
	v_mfma_f32_16x16x32_bf16 v[124:127], v[140:143], v[178:181], v[124:127]
	v_mfma_f32_16x16x32_bf16 v[120:123], v[154:157], v[178:181], v[120:123]
	v_mfma_f32_16x16x32_bf16 v[108:111], v[140:143], v[186:189], v[108:111]
	v_mfma_f32_16x16x32_bf16 v[104:107], v[154:157], v[186:189], v[104:107]
	v_mfma_f32_16x16x32_bf16 v[92:95], v[140:143], v[194:197], v[92:95]
	v_mfma_f32_16x16x32_bf16 v[88:91], v[154:157], v[194:197], v[88:91]
	v_mfma_f32_16x16x32_bf16 v[76:79], v[140:143], v[202:205], v[76:79]
	v_mfma_f32_16x16x32_bf16 v[72:75], v[154:157], v[202:205], v[72:75]
	v_mfma_f32_16x16x32_bf16 v[124:127], v[150:153], v[182:185], v[124:127]
	v_mfma_f32_16x16x32_bf16 v[120:123], v[158:161], v[182:185], v[120:123]
	v_mfma_f32_16x16x32_bf16 v[108:111], v[150:153], v[190:193], v[108:111]
	v_mfma_f32_16x16x32_bf16 v[104:107], v[158:161], v[190:193], v[104:107]
	v_mfma_f32_16x16x32_bf16 v[92:95], v[150:153], v[198:201], v[92:95]
	v_mfma_f32_16x16x32_bf16 v[88:91], v[158:161], v[198:201], v[88:91]
	v_mfma_f32_16x16x32_bf16 v[76:79], v[150:153], v[208:211], v[76:79]
	v_mfma_f32_16x16x32_bf16 v[72:75], v[158:161], v[208:211], v[72:75]
	v_mfma_f32_16x16x32_bf16 v[116:119], v[162:165], v[178:181], v[116:119]
	v_mfma_f32_16x16x32_bf16 v[112:115], v[170:173], v[178:181], v[112:115]
	v_mfma_f32_16x16x32_bf16 v[100:103], v[162:165], v[186:189], v[100:103]
	v_mfma_f32_16x16x32_bf16 v[96:99], v[170:173], v[186:189], v[96:99]
	v_mfma_f32_16x16x32_bf16 v[84:87], v[162:165], v[194:197], v[84:87]
	v_mfma_f32_16x16x32_bf16 v[80:83], v[170:173], v[194:197], v[80:83]
	v_mfma_f32_16x16x32_bf16 v[68:71], v[162:165], v[202:205], v[68:71]
	v_mfma_f32_16x16x32_bf16 v[64:67], v[170:173], v[202:205], v[64:67]
	v_mfma_f32_16x16x32_bf16 v[116:119], v[166:169], v[182:185], v[116:119]
	v_mfma_f32_16x16x32_bf16 v[112:115], v[174:177], v[182:185], v[112:115]
	v_mfma_f32_16x16x32_bf16 v[100:103], v[166:169], v[190:193], v[100:103]
	v_mfma_f32_16x16x32_bf16 v[96:99], v[174:177], v[190:193], v[96:99]
	v_mfma_f32_16x16x32_bf16 v[84:87], v[166:169], v[198:201], v[84:87]
	v_mfma_f32_16x16x32_bf16 v[80:83], v[174:177], v[198:201], v[80:83]
	v_mfma_f32_16x16x32_bf16 v[68:71], v[166:169], v[208:211], v[68:71]
	v_mfma_f32_16x16x32_bf16 v[64:67], v[174:177], v[208:211], v[64:67]
	s_barrier
	s_add_i32 s28, s52, s43
	s_mov_b32 m0, s28
	ds_read_b128 v[178:181], v149 offset:16384
	ds_read_b128 v[182:185], v149 offset:17408
	ds_read_b128 v[186:189], v149 offset:18432
	ds_read_b128 v[190:193], v149 offset:19456
	ds_read_b128 v[194:197], v149 offset:20480
	ds_read_b128 v[198:201], v149 offset:21504
	ds_read_b128 v[202:205], v149 offset:22528
	ds_read_b128 v[208:211], v149 offset:23552
	global_load_lds_dwordx4 v128, s[34:35]
	s_add_i32 m0, s28, 0x2000
	s_add_u32 s28, s34, 0x100000
	s_mov_b64 s[98:99], s[34:35]
	s_addc_u32 s29, s35, 0
	s_add_i32 s59, s53, s43
	global_load_lds_dwordx4 v130, s[34:35]
	s_mov_b32 m0, s59
	s_nop 0
	global_load_lds_dwordx4 v128, s[28:29]
	s_add_i32 m0, s59, 0x2000
	s_nop 0
	global_load_lds_dwordx4 v130, s[28:29]
	s_mov_b32 m0, s44
	s_nop 0
	global_load_lds_dwordx4 v128, s[36:37]
	s_mov_b32 m0, s45
	s_nop 0
	global_load_lds_dwordx4 v130, s[36:37]
	s_waitcnt vmcnt(8)
	s_waitcnt lgkmcnt(0)
	s_barrier
	s_waitcnt lgkmcnt(0)
	v_mfma_f32_16x16x32_bf16 v[60:63], v[140:143], v[178:181], v[60:63]
	v_mfma_f32_16x16x32_bf16 v[56:59], v[154:157], v[178:181], v[56:59]
	v_mfma_f32_16x16x32_bf16 v[44:47], v[140:143], v[186:189], v[44:47]
	v_mfma_f32_16x16x32_bf16 v[40:43], v[154:157], v[186:189], v[40:43]
	v_mfma_f32_16x16x32_bf16 v[28:31], v[140:143], v[194:197], v[28:31]
	v_mfma_f32_16x16x32_bf16 v[24:27], v[154:157], v[194:197], v[24:27]
	v_mfma_f32_16x16x32_bf16 v[12:15], v[140:143], v[202:205], v[12:15]
	v_mfma_f32_16x16x32_bf16 v[8:11], v[154:157], v[202:205], v[8:11]
	v_mfma_f32_16x16x32_bf16 v[60:63], v[150:153], v[182:185], v[60:63]
	v_mfma_f32_16x16x32_bf16 v[56:59], v[158:161], v[182:185], v[56:59]
	v_mfma_f32_16x16x32_bf16 v[44:47], v[150:153], v[190:193], v[44:47]
	v_mfma_f32_16x16x32_bf16 v[40:43], v[158:161], v[190:193], v[40:43]
	v_mfma_f32_16x16x32_bf16 v[28:31], v[150:153], v[198:201], v[28:31]
	v_mfma_f32_16x16x32_bf16 v[24:27], v[158:161], v[198:201], v[24:27]
	v_mfma_f32_16x16x32_bf16 v[12:15], v[150:153], v[208:211], v[12:15]
	v_mfma_f32_16x16x32_bf16 v[8:11], v[158:161], v[208:211], v[8:11]
	v_mfma_f32_16x16x32_bf16 v[52:55], v[162:165], v[178:181], v[52:55]
	v_mfma_f32_16x16x32_bf16 v[48:51], v[170:173], v[178:181], v[48:51]
	v_mfma_f32_16x16x32_bf16 v[36:39], v[162:165], v[186:189], v[36:39]
	v_mfma_f32_16x16x32_bf16 v[32:35], v[170:173], v[186:189], v[32:35]
	v_mfma_f32_16x16x32_bf16 v[20:23], v[162:165], v[194:197], v[20:23]
	v_mfma_f32_16x16x32_bf16 v[16:19], v[170:173], v[194:197], v[16:19]
	v_mfma_f32_16x16x32_bf16 v[4:7], v[162:165], v[202:205], v[4:7]
	v_mfma_f32_16x16x32_bf16 v[0:3], v[170:173], v[202:205], v[0:3]
	v_mfma_f32_16x16x32_bf16 v[52:55], v[166:169], v[182:185], v[52:55]
	v_mfma_f32_16x16x32_bf16 v[48:51], v[174:177], v[182:185], v[48:51]
	v_mfma_f32_16x16x32_bf16 v[36:39], v[166:169], v[190:193], v[36:39]
	v_mfma_f32_16x16x32_bf16 v[32:35], v[174:177], v[190:193], v[32:35]
	v_mfma_f32_16x16x32_bf16 v[20:23], v[166:169], v[198:201], v[20:23]
	v_mfma_f32_16x16x32_bf16 v[16:19], v[174:177], v[198:201], v[16:19]
	v_mfma_f32_16x16x32_bf16 v[4:7], v[166:169], v[208:211], v[4:7]
	v_mfma_f32_16x16x32_bf16 v[0:3], v[174:177], v[208:211], v[0:3]
	s_barrier
	s_add_i32 s59, 0, 0x18000
	s_add_i32 s60, 0, 0x1c000
	v_add_u32_e32 v158, s59, v145
	v_add_u32_e32 v174, s60, v145
	ds_read_b128 v[140:143], v158
	ds_read_b128 v[150:153], v158 offset:1024
	ds_read_b128 v[154:157], v158 offset:2048
	ds_read_b128 v[158:161], v158 offset:3072
	ds_read_b128 v[162:165], v174
	ds_read_b128 v[166:169], v174 offset:1024
	ds_read_b128 v[170:173], v174 offset:2048
	ds_read_b128 v[174:177], v174 offset:3072
	s_add_u32 s28, s36, 0x100000
	s_addc_u32 s29, s37, 0
	s_mov_b32 m0, s46
	ds_read_b128 v[178:181], v149 offset:32768
	ds_read_b128 v[182:185], v149 offset:33792
	ds_read_b128 v[186:189], v149 offset:34816
	ds_read_b128 v[190:193], v149 offset:35840
	ds_read_b128 v[194:197], v149 offset:36864
	ds_read_b128 v[198:201], v149 offset:37888
	ds_read_b128 v[202:205], v149 offset:38912
	ds_read_b128 v[208:211], v149 offset:39936
	global_load_lds_dwordx4 v128, s[28:29]
	s_mov_b32 m0, s47
	s_nop 0
	global_load_lds_dwordx4 v130, s[28:29]
	s_waitcnt vmcnt(8)
	s_waitcnt lgkmcnt(0)
	s_barrier
	s_waitcnt lgkmcnt(0)
	v_mfma_f32_16x16x32_bf16 v[124:127], v[140:143], v[178:181], v[124:127]
	v_mfma_f32_16x16x32_bf16 v[120:123], v[154:157], v[178:181], v[120:123]
	v_mfma_f32_16x16x32_bf16 v[108:111], v[140:143], v[186:189], v[108:111]
	v_mfma_f32_16x16x32_bf16 v[104:107], v[154:157], v[186:189], v[104:107]
	v_mfma_f32_16x16x32_bf16 v[92:95], v[140:143], v[194:197], v[92:95]
	v_mfma_f32_16x16x32_bf16 v[88:91], v[154:157], v[194:197], v[88:91]
	v_mfma_f32_16x16x32_bf16 v[76:79], v[140:143], v[202:205], v[76:79]
	v_mfma_f32_16x16x32_bf16 v[72:75], v[154:157], v[202:205], v[72:75]
	v_mfma_f32_16x16x32_bf16 v[124:127], v[150:153], v[182:185], v[124:127]
	v_mfma_f32_16x16x32_bf16 v[120:123], v[158:161], v[182:185], v[120:123]
	v_mfma_f32_16x16x32_bf16 v[108:111], v[150:153], v[190:193], v[108:111]
	v_mfma_f32_16x16x32_bf16 v[104:107], v[158:161], v[190:193], v[104:107]
	v_mfma_f32_16x16x32_bf16 v[92:95], v[150:153], v[198:201], v[92:95]
	v_mfma_f32_16x16x32_bf16 v[88:91], v[158:161], v[198:201], v[88:91]
	v_mfma_f32_16x16x32_bf16 v[76:79], v[150:153], v[208:211], v[76:79]
	v_mfma_f32_16x16x32_bf16 v[72:75], v[158:161], v[208:211], v[72:75]
	v_mfma_f32_16x16x32_bf16 v[116:119], v[162:165], v[178:181], v[116:119]
	v_mfma_f32_16x16x32_bf16 v[112:115], v[170:173], v[178:181], v[112:115]
	v_mfma_f32_16x16x32_bf16 v[100:103], v[162:165], v[186:189], v[100:103]
	v_mfma_f32_16x16x32_bf16 v[96:99], v[170:173], v[186:189], v[96:99]
	v_mfma_f32_16x16x32_bf16 v[84:87], v[162:165], v[194:197], v[84:87]
	v_mfma_f32_16x16x32_bf16 v[80:83], v[170:173], v[194:197], v[80:83]
	v_mfma_f32_16x16x32_bf16 v[68:71], v[162:165], v[202:205], v[68:71]
	v_mfma_f32_16x16x32_bf16 v[64:67], v[170:173], v[202:205], v[64:67]
	v_mfma_f32_16x16x32_bf16 v[116:119], v[166:169], v[182:185], v[116:119]
	v_mfma_f32_16x16x32_bf16 v[112:115], v[174:177], v[182:185], v[112:115]
	v_mfma_f32_16x16x32_bf16 v[100:103], v[166:169], v[190:193], v[100:103]
	v_mfma_f32_16x16x32_bf16 v[96:99], v[174:177], v[190:193], v[96:99]
	v_mfma_f32_16x16x32_bf16 v[84:87], v[166:169], v[198:201], v[84:87]
	v_mfma_f32_16x16x32_bf16 v[80:83], v[174:177], v[198:201], v[80:83]
	v_mfma_f32_16x16x32_bf16 v[68:71], v[166:169], v[208:211], v[68:71]
	v_mfma_f32_16x16x32_bf16 v[64:67], v[174:177], v[208:211], v[64:67]
	s_barrier
	s_add_i32 s28, s59, s43
	s_mov_b32 m0, s28
	ds_read_b128 v[178:181], v149 offset:49152
	ds_read_b128 v[182:185], v149 offset:50176
	ds_read_b128 v[186:189], v149 offset:51200
	ds_read_b128 v[190:193], v149 offset:52224
	ds_read_b128 v[194:197], v149 offset:53248
	ds_read_b128 v[198:201], v149 offset:54272
	ds_read_b128 v[202:205], v149 offset:55296
	ds_read_b128 v[208:211], v149 offset:56320
	global_load_lds_dwordx4 v212, s[34:35]
	s_add_i32 m0, s28, 0x2000
	s_add_u32 s28, s34, 0x100080
	s_addc_u32 s29, s35, 0
	s_add_i32 s34, s60, s43
	global_load_lds_dwordx4 v213, s[98:99]
	s_mov_b32 m0, s34
	s_nop 0
	global_load_lds_dwordx4 v128, s[28:29]
	s_add_i32 m0, s34, 0x2000
	s_nop 0
	global_load_lds_dwordx4 v130, s[28:29]
	s_mov_b32 m0, s49
	s_nop 0
	global_load_lds_dwordx4 v212, s[36:37]
	s_mov_b32 m0, s50
	s_nop 0
	global_load_lds_dwordx4 v213, s[36:37]
	s_waitcnt vmcnt(8)
	s_waitcnt lgkmcnt(0)
	s_barrier
	s_waitcnt lgkmcnt(0)
	v_mfma_f32_16x16x32_bf16 v[60:63], v[140:143], v[178:181], v[60:63]
	v_mfma_f32_16x16x32_bf16 v[56:59], v[154:157], v[178:181], v[56:59]
	v_mfma_f32_16x16x32_bf16 v[44:47], v[140:143], v[186:189], v[44:47]
	v_mfma_f32_16x16x32_bf16 v[40:43], v[154:157], v[186:189], v[40:43]
	v_mfma_f32_16x16x32_bf16 v[28:31], v[140:143], v[194:197], v[28:31]
	v_mfma_f32_16x16x32_bf16 v[24:27], v[154:157], v[194:197], v[24:27]
	v_mfma_f32_16x16x32_bf16 v[12:15], v[140:143], v[202:205], v[12:15]
	v_mfma_f32_16x16x32_bf16 v[8:11], v[154:157], v[202:205], v[8:11]
	v_mfma_f32_16x16x32_bf16 v[60:63], v[150:153], v[182:185], v[60:63]
	v_mfma_f32_16x16x32_bf16 v[56:59], v[158:161], v[182:185], v[56:59]
	v_mfma_f32_16x16x32_bf16 v[44:47], v[150:153], v[190:193], v[44:47]
	v_mfma_f32_16x16x32_bf16 v[40:43], v[158:161], v[190:193], v[40:43]
	v_mfma_f32_16x16x32_bf16 v[28:31], v[150:153], v[198:201], v[28:31]
	v_mfma_f32_16x16x32_bf16 v[24:27], v[158:161], v[198:201], v[24:27]
	v_mfma_f32_16x16x32_bf16 v[12:15], v[150:153], v[208:211], v[12:15]
	v_mfma_f32_16x16x32_bf16 v[8:11], v[158:161], v[208:211], v[8:11]
	v_mfma_f32_16x16x32_bf16 v[52:55], v[162:165], v[178:181], v[52:55]
	v_mfma_f32_16x16x32_bf16 v[48:51], v[170:173], v[178:181], v[48:51]
	v_mfma_f32_16x16x32_bf16 v[36:39], v[162:165], v[186:189], v[36:39]
	v_mfma_f32_16x16x32_bf16 v[32:35], v[170:173], v[186:189], v[32:35]
	v_mfma_f32_16x16x32_bf16 v[20:23], v[162:165], v[194:197], v[20:23]
	v_mfma_f32_16x16x32_bf16 v[16:19], v[170:173], v[194:197], v[16:19]
	v_mfma_f32_16x16x32_bf16 v[4:7], v[162:165], v[202:205], v[4:7]
	v_mfma_f32_16x16x32_bf16 v[0:3], v[170:173], v[202:205], v[0:3]
	v_mfma_f32_16x16x32_bf16 v[52:55], v[166:169], v[182:185], v[52:55]
	v_mfma_f32_16x16x32_bf16 v[48:51], v[174:177], v[182:185], v[48:51]
	v_mfma_f32_16x16x32_bf16 v[36:39], v[166:169], v[190:193], v[36:39]
	v_mfma_f32_16x16x32_bf16 v[32:35], v[174:177], v[190:193], v[32:35]
	v_mfma_f32_16x16x32_bf16 v[20:23], v[166:169], v[198:201], v[20:23]
	v_mfma_f32_16x16x32_bf16 v[16:19], v[174:177], v[198:201], v[16:19]
	v_mfma_f32_16x16x32_bf16 v[4:7], v[166:169], v[208:211], v[4:7]
	v_mfma_f32_16x16x32_bf16 v[0:3], v[174:177], v[208:211], v[0:3]
	s_barrier
	s_add_i32 s58, s58, 2
	s_add_u32 s56, s56, 0x100
	s_addc_u32 s57, s57, 0
	s_cmp_gt_u32 s58, 61
	s_mov_b64 s[28:29], s[30:31]
	s_cbranch_scc0 .LBB0_778
	s_setprio 0
	s_and_b64 vcc, exec, s[16:17]
	s_cbranch_vccz .LBB0_781
	s_barrier

.LBB0_894:
	s_ashr_i32 s29, s28, 31
	s_lshl_b64 s[30:31], s[28:29], 19
	s_add_u32 s30, s8, s30
	s_addc_u32 s31, s9, s31
	s_and_b64 s[34:35], s[6:7], exec
	s_cselect_b32 s3, s31, s39
	s_cselect_b32 s29, s30, s38
	s_ashr_i32 s27, s26, 31
	s_lshl_b64 s[34:35], s[26:27], 19
	s_add_u32 s34, s43, s34
	s_addc_u32 s35, s44, s35
	s_and_b64 s[40:41], s[6:7], exec
	s_cselect_b32 s27, s35, s37
	s_cselect_b32 s58, s34, s36
	s_add_u32 s59, s36, 0x100
	s_addc_u32 s60, s37, 0
	s_add_u32 s36, s38, 0x40080
	v_mov_b32_e32 v0, 0
	s_addc_u32 s37, s39, 0
	s_mov_b32 s61, -2
	v_mov_b32_e32 v1, v0
	v_mov_b32_e32 v2, v0
	v_mov_b32_e32 v3, v0
	v_mov_b32_e32 v4, v0
	v_mov_b32_e32 v5, v0
	v_mov_b32_e32 v6, v0
	v_mov_b32_e32 v7, v0
	v_mov_b32_e32 v16, v0
	v_mov_b32_e32 v17, v0
	v_mov_b32_e32 v18, v0
	v_mov_b32_e32 v19, v0
	v_mov_b32_e32 v20, v0
	v_mov_b32_e32 v21, v0
	v_mov_b32_e32 v22, v0
	v_mov_b32_e32 v23, v0
	v_mov_b32_e32 v32, v0
	v_mov_b32_e32 v33, v0
	v_mov_b32_e32 v34, v0
	v_mov_b32_e32 v35, v0
	v_mov_b32_e32 v36, v0
	v_mov_b32_e32 v37, v0
	v_mov_b32_e32 v38, v0
	v_mov_b32_e32 v39, v0
	v_mov_b32_e32 v48, v0
	v_mov_b32_e32 v49, v0
	v_mov_b32_e32 v50, v0
	v_mov_b32_e32 v51, v0
	v_mov_b32_e32 v52, v0
	v_mov_b32_e32 v53, v0
	v_mov_b32_e32 v54, v0
	v_mov_b32_e32 v55, v0
	v_mov_b32_e32 v8, v0
	v_mov_b32_e32 v9, v0
	v_mov_b32_e32 v10, v0
	v_mov_b32_e32 v11, v0
	v_mov_b32_e32 v12, v0
	v_mov_b32_e32 v13, v0
	v_mov_b32_e32 v14, v0
	v_mov_b32_e32 v15, v0
	v_mov_b32_e32 v24, v0
	v_mov_b32_e32 v25, v0
	v_mov_b32_e32 v26, v0
	v_mov_b32_e32 v27, v0
	v_mov_b32_e32 v28, v0
	v_mov_b32_e32 v29, v0
	v_mov_b32_e32 v30, v0
	v_mov_b32_e32 v31, v0
	v_mov_b32_e32 v40, v0
	v_mov_b32_e32 v41, v0
	v_mov_b32_e32 v42, v0
	v_mov_b32_e32 v43, v0
	v_mov_b32_e32 v44, v0
	v_mov_b32_e32 v45, v0
	v_mov_b32_e32 v46, v0
	v_mov_b32_e32 v47, v0
	v_mov_b32_e32 v56, v0
	v_mov_b32_e32 v57, v0
	v_mov_b32_e32 v58, v0
	v_mov_b32_e32 v59, v0
	v_mov_b32_e32 v60, v0
	v_mov_b32_e32 v61, v0
	v_mov_b32_e32 v62, v0
	v_mov_b32_e32 v63, v0
	v_mov_b32_e32 v64, v0
	v_mov_b32_e32 v65, v0
	v_mov_b32_e32 v66, v0
	v_mov_b32_e32 v67, v0
	v_mov_b32_e32 v68, v0
	v_mov_b32_e32 v69, v0
	v_mov_b32_e32 v70, v0
	v_mov_b32_e32 v71, v0
	v_mov_b32_e32 v80, v0
	v_mov_b32_e32 v81, v0
	v_mov_b32_e32 v82, v0
	v_mov_b32_e32 v83, v0
	v_mov_b32_e32 v84, v0
	v_mov_b32_e32 v85, v0
	v_mov_b32_e32 v86, v0
	v_mov_b32_e32 v87, v0
	v_mov_b32_e32 v96, v0
	v_mov_b32_e32 v97, v0
	v_mov_b32_e32 v98, v0
	v_mov_b32_e32 v99, v0
	v_mov_b32_e32 v100, v0
	v_mov_b32_e32 v101, v0
	v_mov_b32_e32 v102, v0
	v_mov_b32_e32 v103, v0
	v_mov_b32_e32 v112, v0
	v_mov_b32_e32 v113, v0
	v_mov_b32_e32 v114, v0
	v_mov_b32_e32 v115, v0
	v_mov_b32_e32 v116, v0
	v_mov_b32_e32 v117, v0
	v_mov_b32_e32 v118, v0
	v_mov_b32_e32 v119, v0
	v_mov_b32_e32 v72, v0
	v_mov_b32_e32 v73, v0
	v_mov_b32_e32 v74, v0
	v_mov_b32_e32 v75, v0
	v_mov_b32_e32 v76, v0
	v_mov_b32_e32 v77, v0
	v_mov_b32_e32 v78, v0
	v_mov_b32_e32 v79, v0
	v_mov_b32_e32 v88, v0
	v_mov_b32_e32 v89, v0
	v_mov_b32_e32 v90, v0
	v_mov_b32_e32 v91, v0
	v_mov_b32_e32 v92, v0
	v_mov_b32_e32 v93, v0
	v_mov_b32_e32 v94, v0
	v_mov_b32_e32 v95, v0
	v_mov_b32_e32 v104, v0
	v_mov_b32_e32 v105, v0
	v_mov_b32_e32 v106, v0
	v_mov_b32_e32 v107, v0
	v_mov_b32_e32 v108, v0
	v_mov_b32_e32 v109, v0
	v_mov_b32_e32 v110, v0
	v_mov_b32_e32 v111, v0
	v_mov_b32_e32 v120, v0
	v_mov_b32_e32 v121, v0
	v_mov_b32_e32 v122, v0
	v_mov_b32_e32 v123, v0
	v_mov_b32_e32 v124, v0
	v_mov_b32_e32 v125, v0
	v_mov_b32_e32 v126, v0
	v_mov_b32_e32 v127, v0
	v_add_u32_e32 v148, 0x80, v128
	v_add_u32_e32 v149, 0x80, v130
	v_readfirstlane_b32 s101, v206
	s_nop 3
	s_lshr_b32 s101, s101, 8
	s_cmp_eq_u32 s101, 1
	s_cbranch_scc0 .Lprio_skip_17
	s_setprio 1

.LBB0_895:
	ds_read_b128 v[140:143], v153
	ds_read_b128 v[144:147], v153 offset:1024
	ds_read_b128 v[158:161], v153 offset:2048
	ds_read_b128 v[162:165], v153 offset:3072
	ds_read_b128 v[166:169], v154
	ds_read_b128 v[170:173], v154 offset:1024
	ds_read_b128 v[174:177], v154 offset:2048
	ds_read_b128 v[178:181], v154 offset:3072
	s_add_u32 s38, s36, 0xfffc0080
	s_addc_u32 s39, s37, -1
	s_cmp_eq_u32 s61, 12
	s_cselect_b32 s41, s3, s39
	s_cselect_b32 s40, s29, s38
	s_cselect_b32 s39, s27, s60
	s_cselect_b32 s38, s58, s59
	s_add_i32 m0, s46, 0xc000
	ds_read_b128 v[182:185], v155
	ds_read_b128 v[186:189], v155 offset:1024
	ds_read_b128 v[190:193], v155 offset:2048
	ds_read_b128 v[194:197], v155 offset:3072
	ds_read_b128 v[198:201], v155 offset:4096
	ds_read_b128 v[202:205], v155 offset:5120
	ds_read_b128 v[208:211], v155 offset:6144
	ds_read_b128 v[212:215], v155 offset:7168
	global_load_lds_dwordx4 v134, s[36:37]
	s_add_i32 m0, s46, 0xe000
	s_nop 0
	global_load_lds_dwordx4 v132, s[36:37]
	s_waitcnt vmcnt(8)
	s_waitcnt lgkmcnt(0)
	s_barrier
	s_waitcnt lgkmcnt(0)
	v_mfma_f32_16x16x32_bf16 v[124:127], v[140:143], v[182:185], v[124:127]
	v_mfma_f32_16x16x32_bf16 v[120:123], v[158:161], v[182:185], v[120:123]
	v_mfma_f32_16x16x32_bf16 v[108:111], v[140:143], v[190:193], v[108:111]
	v_mfma_f32_16x16x32_bf16 v[104:107], v[158:161], v[190:193], v[104:107]
	v_mfma_f32_16x16x32_bf16 v[92:95], v[140:143], v[198:201], v[92:95]
	v_mfma_f32_16x16x32_bf16 v[88:91], v[158:161], v[198:201], v[88:91]
	v_mfma_f32_16x16x32_bf16 v[76:79], v[140:143], v[208:211], v[76:79]
	v_mfma_f32_16x16x32_bf16 v[72:75], v[158:161], v[208:211], v[72:75]
	v_mfma_f32_16x16x32_bf16 v[124:127], v[144:147], v[186:189], v[124:127]
	v_mfma_f32_16x16x32_bf16 v[120:123], v[162:165], v[186:189], v[120:123]
	v_mfma_f32_16x16x32_bf16 v[108:111], v[144:147], v[194:197], v[108:111]
	v_mfma_f32_16x16x32_bf16 v[104:107], v[162:165], v[194:197], v[104:107]
	v_mfma_f32_16x16x32_bf16 v[92:95], v[144:147], v[202:205], v[92:95]
	v_mfma_f32_16x16x32_bf16 v[88:91], v[162:165], v[202:205], v[88:91]
	v_mfma_f32_16x16x32_bf16 v[76:79], v[144:147], v[212:215], v[76:79]
	v_mfma_f32_16x16x32_bf16 v[72:75], v[162:165], v[212:215], v[72:75]
	v_mfma_f32_16x16x32_bf16 v[116:119], v[166:169], v[182:185], v[116:119]
	v_mfma_f32_16x16x32_bf16 v[112:115], v[174:177], v[182:185], v[112:115]
	v_mfma_f32_16x16x32_bf16 v[100:103], v[166:169], v[190:193], v[100:103]
	v_mfma_f32_16x16x32_bf16 v[96:99], v[174:177], v[190:193], v[96:99]
	v_mfma_f32_16x16x32_bf16 v[84:87], v[166:169], v[198:201], v[84:87]
	v_mfma_f32_16x16x32_bf16 v[80:83], v[174:177], v[198:201], v[80:83]
	v_mfma_f32_16x16x32_bf16 v[68:71], v[166:169], v[208:211], v[68:71]
	v_mfma_f32_16x16x32_bf16 v[64:67], v[174:177], v[208:211], v[64:67]
	v_mfma_f32_16x16x32_bf16 v[116:119], v[170:173], v[186:189], v[116:119]
	v_mfma_f32_16x16x32_bf16 v[112:115], v[178:181], v[186:189], v[112:115]
	v_mfma_f32_16x16x32_bf16 v[100:103], v[170:173], v[194:197], v[100:103]
	v_mfma_f32_16x16x32_bf16 v[96:99], v[178:181], v[194:197], v[96:99]
	v_mfma_f32_16x16x32_bf16 v[84:87], v[170:173], v[202:205], v[84:87]
	v_mfma_f32_16x16x32_bf16 v[80:83], v[178:181], v[202:205], v[80:83]
	v_mfma_f32_16x16x32_bf16 v[68:71], v[170:173], v[212:215], v[68:71]
	v_mfma_f32_16x16x32_bf16 v[64:67], v[178:181], v[212:215], v[64:67]
	s_barrier
	s_add_i32 s62, s54, s45
	s_mov_b32 m0, s62
	ds_read_b128 v[182:185], v155 offset:16384
	ds_read_b128 v[186:189], v155 offset:17408
	ds_read_b128 v[190:193], v155 offset:18432
	ds_read_b128 v[194:197], v155 offset:19456
	ds_read_b128 v[198:201], v155 offset:20480
	ds_read_b128 v[202:205], v155 offset:21504
	ds_read_b128 v[208:211], v155 offset:22528
	ds_read_b128 v[212:215], v155 offset:23552
	global_load_lds_dwordx4 v128, s[38:39]
	s_add_i32 m0, s62, 0x2000
	s_add_u32 s62, s38, 0x40000
	s_mov_b64 s[98:99], s[38:39]
	s_addc_u32 s63, s39, 0
	s_add_i32 s64, s55, s45
	global_load_lds_dwordx4 v130, s[38:39]
	s_mov_b32 m0, s64
	s_mov_b64 s[100:101], s[40:41]
	global_load_lds_dwordx4 v128, s[62:63]
	s_add_i32 m0, s64, 0x2000
	s_nop 0
	global_load_lds_dwordx4 v130, s[62:63]
	s_mov_b32 m0, s46
	s_nop 0
	global_load_lds_dwordx4 v128, s[40:41]
	s_mov_b32 m0, s47
	s_nop 0
	global_load_lds_dwordx4 v130, s[40:41]
	s_waitcnt vmcnt(8)
	s_waitcnt lgkmcnt(0)
	s_barrier
	s_waitcnt lgkmcnt(0)
	v_mfma_f32_16x16x32_bf16 v[60:63], v[140:143], v[182:185], v[60:63]
	v_mfma_f32_16x16x32_bf16 v[56:59], v[158:161], v[182:185], v[56:59]
	v_mfma_f32_16x16x32_bf16 v[44:47], v[140:143], v[190:193], v[44:47]
	v_mfma_f32_16x16x32_bf16 v[40:43], v[158:161], v[190:193], v[40:43]
	v_mfma_f32_16x16x32_bf16 v[28:31], v[140:143], v[198:201], v[28:31]
	v_mfma_f32_16x16x32_bf16 v[24:27], v[158:161], v[198:201], v[24:27]
	v_mfma_f32_16x16x32_bf16 v[12:15], v[140:143], v[208:211], v[12:15]
	v_mfma_f32_16x16x32_bf16 v[8:11], v[158:161], v[208:211], v[8:11]
	v_mfma_f32_16x16x32_bf16 v[60:63], v[144:147], v[186:189], v[60:63]
	v_mfma_f32_16x16x32_bf16 v[56:59], v[162:165], v[186:189], v[56:59]
	v_mfma_f32_16x16x32_bf16 v[44:47], v[144:147], v[194:197], v[44:47]
	v_mfma_f32_16x16x32_bf16 v[40:43], v[162:165], v[194:197], v[40:43]
	v_mfma_f32_16x16x32_bf16 v[28:31], v[144:147], v[202:205], v[28:31]
	v_mfma_f32_16x16x32_bf16 v[24:27], v[162:165], v[202:205], v[24:27]
	v_mfma_f32_16x16x32_bf16 v[12:15], v[144:147], v[212:215], v[12:15]
	v_mfma_f32_16x16x32_bf16 v[8:11], v[162:165], v[212:215], v[8:11]
	v_mfma_f32_16x16x32_bf16 v[52:55], v[166:169], v[182:185], v[52:55]
	v_mfma_f32_16x16x32_bf16 v[48:51], v[174:177], v[182:185], v[48:51]
	v_mfma_f32_16x16x32_bf16 v[36:39], v[166:169], v[190:193], v[36:39]
	v_mfma_f32_16x16x32_bf16 v[32:35], v[174:177], v[190:193], v[32:35]
	v_mfma_f32_16x16x32_bf16 v[20:23], v[166:169], v[198:201], v[20:23]
	v_mfma_f32_16x16x32_bf16 v[16:19], v[174:177], v[198:201], v[16:19]
	v_mfma_f32_16x16x32_bf16 v[4:7], v[166:169], v[208:211], v[4:7]
	v_mfma_f32_16x16x32_bf16 v[0:3], v[174:177], v[208:211], v[0:3]
	v_mfma_f32_16x16x32_bf16 v[52:55], v[170:173], v[186:189], v[52:55]
	v_mfma_f32_16x16x32_bf16 v[48:51], v[178:181], v[186:189], v[48:51]
	v_mfma_f32_16x16x32_bf16 v[36:39], v[170:173], v[194:197], v[36:39]
	v_mfma_f32_16x16x32_bf16 v[32:35], v[178:181], v[194:197], v[32:35]
	v_mfma_f32_16x16x32_bf16 v[20:23], v[170:173], v[202:205], v[20:23]
	v_mfma_f32_16x16x32_bf16 v[16:19], v[178:181], v[202:205], v[16:19]
	v_mfma_f32_16x16x32_bf16 v[4:7], v[170:173], v[212:215], v[4:7]
	v_mfma_f32_16x16x32_bf16 v[0:3], v[178:181], v[212:215], v[0:3]
	s_barrier
	s_add_i32 s62, 0, 0x18000
	v_add_u32_e32 v157, s62, v151
	s_add_i32 s63, 0, 0x1c000
	ds_read_b128 v[140:143], v157
	ds_read_b128 v[144:147], v157 offset:1024
	ds_read_b128 v[158:161], v157 offset:2048
	ds_read_b128 v[162:165], v157 offset:3072
	v_add_u32_e32 v157, s63, v151
	ds_read_b128 v[166:169], v157
	ds_read_b128 v[170:173], v157 offset:1024
	ds_read_b128 v[174:177], v157 offset:2048
	ds_read_b128 v[178:181], v157 offset:3072
	s_add_u32 s40, s40, 0x40000
	s_addc_u32 s41, s41, 0
	s_mov_b32 m0, s48
	ds_read_b128 v[182:185], v155 offset:32768
	ds_read_b128 v[186:189], v155 offset:33792
	ds_read_b128 v[190:193], v155 offset:34816
	ds_read_b128 v[194:197], v155 offset:35840
	ds_read_b128 v[198:201], v155 offset:36864
	ds_read_b128 v[202:205], v155 offset:37888
	ds_read_b128 v[208:211], v155 offset:38912
	ds_read_b128 v[212:215], v155 offset:39936
	global_load_lds_dwordx4 v128, s[40:41]
	s_mov_b32 m0, s49
	s_nop 0
	global_load_lds_dwordx4 v130, s[40:41]
	s_waitcnt vmcnt(8)
	s_waitcnt lgkmcnt(0)
	s_barrier
	s_waitcnt lgkmcnt(0)
	v_mfma_f32_16x16x32_bf16 v[124:127], v[140:143], v[182:185], v[124:127]
	v_mfma_f32_16x16x32_bf16 v[120:123], v[158:161], v[182:185], v[120:123]
	v_mfma_f32_16x16x32_bf16 v[108:111], v[140:143], v[190:193], v[108:111]
	v_mfma_f32_16x16x32_bf16 v[104:107], v[158:161], v[190:193], v[104:107]
	v_mfma_f32_16x16x32_bf16 v[92:95], v[140:143], v[198:201], v[92:95]
	v_mfma_f32_16x16x32_bf16 v[88:91], v[158:161], v[198:201], v[88:91]
	v_mfma_f32_16x16x32_bf16 v[76:79], v[140:143], v[208:211], v[76:79]
	v_mfma_f32_16x16x32_bf16 v[72:75], v[158:161], v[208:211], v[72:75]
	v_mfma_f32_16x16x32_bf16 v[124:127], v[144:147], v[186:189], v[124:127]
	v_mfma_f32_16x16x32_bf16 v[120:123], v[162:165], v[186:189], v[120:123]
	v_mfma_f32_16x16x32_bf16 v[108:111], v[144:147], v[194:197], v[108:111]
	v_mfma_f32_16x16x32_bf16 v[104:107], v[162:165], v[194:197], v[104:107]
	v_mfma_f32_16x16x32_bf16 v[92:95], v[144:147], v[202:205], v[92:95]
	v_mfma_f32_16x16x32_bf16 v[88:91], v[162:165], v[202:205], v[88:91]
	v_mfma_f32_16x16x32_bf16 v[76:79], v[144:147], v[212:215], v[76:79]
	v_mfma_f32_16x16x32_bf16 v[72:75], v[162:165], v[212:215], v[72:75]
	v_mfma_f32_16x16x32_bf16 v[116:119], v[166:169], v[182:185], v[116:119]
	v_mfma_f32_16x16x32_bf16 v[112:115], v[174:177], v[182:185], v[112:115]
	v_mfma_f32_16x16x32_bf16 v[100:103], v[166:169], v[190:193], v[100:103]
	v_mfma_f32_16x16x32_bf16 v[96:99], v[174:177], v[190:193], v[96:99]
	v_mfma_f32_16x16x32_bf16 v[84:87], v[166:169], v[198:201], v[84:87]
	v_mfma_f32_16x16x32_bf16 v[80:83], v[174:177], v[198:201], v[80:83]
	v_mfma_f32_16x16x32_bf16 v[68:71], v[166:169], v[208:211], v[68:71]
	v_mfma_f32_16x16x32_bf16 v[64:67], v[174:177], v[208:211], v[64:67]
	v_mfma_f32_16x16x32_bf16 v[116:119], v[170:173], v[186:189], v[116:119]
	v_mfma_f32_16x16x32_bf16 v[112:115], v[178:181], v[186:189], v[112:115]
	v_mfma_f32_16x16x32_bf16 v[100:103], v[170:173], v[194:197], v[100:103]
	v_mfma_f32_16x16x32_bf16 v[96:99], v[178:181], v[194:197], v[96:99]
	v_mfma_f32_16x16x32_bf16 v[84:87], v[170:173], v[202:205], v[84:87]
	v_mfma_f32_16x16x32_bf16 v[80:83], v[178:181], v[202:205], v[80:83]
	v_mfma_f32_16x16x32_bf16 v[68:71], v[170:173], v[212:215], v[68:71]
	v_mfma_f32_16x16x32_bf16 v[64:67], v[178:181], v[212:215], v[64:67]
	s_barrier
	s_add_i32 s40, s62, s45
	s_mov_b32 m0, s40
	ds_read_b128 v[182:185], v155 offset:49152
	ds_read_b128 v[186:189], v155 offset:50176
	ds_read_b128 v[190:193], v155 offset:51200
	ds_read_b128 v[194:197], v155 offset:52224
	ds_read_b128 v[198:201], v155 offset:53248
	ds_read_b128 v[202:205], v155 offset:54272
	ds_read_b128 v[208:211], v155 offset:55296
	ds_read_b128 v[212:215], v155 offset:56320
	global_load_lds_dwordx4 v148, s[38:39]
	s_add_i32 m0, s40, 0x2000
	s_add_u32 s38, s38, 0x40080
	s_addc_u32 s39, s39, 0
	s_add_i32 s40, s63, s45
	global_load_lds_dwordx4 v149, s[98:99]
	s_mov_b32 m0, s40
	s_nop 0
	global_load_lds_dwordx4 v128, s[38:39]
	s_add_i32 m0, s40, 0x2000
	s_nop 0
	global_load_lds_dwordx4 v130, s[38:39]
	s_mov_b32 m0, s51
	s_nop 0
	global_load_lds_dwordx4 v148, s[100:101]
	s_mov_b32 m0, s52
	s_nop 0
	global_load_lds_dwordx4 v149, s[100:101]
	s_waitcnt vmcnt(8)
	s_waitcnt lgkmcnt(0)
	s_barrier
	s_waitcnt lgkmcnt(0)
	v_mfma_f32_16x16x32_bf16 v[60:63], v[140:143], v[182:185], v[60:63]
	v_mfma_f32_16x16x32_bf16 v[56:59], v[158:161], v[182:185], v[56:59]
	v_mfma_f32_16x16x32_bf16 v[44:47], v[140:143], v[190:193], v[44:47]
	v_mfma_f32_16x16x32_bf16 v[40:43], v[158:161], v[190:193], v[40:43]
	v_mfma_f32_16x16x32_bf16 v[28:31], v[140:143], v[198:201], v[28:31]
	v_mfma_f32_16x16x32_bf16 v[24:27], v[158:161], v[198:201], v[24:27]
	v_mfma_f32_16x16x32_bf16 v[12:15], v[140:143], v[208:211], v[12:15]
	v_mfma_f32_16x16x32_bf16 v[8:11], v[158:161], v[208:211], v[8:11]
	v_mfma_f32_16x16x32_bf16 v[60:63], v[144:147], v[186:189], v[60:63]
	v_mfma_f32_16x16x32_bf16 v[56:59], v[162:165], v[186:189], v[56:59]
	v_mfma_f32_16x16x32_bf16 v[44:47], v[144:147], v[194:197], v[44:47]
	v_mfma_f32_16x16x32_bf16 v[40:43], v[162:165], v[194:197], v[40:43]
	v_mfma_f32_16x16x32_bf16 v[28:31], v[144:147], v[202:205], v[28:31]
	v_mfma_f32_16x16x32_bf16 v[24:27], v[162:165], v[202:205], v[24:27]
	v_mfma_f32_16x16x32_bf16 v[12:15], v[144:147], v[212:215], v[12:15]
	v_mfma_f32_16x16x32_bf16 v[8:11], v[162:165], v[212:215], v[8:11]
	v_mfma_f32_16x16x32_bf16 v[52:55], v[166:169], v[182:185], v[52:55]
	v_mfma_f32_16x16x32_bf16 v[48:51], v[174:177], v[182:185], v[48:51]
	v_mfma_f32_16x16x32_bf16 v[36:39], v[166:169], v[190:193], v[36:39]
	v_mfma_f32_16x16x32_bf16 v[32:35], v[174:177], v[190:193], v[32:35]
	v_mfma_f32_16x16x32_bf16 v[20:23], v[166:169], v[198:201], v[20:23]
	v_mfma_f32_16x16x32_bf16 v[16:19], v[174:177], v[198:201], v[16:19]
	v_mfma_f32_16x16x32_bf16 v[4:7], v[166:169], v[208:211], v[4:7]
	v_mfma_f32_16x16x32_bf16 v[0:3], v[174:177], v[208:211], v[0:3]
	v_mfma_f32_16x16x32_bf16 v[52:55], v[170:173], v[186:189], v[52:55]
	v_mfma_f32_16x16x32_bf16 v[48:51], v[178:181], v[186:189], v[48:51]
	v_mfma_f32_16x16x32_bf16 v[36:39], v[170:173], v[194:197], v[36:39]
	v_mfma_f32_16x16x32_bf16 v[32:35], v[178:181], v[194:197], v[32:35]
	v_mfma_f32_16x16x32_bf16 v[20:23], v[170:173], v[202:205], v[20:23]
	v_mfma_f32_16x16x32_bf16 v[16:19], v[178:181], v[202:205], v[16:19]
	v_mfma_f32_16x16x32_bf16 v[4:7], v[170:173], v[212:215], v[4:7]
	v_mfma_f32_16x16x32_bf16 v[0:3], v[178:181], v[212:215], v[0:3]
	s_barrier
	s_add_i32 s61, s61, 2
	s_add_u32 s59, s59, 0x100
	s_addc_u32 s60, s60, 0
	s_add_u32 s36, s36, 0x100
	s_addc_u32 s37, s37, 0
	s_cmp_gt_u32 s61, 13
	s_cbranch_scc0 .LBB0_895
	s_setprio 0
	s_and_b64 vcc, exec, s[24:25]
	s_cbranch_vccz .LBB0_898
	s_barrier

.LBB0_987:
	s_ashr_i32 s19, s18, 31
	s_lshl_b64 s[6:7], s[18:19], 19
	s_add_u32 s20, s34, s6
	s_addc_u32 s21, s35, s7
	s_and_b64 s[6:7], s[4:5], exec
	s_cselect_b32 s19, s21, s29
	s_cselect_b32 s49, s20, s28
	s_ashr_i32 s17, s16, 31
	s_lshl_b64 s[6:7], s[16:17], 19
	s_add_u32 s22, s36, s6
	s_addc_u32 s23, s37, s7
	s_and_b64 s[6:7], s[4:5], exec
	s_cselect_b32 s17, s23, s27
	s_cselect_b32 s50, s22, s26
	s_add_u32 s51, s26, 0x100
	s_addc_u32 s52, s27, 0
	s_add_u32 s6, s28, 0x40080
	v_mov_b32_e32 v0, 0
	s_addc_u32 s7, s29, 0
	s_mov_b32 s53, -2
	v_mov_b32_e32 v1, v0
	v_mov_b32_e32 v2, v0
	v_mov_b32_e32 v3, v0
	v_mov_b32_e32 v4, v0
	v_mov_b32_e32 v5, v0
	v_mov_b32_e32 v6, v0
	v_mov_b32_e32 v7, v0
	v_mov_b32_e32 v16, v0
	v_mov_b32_e32 v17, v0
	v_mov_b32_e32 v18, v0
	v_mov_b32_e32 v19, v0
	v_mov_b32_e32 v20, v0
	v_mov_b32_e32 v21, v0
	v_mov_b32_e32 v22, v0
	v_mov_b32_e32 v23, v0
	v_mov_b32_e32 v32, v0
	v_mov_b32_e32 v33, v0
	v_mov_b32_e32 v34, v0
	v_mov_b32_e32 v35, v0
	v_mov_b32_e32 v36, v0
	v_mov_b32_e32 v37, v0
	v_mov_b32_e32 v38, v0
	v_mov_b32_e32 v39, v0
	v_mov_b32_e32 v48, v0
	v_mov_b32_e32 v49, v0
	v_mov_b32_e32 v50, v0
	v_mov_b32_e32 v51, v0
	v_mov_b32_e32 v52, v0
	v_mov_b32_e32 v53, v0
	v_mov_b32_e32 v54, v0
	v_mov_b32_e32 v55, v0
	v_mov_b32_e32 v8, v0
	v_mov_b32_e32 v9, v0
	v_mov_b32_e32 v10, v0
	v_mov_b32_e32 v11, v0
	v_mov_b32_e32 v12, v0
	v_mov_b32_e32 v13, v0
	v_mov_b32_e32 v14, v0
	v_mov_b32_e32 v15, v0
	v_mov_b32_e32 v24, v0
	v_mov_b32_e32 v25, v0
	v_mov_b32_e32 v26, v0
	v_mov_b32_e32 v27, v0
	v_mov_b32_e32 v28, v0
	v_mov_b32_e32 v29, v0
	v_mov_b32_e32 v30, v0
	v_mov_b32_e32 v31, v0
	v_mov_b32_e32 v40, v0
	v_mov_b32_e32 v41, v0
	v_mov_b32_e32 v42, v0
	v_mov_b32_e32 v43, v0
	v_mov_b32_e32 v44, v0
	v_mov_b32_e32 v45, v0
	v_mov_b32_e32 v46, v0
	v_mov_b32_e32 v47, v0
	v_mov_b32_e32 v56, v0
	v_mov_b32_e32 v57, v0
	v_mov_b32_e32 v58, v0
	v_mov_b32_e32 v59, v0
	v_mov_b32_e32 v60, v0
	v_mov_b32_e32 v61, v0
	v_mov_b32_e32 v62, v0
	v_mov_b32_e32 v63, v0
	v_mov_b32_e32 v64, v0
	v_mov_b32_e32 v65, v0
	v_mov_b32_e32 v66, v0
	v_mov_b32_e32 v67, v0
	v_mov_b32_e32 v68, v0
	v_mov_b32_e32 v69, v0
	v_mov_b32_e32 v70, v0
	v_mov_b32_e32 v71, v0
	v_mov_b32_e32 v80, v0
	v_mov_b32_e32 v81, v0
	v_mov_b32_e32 v82, v0
	v_mov_b32_e32 v83, v0
	v_mov_b32_e32 v84, v0
	v_mov_b32_e32 v85, v0
	v_mov_b32_e32 v86, v0
	v_mov_b32_e32 v87, v0
	v_mov_b32_e32 v96, v0
	v_mov_b32_e32 v97, v0
	v_mov_b32_e32 v98, v0
	v_mov_b32_e32 v99, v0
	v_mov_b32_e32 v100, v0
	v_mov_b32_e32 v101, v0
	v_mov_b32_e32 v102, v0
	v_mov_b32_e32 v103, v0
	v_mov_b32_e32 v112, v0
	v_mov_b32_e32 v113, v0
	v_mov_b32_e32 v114, v0
	v_mov_b32_e32 v115, v0
	v_mov_b32_e32 v116, v0
	v_mov_b32_e32 v117, v0
	v_mov_b32_e32 v118, v0
	v_mov_b32_e32 v119, v0
	v_mov_b32_e32 v72, v0
	v_mov_b32_e32 v73, v0
	v_mov_b32_e32 v74, v0
	v_mov_b32_e32 v75, v0
	v_mov_b32_e32 v76, v0
	v_mov_b32_e32 v77, v0
	v_mov_b32_e32 v78, v0
	v_mov_b32_e32 v79, v0
	v_mov_b32_e32 v88, v0
	v_mov_b32_e32 v89, v0
	v_mov_b32_e32 v90, v0
	v_mov_b32_e32 v91, v0
	v_mov_b32_e32 v92, v0
	v_mov_b32_e32 v93, v0
	v_mov_b32_e32 v94, v0
	v_mov_b32_e32 v95, v0
	v_mov_b32_e32 v104, v0
	v_mov_b32_e32 v105, v0
	v_mov_b32_e32 v106, v0
	v_mov_b32_e32 v107, v0
	v_mov_b32_e32 v108, v0
	v_mov_b32_e32 v109, v0
	v_mov_b32_e32 v110, v0
	v_mov_b32_e32 v111, v0
	v_mov_b32_e32 v120, v0
	v_mov_b32_e32 v121, v0
	v_mov_b32_e32 v122, v0
	v_mov_b32_e32 v123, v0
	v_mov_b32_e32 v124, v0
	v_mov_b32_e32 v125, v0
	v_mov_b32_e32 v126, v0
	v_mov_b32_e32 v127, v0
	v_add_u32_e32 v204, 0x80, v128
	v_add_u32_e32 v205, 0x80, v130
	v_add_u32_e32 v220, 0x80, v132
	v_add_u32_e32 v221, 0x80, v134
	v_readfirstlane_b32 s101, v206
	s_nop 3
	s_lshr_b32 s101, s101, 8
	s_cmp_eq_u32 s101, 1
	s_cbranch_scc0 .Lprio_skip_16
	s_setprio 1

.LBB0_988:
	ds_read_b128 v[144:147], v151
	ds_read_b128 v[156:159], v151 offset:1024
	ds_read_b128 v[160:163], v151 offset:2048
	ds_read_b128 v[164:167], v151 offset:3072
	ds_read_b128 v[168:171], v152
	ds_read_b128 v[172:175], v152 offset:1024
	ds_read_b128 v[176:179], v152 offset:2048
	ds_read_b128 v[180:183], v152 offset:3072
	s_add_u32 s26, s6, 0xfffc0080
	s_addc_u32 s27, s7, -1
	s_cmp_eq_u32 s53, 12
	s_cselect_b32 s29, s19, s27
	s_cselect_b32 s28, s49, s26
	s_cselect_b32 s27, s17, s52
	s_cselect_b32 s26, s50, s51
	s_add_i32 m0, s25, 0xc000
	ds_read_b128 v[184:187], v153
	ds_read_b128 v[188:191], v153 offset:1024
	ds_read_b128 v[192:195], v153 offset:2048
	ds_read_b128 v[196:199], v153 offset:3072
	ds_read_b128 v[200:203], v153 offset:4096
	ds_read_b128 v[208:211], v153 offset:5120
	ds_read_b128 v[212:215], v153 offset:6144
	ds_read_b128 v[216:219], v153 offset:7168
	global_load_lds_dwordx4 v138, s[6:7]
	s_add_i32 m0, s25, 0xe000
	s_nop 0
	global_load_lds_dwordx4 v136, s[6:7]
	s_waitcnt vmcnt(8)
	s_waitcnt lgkmcnt(0)
	s_barrier
	s_waitcnt lgkmcnt(0)
	v_mfma_f32_16x16x32_bf16 v[124:127], v[144:147], v[184:187], v[124:127]
	v_mfma_f32_16x16x32_bf16 v[120:123], v[160:163], v[184:187], v[120:123]
	v_mfma_f32_16x16x32_bf16 v[108:111], v[144:147], v[192:195], v[108:111]
	v_mfma_f32_16x16x32_bf16 v[104:107], v[160:163], v[192:195], v[104:107]
	v_mfma_f32_16x16x32_bf16 v[92:95], v[144:147], v[200:203], v[92:95]
	v_mfma_f32_16x16x32_bf16 v[88:91], v[160:163], v[200:203], v[88:91]
	v_mfma_f32_16x16x32_bf16 v[76:79], v[144:147], v[212:215], v[76:79]
	v_mfma_f32_16x16x32_bf16 v[72:75], v[160:163], v[212:215], v[72:75]
	v_mfma_f32_16x16x32_bf16 v[124:127], v[156:159], v[188:191], v[124:127]
	v_mfma_f32_16x16x32_bf16 v[120:123], v[164:167], v[188:191], v[120:123]
	v_mfma_f32_16x16x32_bf16 v[108:111], v[156:159], v[196:199], v[108:111]
	v_mfma_f32_16x16x32_bf16 v[104:107], v[164:167], v[196:199], v[104:107]
	v_mfma_f32_16x16x32_bf16 v[92:95], v[156:159], v[208:211], v[92:95]
	v_mfma_f32_16x16x32_bf16 v[88:91], v[164:167], v[208:211], v[88:91]
	v_mfma_f32_16x16x32_bf16 v[76:79], v[156:159], v[216:219], v[76:79]
	v_mfma_f32_16x16x32_bf16 v[72:75], v[164:167], v[216:219], v[72:75]
	v_mfma_f32_16x16x32_bf16 v[116:119], v[168:171], v[184:187], v[116:119]
	v_mfma_f32_16x16x32_bf16 v[112:115], v[176:179], v[184:187], v[112:115]
	v_mfma_f32_16x16x32_bf16 v[100:103], v[168:171], v[192:195], v[100:103]
	v_mfma_f32_16x16x32_bf16 v[96:99], v[176:179], v[192:195], v[96:99]
	v_mfma_f32_16x16x32_bf16 v[84:87], v[168:171], v[200:203], v[84:87]
	v_mfma_f32_16x16x32_bf16 v[80:83], v[176:179], v[200:203], v[80:83]
	v_mfma_f32_16x16x32_bf16 v[68:71], v[168:171], v[212:215], v[68:71]
	v_mfma_f32_16x16x32_bf16 v[64:67], v[176:179], v[212:215], v[64:67]
	v_mfma_f32_16x16x32_bf16 v[116:119], v[172:175], v[188:191], v[116:119]
	v_mfma_f32_16x16x32_bf16 v[112:115], v[180:183], v[188:191], v[112:115]
	v_mfma_f32_16x16x32_bf16 v[100:103], v[172:175], v[196:199], v[100:103]
	v_mfma_f32_16x16x32_bf16 v[96:99], v[180:183], v[196:199], v[96:99]
	v_mfma_f32_16x16x32_bf16 v[84:87], v[172:175], v[208:211], v[84:87]
	v_mfma_f32_16x16x32_bf16 v[80:83], v[180:183], v[208:211], v[80:83]
	v_mfma_f32_16x16x32_bf16 v[68:71], v[172:175], v[216:219], v[68:71]
	v_mfma_f32_16x16x32_bf16 v[64:67], v[180:183], v[216:219], v[64:67]
	s_barrier
	s_add_i32 s54, s45, s38
	s_mov_b32 m0, s54
	ds_read_b128 v[184:187], v153 offset:16384
	ds_read_b128 v[188:191], v153 offset:17408
	ds_read_b128 v[192:195], v153 offset:18432
	ds_read_b128 v[196:199], v153 offset:19456
	ds_read_b128 v[200:203], v153 offset:20480
	ds_read_b128 v[208:211], v153 offset:21504
	ds_read_b128 v[212:215], v153 offset:22528
	ds_read_b128 v[216:219], v153 offset:23552
	global_load_lds_dwordx4 v130, s[26:27]
	s_add_i32 m0, s54, 0x2000
	s_add_u32 s54, s26, 0x40000
	s_mov_b64 s[98:99], s[26:27]
	s_addc_u32 s55, s27, 0
	s_add_i32 s56, s46, s38
	global_load_lds_dwordx4 v134, s[26:27]
	s_mov_b32 m0, s56
	s_mov_b64 s[100:101], s[28:29]
	global_load_lds_dwordx4 v130, s[54:55]
	s_add_i32 m0, s56, 0x2000
	s_nop 0
	global_load_lds_dwordx4 v134, s[54:55]
	s_mov_b32 m0, s25
	s_nop 0
	global_load_lds_dwordx4 v128, s[28:29]
	s_mov_b32 m0, s39
	s_nop 0
	global_load_lds_dwordx4 v132, s[28:29]
	s_waitcnt vmcnt(8)
	s_waitcnt lgkmcnt(0)
	s_barrier
	s_waitcnt lgkmcnt(0)
	v_mfma_f32_16x16x32_bf16 v[60:63], v[144:147], v[184:187], v[60:63]
	v_mfma_f32_16x16x32_bf16 v[56:59], v[160:163], v[184:187], v[56:59]
	v_mfma_f32_16x16x32_bf16 v[44:47], v[144:147], v[192:195], v[44:47]
	v_mfma_f32_16x16x32_bf16 v[40:43], v[160:163], v[192:195], v[40:43]
	v_mfma_f32_16x16x32_bf16 v[28:31], v[144:147], v[200:203], v[28:31]
	v_mfma_f32_16x16x32_bf16 v[24:27], v[160:163], v[200:203], v[24:27]
	v_mfma_f32_16x16x32_bf16 v[12:15], v[144:147], v[212:215], v[12:15]
	v_mfma_f32_16x16x32_bf16 v[8:11], v[160:163], v[212:215], v[8:11]
	v_mfma_f32_16x16x32_bf16 v[60:63], v[156:159], v[188:191], v[60:63]
	v_mfma_f32_16x16x32_bf16 v[56:59], v[164:167], v[188:191], v[56:59]
	v_mfma_f32_16x16x32_bf16 v[44:47], v[156:159], v[196:199], v[44:47]
	v_mfma_f32_16x16x32_bf16 v[40:43], v[164:167], v[196:199], v[40:43]
	v_mfma_f32_16x16x32_bf16 v[28:31], v[156:159], v[208:211], v[28:31]
	v_mfma_f32_16x16x32_bf16 v[24:27], v[164:167], v[208:211], v[24:27]
	v_mfma_f32_16x16x32_bf16 v[12:15], v[156:159], v[216:219], v[12:15]
	v_mfma_f32_16x16x32_bf16 v[8:11], v[164:167], v[216:219], v[8:11]
	v_mfma_f32_16x16x32_bf16 v[52:55], v[168:171], v[184:187], v[52:55]
	v_mfma_f32_16x16x32_bf16 v[48:51], v[176:179], v[184:187], v[48:51]
	v_mfma_f32_16x16x32_bf16 v[36:39], v[168:171], v[192:195], v[36:39]
	v_mfma_f32_16x16x32_bf16 v[32:35], v[176:179], v[192:195], v[32:35]
	v_mfma_f32_16x16x32_bf16 v[20:23], v[168:171], v[200:203], v[20:23]
	v_mfma_f32_16x16x32_bf16 v[16:19], v[176:179], v[200:203], v[16:19]
	v_mfma_f32_16x16x32_bf16 v[4:7], v[168:171], v[212:215], v[4:7]
	v_mfma_f32_16x16x32_bf16 v[0:3], v[176:179], v[212:215], v[0:3]
	v_mfma_f32_16x16x32_bf16 v[52:55], v[172:175], v[188:191], v[52:55]
	v_mfma_f32_16x16x32_bf16 v[48:51], v[180:183], v[188:191], v[48:51]
	v_mfma_f32_16x16x32_bf16 v[36:39], v[172:175], v[196:199], v[36:39]
	v_mfma_f32_16x16x32_bf16 v[32:35], v[180:183], v[196:199], v[32:35]
	v_mfma_f32_16x16x32_bf16 v[20:23], v[172:175], v[208:211], v[20:23]
	v_mfma_f32_16x16x32_bf16 v[16:19], v[180:183], v[208:211], v[16:19]
	v_mfma_f32_16x16x32_bf16 v[4:7], v[172:175], v[216:219], v[4:7]
	v_mfma_f32_16x16x32_bf16 v[0:3], v[180:183], v[216:219], v[0:3]
	s_barrier
	s_add_i32 s54, 0, 0x18000
	v_add_u32_e32 v155, s54, v149
	s_add_i32 s55, 0, 0x1c000
	ds_read_b128 v[144:147], v155
	ds_read_b128 v[156:159], v155 offset:1024
	ds_read_b128 v[160:163], v155 offset:2048
	ds_read_b128 v[164:167], v155 offset:3072
	v_add_u32_e32 v155, s55, v149
	ds_read_b128 v[168:171], v155
	ds_read_b128 v[172:175], v155 offset:1024
	ds_read_b128 v[176:179], v155 offset:2048
	ds_read_b128 v[180:183], v155 offset:3072
	s_add_u32 s28, s28, 0x40000
	s_addc_u32 s29, s29, 0
	s_mov_b32 m0, s40
	ds_read_b128 v[184:187], v153 offset:32768
	ds_read_b128 v[188:191], v153 offset:33792
	ds_read_b128 v[192:195], v153 offset:34816
	ds_read_b128 v[196:199], v153 offset:35840
	ds_read_b128 v[200:203], v153 offset:36864
	ds_read_b128 v[208:211], v153 offset:37888
	ds_read_b128 v[212:215], v153 offset:38912
	ds_read_b128 v[216:219], v153 offset:39936
	global_load_lds_dwordx4 v128, s[28:29]
	s_mov_b32 m0, s41
	s_nop 0
	global_load_lds_dwordx4 v132, s[28:29]
	s_waitcnt vmcnt(8)
	s_waitcnt lgkmcnt(0)
	s_barrier
	s_waitcnt lgkmcnt(0)
	v_mfma_f32_16x16x32_bf16 v[124:127], v[144:147], v[184:187], v[124:127]
	v_mfma_f32_16x16x32_bf16 v[120:123], v[160:163], v[184:187], v[120:123]
	v_mfma_f32_16x16x32_bf16 v[108:111], v[144:147], v[192:195], v[108:111]
	v_mfma_f32_16x16x32_bf16 v[104:107], v[160:163], v[192:195], v[104:107]
	v_mfma_f32_16x16x32_bf16 v[92:95], v[144:147], v[200:203], v[92:95]
	v_mfma_f32_16x16x32_bf16 v[88:91], v[160:163], v[200:203], v[88:91]
	v_mfma_f32_16x16x32_bf16 v[76:79], v[144:147], v[212:215], v[76:79]
	v_mfma_f32_16x16x32_bf16 v[72:75], v[160:163], v[212:215], v[72:75]
	v_mfma_f32_16x16x32_bf16 v[124:127], v[156:159], v[188:191], v[124:127]
	v_mfma_f32_16x16x32_bf16 v[120:123], v[164:167], v[188:191], v[120:123]
	v_mfma_f32_16x16x32_bf16 v[108:111], v[156:159], v[196:199], v[108:111]
	v_mfma_f32_16x16x32_bf16 v[104:107], v[164:167], v[196:199], v[104:107]
	v_mfma_f32_16x16x32_bf16 v[92:95], v[156:159], v[208:211], v[92:95]
	v_mfma_f32_16x16x32_bf16 v[88:91], v[164:167], v[208:211], v[88:91]
	v_mfma_f32_16x16x32_bf16 v[76:79], v[156:159], v[216:219], v[76:79]
	v_mfma_f32_16x16x32_bf16 v[72:75], v[164:167], v[216:219], v[72:75]
	v_mfma_f32_16x16x32_bf16 v[116:119], v[168:171], v[184:187], v[116:119]
	v_mfma_f32_16x16x32_bf16 v[112:115], v[176:179], v[184:187], v[112:115]
	v_mfma_f32_16x16x32_bf16 v[100:103], v[168:171], v[192:195], v[100:103]
	v_mfma_f32_16x16x32_bf16 v[96:99], v[176:179], v[192:195], v[96:99]
	v_mfma_f32_16x16x32_bf16 v[84:87], v[168:171], v[200:203], v[84:87]
	v_mfma_f32_16x16x32_bf16 v[80:83], v[176:179], v[200:203], v[80:83]
	v_mfma_f32_16x16x32_bf16 v[68:71], v[168:171], v[212:215], v[68:71]
	v_mfma_f32_16x16x32_bf16 v[64:67], v[176:179], v[212:215], v[64:67]
	v_mfma_f32_16x16x32_bf16 v[116:119], v[172:175], v[188:191], v[116:119]
	v_mfma_f32_16x16x32_bf16 v[112:115], v[180:183], v[188:191], v[112:115]
	v_mfma_f32_16x16x32_bf16 v[100:103], v[172:175], v[196:199], v[100:103]
	v_mfma_f32_16x16x32_bf16 v[96:99], v[180:183], v[196:199], v[96:99]
	v_mfma_f32_16x16x32_bf16 v[84:87], v[172:175], v[208:211], v[84:87]
	v_mfma_f32_16x16x32_bf16 v[80:83], v[180:183], v[208:211], v[80:83]
	v_mfma_f32_16x16x32_bf16 v[68:71], v[172:175], v[216:219], v[68:71]
	v_mfma_f32_16x16x32_bf16 v[64:67], v[180:183], v[216:219], v[64:67]
	s_barrier
	s_add_i32 s28, s54, s38
	s_mov_b32 m0, s28
	ds_read_b128 v[184:187], v153 offset:49152
	ds_read_b128 v[188:191], v153 offset:50176
	ds_read_b128 v[192:195], v153 offset:51200
	ds_read_b128 v[196:199], v153 offset:52224
	ds_read_b128 v[200:203], v153 offset:53248
	ds_read_b128 v[208:211], v153 offset:54272
	ds_read_b128 v[212:215], v153 offset:55296
	ds_read_b128 v[216:219], v153 offset:56320
	global_load_lds_dwordx4 v205, s[26:27]
	s_add_i32 m0, s28, 0x2000
	s_add_u32 s26, s26, 0x40080
	s_addc_u32 s27, s27, 0
	s_add_i32 s28, s55, s38
	global_load_lds_dwordx4 v221, s[98:99]
	s_mov_b32 m0, s28
	s_nop 0
	global_load_lds_dwordx4 v130, s[26:27]
	s_add_i32 m0, s28, 0x2000
	s_nop 0
	global_load_lds_dwordx4 v134, s[26:27]
	s_mov_b32 m0, s43
	s_nop 0
	global_load_lds_dwordx4 v204, s[100:101]
	s_mov_b32 m0, s44
	s_nop 0
	global_load_lds_dwordx4 v220, s[100:101]
	s_waitcnt vmcnt(8)
	s_waitcnt lgkmcnt(0)
	s_barrier
	s_waitcnt lgkmcnt(0)
	v_mfma_f32_16x16x32_bf16 v[60:63], v[144:147], v[184:187], v[60:63]
	v_mfma_f32_16x16x32_bf16 v[56:59], v[160:163], v[184:187], v[56:59]
	v_mfma_f32_16x16x32_bf16 v[44:47], v[144:147], v[192:195], v[44:47]
	v_mfma_f32_16x16x32_bf16 v[40:43], v[160:163], v[192:195], v[40:43]
	v_mfma_f32_16x16x32_bf16 v[28:31], v[144:147], v[200:203], v[28:31]
	v_mfma_f32_16x16x32_bf16 v[24:27], v[160:163], v[200:203], v[24:27]
	v_mfma_f32_16x16x32_bf16 v[12:15], v[144:147], v[212:215], v[12:15]
	v_mfma_f32_16x16x32_bf16 v[8:11], v[160:163], v[212:215], v[8:11]
	v_mfma_f32_16x16x32_bf16 v[60:63], v[156:159], v[188:191], v[60:63]
	v_mfma_f32_16x16x32_bf16 v[56:59], v[164:167], v[188:191], v[56:59]
	v_mfma_f32_16x16x32_bf16 v[44:47], v[156:159], v[196:199], v[44:47]
	v_mfma_f32_16x16x32_bf16 v[40:43], v[164:167], v[196:199], v[40:43]
	v_mfma_f32_16x16x32_bf16 v[28:31], v[156:159], v[208:211], v[28:31]
	v_mfma_f32_16x16x32_bf16 v[24:27], v[164:167], v[208:211], v[24:27]
	v_mfma_f32_16x16x32_bf16 v[12:15], v[156:159], v[216:219], v[12:15]
	v_mfma_f32_16x16x32_bf16 v[8:11], v[164:167], v[216:219], v[8:11]
	v_mfma_f32_16x16x32_bf16 v[52:55], v[168:171], v[184:187], v[52:55]
	v_mfma_f32_16x16x32_bf16 v[48:51], v[176:179], v[184:187], v[48:51]
	v_mfma_f32_16x16x32_bf16 v[36:39], v[168:171], v[192:195], v[36:39]
	v_mfma_f32_16x16x32_bf16 v[32:35], v[176:179], v[192:195], v[32:35]
	v_mfma_f32_16x16x32_bf16 v[20:23], v[168:171], v[200:203], v[20:23]
	v_mfma_f32_16x16x32_bf16 v[16:19], v[176:179], v[200:203], v[16:19]
	v_mfma_f32_16x16x32_bf16 v[4:7], v[168:171], v[212:215], v[4:7]
	v_mfma_f32_16x16x32_bf16 v[0:3], v[176:179], v[212:215], v[0:3]
	v_mfma_f32_16x16x32_bf16 v[52:55], v[172:175], v[188:191], v[52:55]
	v_mfma_f32_16x16x32_bf16 v[48:51], v[180:183], v[188:191], v[48:51]
	v_mfma_f32_16x16x32_bf16 v[36:39], v[172:175], v[196:199], v[36:39]
	v_mfma_f32_16x16x32_bf16 v[32:35], v[180:183], v[196:199], v[32:35]
	v_mfma_f32_16x16x32_bf16 v[20:23], v[172:175], v[208:211], v[20:23]
	v_mfma_f32_16x16x32_bf16 v[16:19], v[180:183], v[208:211], v[16:19]
	v_mfma_f32_16x16x32_bf16 v[4:7], v[172:175], v[216:219], v[4:7]
	v_mfma_f32_16x16x32_bf16 v[0:3], v[180:183], v[216:219], v[0:3]
	s_barrier
	s_add_i32 s53, s53, 2
	s_add_u32 s51, s51, 0x100
	s_addc_u32 s52, s52, 0
	s_add_u32 s6, s6, 0x100
	s_addc_u32 s7, s7, 0
	s_cmp_gt_u32 s53, 13
	s_cbranch_scc0 .LBB0_988
	s_setprio 0
	s_and_b64 vcc, exec, s[14:15]
	s_cbranch_vccz .LBB0_991
	s_barrier

.LBB0_1192:
	s_ashr_i32 s17, s16, 31
	s_lshl_b64 s[18:19], s[16:17], 18
	s_add_u32 s18, s6, s18
	s_addc_u32 s19, s7, s19
	s_and_b64 s[20:21], s[4:5], exec
	s_cselect_b32 s17, s19, s27
	s_cselect_b32 s46, s18, s26
	s_ashr_i32 s15, s14, 31
	s_lshl_b64 s[20:21], s[14:15], 18
	s_add_u32 s20, s34, s20
	s_addc_u32 s21, s35, s21
	s_and_b64 s[28:29], s[4:5], exec
	s_cselect_b32 s15, s21, s25
	s_cselect_b32 s47, s20, s24
	s_add_u32 s48, s24, 0x100
	s_addc_u32 s49, s25, 0
	s_add_u32 s24, s26, 0x20080
	v_mov_b32_e32 v0, 0
	s_addc_u32 s25, s27, 0
	s_mov_b32 s50, -2
	v_mov_b32_e32 v1, v0
	v_mov_b32_e32 v2, v0
	v_mov_b32_e32 v3, v0
	v_mov_b32_e32 v4, v0
	v_mov_b32_e32 v5, v0
	v_mov_b32_e32 v6, v0
	v_mov_b32_e32 v7, v0
	v_mov_b32_e32 v16, v0
	v_mov_b32_e32 v17, v0
	v_mov_b32_e32 v18, v0
	v_mov_b32_e32 v19, v0
	v_mov_b32_e32 v20, v0
	v_mov_b32_e32 v21, v0
	v_mov_b32_e32 v22, v0
	v_mov_b32_e32 v23, v0
	v_mov_b32_e32 v32, v0
	v_mov_b32_e32 v33, v0
	v_mov_b32_e32 v34, v0
	v_mov_b32_e32 v35, v0
	v_mov_b32_e32 v36, v0
	v_mov_b32_e32 v37, v0
	v_mov_b32_e32 v38, v0
	v_mov_b32_e32 v39, v0
	v_mov_b32_e32 v48, v0
	v_mov_b32_e32 v49, v0
	v_mov_b32_e32 v50, v0
	v_mov_b32_e32 v51, v0
	v_mov_b32_e32 v52, v0
	v_mov_b32_e32 v53, v0
	v_mov_b32_e32 v54, v0
	v_mov_b32_e32 v55, v0
	v_mov_b32_e32 v8, v0
	v_mov_b32_e32 v9, v0
	v_mov_b32_e32 v10, v0
	v_mov_b32_e32 v11, v0
	v_mov_b32_e32 v12, v0
	v_mov_b32_e32 v13, v0
	v_mov_b32_e32 v14, v0
	v_mov_b32_e32 v15, v0
	v_mov_b32_e32 v24, v0
	v_mov_b32_e32 v25, v0
	v_mov_b32_e32 v26, v0
	v_mov_b32_e32 v27, v0
	v_mov_b32_e32 v28, v0
	v_mov_b32_e32 v29, v0
	v_mov_b32_e32 v30, v0
	v_mov_b32_e32 v31, v0
	v_mov_b32_e32 v40, v0
	v_mov_b32_e32 v41, v0
	v_mov_b32_e32 v42, v0
	v_mov_b32_e32 v43, v0
	v_mov_b32_e32 v44, v0
	v_mov_b32_e32 v45, v0
	v_mov_b32_e32 v46, v0
	v_mov_b32_e32 v47, v0
	v_mov_b32_e32 v56, v0
	v_mov_b32_e32 v57, v0
	v_mov_b32_e32 v58, v0
	v_mov_b32_e32 v59, v0
	v_mov_b32_e32 v60, v0
	v_mov_b32_e32 v61, v0
	v_mov_b32_e32 v62, v0
	v_mov_b32_e32 v63, v0
	v_mov_b32_e32 v64, v0
	v_mov_b32_e32 v65, v0
	v_mov_b32_e32 v66, v0
	v_mov_b32_e32 v67, v0
	v_mov_b32_e32 v68, v0
	v_mov_b32_e32 v69, v0
	v_mov_b32_e32 v70, v0
	v_mov_b32_e32 v71, v0
	v_mov_b32_e32 v80, v0
	v_mov_b32_e32 v81, v0
	v_mov_b32_e32 v82, v0
	v_mov_b32_e32 v83, v0
	v_mov_b32_e32 v84, v0
	v_mov_b32_e32 v85, v0
	v_mov_b32_e32 v86, v0
	v_mov_b32_e32 v87, v0
	v_mov_b32_e32 v96, v0
	v_mov_b32_e32 v97, v0
	v_mov_b32_e32 v98, v0
	v_mov_b32_e32 v99, v0
	v_mov_b32_e32 v100, v0
	v_mov_b32_e32 v101, v0
	v_mov_b32_e32 v102, v0
	v_mov_b32_e32 v103, v0
	v_mov_b32_e32 v112, v0
	v_mov_b32_e32 v113, v0
	v_mov_b32_e32 v114, v0
	v_mov_b32_e32 v115, v0
	v_mov_b32_e32 v116, v0
	v_mov_b32_e32 v117, v0
	v_mov_b32_e32 v118, v0
	v_mov_b32_e32 v119, v0
	v_mov_b32_e32 v72, v0
	v_mov_b32_e32 v73, v0
	v_mov_b32_e32 v74, v0
	v_mov_b32_e32 v75, v0
	v_mov_b32_e32 v76, v0
	v_mov_b32_e32 v77, v0
	v_mov_b32_e32 v78, v0
	v_mov_b32_e32 v79, v0
	v_mov_b32_e32 v88, v0
	v_mov_b32_e32 v89, v0
	v_mov_b32_e32 v90, v0
	v_mov_b32_e32 v91, v0
	v_mov_b32_e32 v92, v0
	v_mov_b32_e32 v93, v0
	v_mov_b32_e32 v94, v0
	v_mov_b32_e32 v95, v0
	v_mov_b32_e32 v104, v0
	v_mov_b32_e32 v105, v0
	v_mov_b32_e32 v106, v0
	v_mov_b32_e32 v107, v0
	v_mov_b32_e32 v108, v0
	v_mov_b32_e32 v109, v0
	v_mov_b32_e32 v110, v0
	v_mov_b32_e32 v111, v0
	v_mov_b32_e32 v120, v0
	v_mov_b32_e32 v121, v0
	v_mov_b32_e32 v122, v0
	v_mov_b32_e32 v123, v0
	v_mov_b32_e32 v124, v0
	v_mov_b32_e32 v125, v0
	v_mov_b32_e32 v126, v0
	v_mov_b32_e32 v127, v0
	v_add_u32_e32 v216, 0x80, v128
	v_add_u32_e32 v217, 0x80, v130
	v_add_u32_e32 v218, 0x80, v132
	v_add_u32_e32 v219, 0x80, v134
	v_readfirstlane_b32 s101, v206
	s_nop 3
	s_lshr_b32 s101, s101, 8
	s_cmp_eq_u32 s101, 1
	s_cbranch_scc0 .Lprio_skip_15
	s_setprio 1

.LBB0_1193:
	ds_read_b128 v[144:147], v151
	ds_read_b128 v[154:157], v151 offset:1024
	ds_read_b128 v[158:161], v151 offset:2048
	ds_read_b128 v[162:165], v151 offset:3072
	ds_read_b128 v[166:169], v152
	ds_read_b128 v[170:173], v152 offset:1024
	ds_read_b128 v[174:177], v152 offset:2048
	ds_read_b128 v[178:181], v152 offset:3072
	s_add_u32 s26, s24, 0xfffe0080
	s_addc_u32 s27, s25, -1
	s_cmp_eq_u32 s50, 4
	s_cselect_b32 s29, s17, s27
	s_cselect_b32 s28, s46, s26
	s_cselect_b32 s27, s15, s49
	s_cselect_b32 s26, s47, s48
	s_add_i32 m0, s23, 0xc000
	ds_read_b128 v[182:185], v153
	ds_read_b128 v[186:189], v153 offset:1024
	ds_read_b128 v[190:193], v153 offset:2048
	ds_read_b128 v[194:197], v153 offset:3072
	ds_read_b128 v[198:201], v153 offset:4096
	ds_read_b128 v[202:205], v153 offset:5120
	ds_read_b128 v[208:211], v153 offset:6144
	ds_read_b128 v[212:215], v153 offset:7168
	global_load_lds_dwordx4 v138, s[24:25]
	s_add_i32 m0, s23, 0xe000
	s_nop 0
	global_load_lds_dwordx4 v136, s[24:25]
	s_waitcnt vmcnt(8)
	s_waitcnt lgkmcnt(0)
	s_barrier
	s_waitcnt lgkmcnt(0)
	v_mfma_f32_16x16x32_bf16 v[124:127], v[144:147], v[182:185], v[124:127]
	v_mfma_f32_16x16x32_bf16 v[120:123], v[158:161], v[182:185], v[120:123]
	v_mfma_f32_16x16x32_bf16 v[108:111], v[144:147], v[190:193], v[108:111]
	v_mfma_f32_16x16x32_bf16 v[104:107], v[158:161], v[190:193], v[104:107]
	v_mfma_f32_16x16x32_bf16 v[92:95], v[144:147], v[198:201], v[92:95]
	v_mfma_f32_16x16x32_bf16 v[88:91], v[158:161], v[198:201], v[88:91]
	v_mfma_f32_16x16x32_bf16 v[76:79], v[144:147], v[208:211], v[76:79]
	v_mfma_f32_16x16x32_bf16 v[72:75], v[158:161], v[208:211], v[72:75]
	v_mfma_f32_16x16x32_bf16 v[124:127], v[154:157], v[186:189], v[124:127]
	v_mfma_f32_16x16x32_bf16 v[120:123], v[162:165], v[186:189], v[120:123]
	v_mfma_f32_16x16x32_bf16 v[108:111], v[154:157], v[194:197], v[108:111]
	v_mfma_f32_16x16x32_bf16 v[104:107], v[162:165], v[194:197], v[104:107]
	v_mfma_f32_16x16x32_bf16 v[92:95], v[154:157], v[202:205], v[92:95]
	v_mfma_f32_16x16x32_bf16 v[88:91], v[162:165], v[202:205], v[88:91]
	v_mfma_f32_16x16x32_bf16 v[76:79], v[154:157], v[212:215], v[76:79]
	v_mfma_f32_16x16x32_bf16 v[72:75], v[162:165], v[212:215], v[72:75]
	v_mfma_f32_16x16x32_bf16 v[116:119], v[166:169], v[182:185], v[116:119]
	v_mfma_f32_16x16x32_bf16 v[112:115], v[174:177], v[182:185], v[112:115]
	v_mfma_f32_16x16x32_bf16 v[100:103], v[166:169], v[190:193], v[100:103]
	v_mfma_f32_16x16x32_bf16 v[96:99], v[174:177], v[190:193], v[96:99]
	v_mfma_f32_16x16x32_bf16 v[84:87], v[166:169], v[198:201], v[84:87]
	v_mfma_f32_16x16x32_bf16 v[80:83], v[174:177], v[198:201], v[80:83]
	v_mfma_f32_16x16x32_bf16 v[68:71], v[166:169], v[208:211], v[68:71]
	v_mfma_f32_16x16x32_bf16 v[64:67], v[174:177], v[208:211], v[64:67]
	v_mfma_f32_16x16x32_bf16 v[116:119], v[170:173], v[186:189], v[116:119]
	v_mfma_f32_16x16x32_bf16 v[112:115], v[178:181], v[186:189], v[112:115]
	v_mfma_f32_16x16x32_bf16 v[100:103], v[170:173], v[194:197], v[100:103]
	v_mfma_f32_16x16x32_bf16 v[96:99], v[178:181], v[194:197], v[96:99]
	v_mfma_f32_16x16x32_bf16 v[84:87], v[170:173], v[202:205], v[84:87]
	v_mfma_f32_16x16x32_bf16 v[80:83], v[178:181], v[202:205], v[80:83]
	v_mfma_f32_16x16x32_bf16 v[68:71], v[170:173], v[212:215], v[68:71]
	v_mfma_f32_16x16x32_bf16 v[64:67], v[178:181], v[212:215], v[64:67]
	s_barrier
	s_add_i32 s51, s43, s36
	s_mov_b32 m0, s51
	ds_read_b128 v[182:185], v153 offset:16384
	ds_read_b128 v[186:189], v153 offset:17408
	ds_read_b128 v[190:193], v153 offset:18432
	ds_read_b128 v[194:197], v153 offset:19456
	ds_read_b128 v[198:201], v153 offset:20480
	ds_read_b128 v[202:205], v153 offset:21504
	ds_read_b128 v[208:211], v153 offset:22528
	ds_read_b128 v[212:215], v153 offset:23552
	global_load_lds_dwordx4 v130, s[26:27]
	s_add_i32 m0, s51, 0x2000
	s_add_u32 s52, s26, 0x20000
	s_mov_b64 s[98:99], s[26:27]
	s_addc_u32 s53, s27, 0
	s_add_i32 s51, s44, s36
	global_load_lds_dwordx4 v134, s[26:27]
	s_mov_b32 m0, s51
	s_mov_b64 s[100:101], s[28:29]
	global_load_lds_dwordx4 v130, s[52:53]
	s_add_i32 m0, s51, 0x2000
	s_nop 0
	global_load_lds_dwordx4 v134, s[52:53]
	s_mov_b32 m0, s23
	s_nop 0
	global_load_lds_dwordx4 v128, s[28:29]
	s_mov_b32 m0, s37
	s_nop 0
	global_load_lds_dwordx4 v132, s[28:29]
	s_waitcnt vmcnt(8)
	s_waitcnt lgkmcnt(0)
	s_barrier
	s_waitcnt lgkmcnt(0)
	v_mfma_f32_16x16x32_bf16 v[60:63], v[144:147], v[182:185], v[60:63]
	v_mfma_f32_16x16x32_bf16 v[56:59], v[158:161], v[182:185], v[56:59]
	v_mfma_f32_16x16x32_bf16 v[44:47], v[144:147], v[190:193], v[44:47]
	v_mfma_f32_16x16x32_bf16 v[40:43], v[158:161], v[190:193], v[40:43]
	v_mfma_f32_16x16x32_bf16 v[28:31], v[144:147], v[198:201], v[28:31]
	v_mfma_f32_16x16x32_bf16 v[24:27], v[158:161], v[198:201], v[24:27]
	v_mfma_f32_16x16x32_bf16 v[12:15], v[144:147], v[208:211], v[12:15]
	v_mfma_f32_16x16x32_bf16 v[8:11], v[158:161], v[208:211], v[8:11]
	v_mfma_f32_16x16x32_bf16 v[60:63], v[154:157], v[186:189], v[60:63]
	v_mfma_f32_16x16x32_bf16 v[56:59], v[162:165], v[186:189], v[56:59]
	v_mfma_f32_16x16x32_bf16 v[44:47], v[154:157], v[194:197], v[44:47]
	v_mfma_f32_16x16x32_bf16 v[40:43], v[162:165], v[194:197], v[40:43]
	v_mfma_f32_16x16x32_bf16 v[28:31], v[154:157], v[202:205], v[28:31]
	v_mfma_f32_16x16x32_bf16 v[24:27], v[162:165], v[202:205], v[24:27]
	v_mfma_f32_16x16x32_bf16 v[12:15], v[154:157], v[212:215], v[12:15]
	v_mfma_f32_16x16x32_bf16 v[8:11], v[162:165], v[212:215], v[8:11]
	v_mfma_f32_16x16x32_bf16 v[52:55], v[166:169], v[182:185], v[52:55]
	v_mfma_f32_16x16x32_bf16 v[48:51], v[174:177], v[182:185], v[48:51]
	v_mfma_f32_16x16x32_bf16 v[36:39], v[166:169], v[190:193], v[36:39]
	v_mfma_f32_16x16x32_bf16 v[32:35], v[174:177], v[190:193], v[32:35]
	v_mfma_f32_16x16x32_bf16 v[20:23], v[166:169], v[198:201], v[20:23]
	v_mfma_f32_16x16x32_bf16 v[16:19], v[174:177], v[198:201], v[16:19]
	v_mfma_f32_16x16x32_bf16 v[4:7], v[166:169], v[208:211], v[4:7]
	v_mfma_f32_16x16x32_bf16 v[0:3], v[174:177], v[208:211], v[0:3]
	v_mfma_f32_16x16x32_bf16 v[52:55], v[170:173], v[186:189], v[52:55]
	v_mfma_f32_16x16x32_bf16 v[48:51], v[178:181], v[186:189], v[48:51]
	v_mfma_f32_16x16x32_bf16 v[36:39], v[170:173], v[194:197], v[36:39]
	v_mfma_f32_16x16x32_bf16 v[32:35], v[178:181], v[194:197], v[32:35]
	v_mfma_f32_16x16x32_bf16 v[20:23], v[170:173], v[202:205], v[20:23]
	v_mfma_f32_16x16x32_bf16 v[16:19], v[178:181], v[202:205], v[16:19]
	v_mfma_f32_16x16x32_bf16 v[4:7], v[170:173], v[212:215], v[4:7]
	v_mfma_f32_16x16x32_bf16 v[0:3], v[178:181], v[212:215], v[0:3]
	s_barrier
	s_add_i32 s51, 0, 0x18000
	s_add_i32 s52, 0, 0x1c000
	v_add_u32_e32 v162, s51, v149
	v_add_u32_e32 v178, s52, v149
	ds_read_b128 v[144:147], v162
	ds_read_b128 v[154:157], v162 offset:1024
	ds_read_b128 v[158:161], v162 offset:2048
	ds_read_b128 v[162:165], v162 offset:3072
	ds_read_b128 v[166:169], v178
	ds_read_b128 v[170:173], v178 offset:1024
	ds_read_b128 v[174:177], v178 offset:2048
	ds_read_b128 v[178:181], v178 offset:3072
	s_add_u32 s28, s28, 0x20000
	s_addc_u32 s29, s29, 0
	s_mov_b32 m0, s38
	ds_read_b128 v[182:185], v153 offset:32768
	ds_read_b128 v[186:189], v153 offset:33792
	ds_read_b128 v[190:193], v153 offset:34816
	ds_read_b128 v[194:197], v153 offset:35840
	ds_read_b128 v[198:201], v153 offset:36864
	ds_read_b128 v[202:205], v153 offset:37888
	ds_read_b128 v[208:211], v153 offset:38912
	ds_read_b128 v[212:215], v153 offset:39936
	global_load_lds_dwordx4 v128, s[28:29]
	s_mov_b32 m0, s39
	s_nop 0
	global_load_lds_dwordx4 v132, s[28:29]
	s_waitcnt vmcnt(8)
	s_waitcnt lgkmcnt(0)
	s_barrier
	s_waitcnt lgkmcnt(0)
	v_mfma_f32_16x16x32_bf16 v[124:127], v[144:147], v[182:185], v[124:127]
	v_mfma_f32_16x16x32_bf16 v[120:123], v[158:161], v[182:185], v[120:123]
	v_mfma_f32_16x16x32_bf16 v[108:111], v[144:147], v[190:193], v[108:111]
	v_mfma_f32_16x16x32_bf16 v[104:107], v[158:161], v[190:193], v[104:107]
	v_mfma_f32_16x16x32_bf16 v[92:95], v[144:147], v[198:201], v[92:95]
	v_mfma_f32_16x16x32_bf16 v[88:91], v[158:161], v[198:201], v[88:91]
	v_mfma_f32_16x16x32_bf16 v[76:79], v[144:147], v[208:211], v[76:79]
	v_mfma_f32_16x16x32_bf16 v[72:75], v[158:161], v[208:211], v[72:75]
	v_mfma_f32_16x16x32_bf16 v[124:127], v[154:157], v[186:189], v[124:127]
	v_mfma_f32_16x16x32_bf16 v[120:123], v[162:165], v[186:189], v[120:123]
	v_mfma_f32_16x16x32_bf16 v[108:111], v[154:157], v[194:197], v[108:111]
	v_mfma_f32_16x16x32_bf16 v[104:107], v[162:165], v[194:197], v[104:107]
	v_mfma_f32_16x16x32_bf16 v[92:95], v[154:157], v[202:205], v[92:95]
	v_mfma_f32_16x16x32_bf16 v[88:91], v[162:165], v[202:205], v[88:91]
	v_mfma_f32_16x16x32_bf16 v[76:79], v[154:157], v[212:215], v[76:79]
	v_mfma_f32_16x16x32_bf16 v[72:75], v[162:165], v[212:215], v[72:75]
	v_mfma_f32_16x16x32_bf16 v[116:119], v[166:169], v[182:185], v[116:119]
	v_mfma_f32_16x16x32_bf16 v[112:115], v[174:177], v[182:185], v[112:115]
	v_mfma_f32_16x16x32_bf16 v[100:103], v[166:169], v[190:193], v[100:103]
	v_mfma_f32_16x16x32_bf16 v[96:99], v[174:177], v[190:193], v[96:99]
	v_mfma_f32_16x16x32_bf16 v[84:87], v[166:169], v[198:201], v[84:87]
	v_mfma_f32_16x16x32_bf16 v[80:83], v[174:177], v[198:201], v[80:83]
	v_mfma_f32_16x16x32_bf16 v[68:71], v[166:169], v[208:211], v[68:71]
	v_mfma_f32_16x16x32_bf16 v[64:67], v[174:177], v[208:211], v[64:67]
	v_mfma_f32_16x16x32_bf16 v[116:119], v[170:173], v[186:189], v[116:119]
	v_mfma_f32_16x16x32_bf16 v[112:115], v[178:181], v[186:189], v[112:115]
	v_mfma_f32_16x16x32_bf16 v[100:103], v[170:173], v[194:197], v[100:103]
	v_mfma_f32_16x16x32_bf16 v[96:99], v[178:181], v[194:197], v[96:99]
	v_mfma_f32_16x16x32_bf16 v[84:87], v[170:173], v[202:205], v[84:87]
	v_mfma_f32_16x16x32_bf16 v[80:83], v[178:181], v[202:205], v[80:83]
	v_mfma_f32_16x16x32_bf16 v[68:71], v[170:173], v[212:215], v[68:71]
	v_mfma_f32_16x16x32_bf16 v[64:67], v[178:181], v[212:215], v[64:67]
	s_barrier
	s_add_i32 s28, s51, s36
	s_mov_b32 m0, s28
	ds_read_b128 v[182:185], v153 offset:49152
	ds_read_b128 v[186:189], v153 offset:50176
	ds_read_b128 v[190:193], v153 offset:51200
	ds_read_b128 v[194:197], v153 offset:52224
	ds_read_b128 v[198:201], v153 offset:53248
	ds_read_b128 v[202:205], v153 offset:54272
	ds_read_b128 v[208:211], v153 offset:55296
	ds_read_b128 v[212:215], v153 offset:56320
	global_load_lds_dwordx4 v217, s[26:27]
	s_add_i32 m0, s28, 0x2000
	s_add_u32 s26, s26, 0x20080
	s_addc_u32 s27, s27, 0
	s_add_i32 s28, s52, s36
	global_load_lds_dwordx4 v219, s[98:99]
	s_mov_b32 m0, s28
	s_nop 0
	global_load_lds_dwordx4 v130, s[26:27]
	s_add_i32 m0, s28, 0x2000
	s_nop 0
	global_load_lds_dwordx4 v134, s[26:27]
	s_mov_b32 m0, s41
	s_nop 0
	global_load_lds_dwordx4 v216, s[100:101]
	s_mov_b32 m0, s42
	s_nop 0
	global_load_lds_dwordx4 v218, s[100:101]
	s_waitcnt vmcnt(8)
	s_waitcnt lgkmcnt(0)
	s_barrier
	s_waitcnt lgkmcnt(0)
	v_mfma_f32_16x16x32_bf16 v[60:63], v[144:147], v[182:185], v[60:63]
	v_mfma_f32_16x16x32_bf16 v[56:59], v[158:161], v[182:185], v[56:59]
	v_mfma_f32_16x16x32_bf16 v[44:47], v[144:147], v[190:193], v[44:47]
	v_mfma_f32_16x16x32_bf16 v[40:43], v[158:161], v[190:193], v[40:43]
	v_mfma_f32_16x16x32_bf16 v[28:31], v[144:147], v[198:201], v[28:31]
	v_mfma_f32_16x16x32_bf16 v[24:27], v[158:161], v[198:201], v[24:27]
	v_mfma_f32_16x16x32_bf16 v[12:15], v[144:147], v[208:211], v[12:15]
	v_mfma_f32_16x16x32_bf16 v[8:11], v[158:161], v[208:211], v[8:11]
	v_mfma_f32_16x16x32_bf16 v[60:63], v[154:157], v[186:189], v[60:63]
	v_mfma_f32_16x16x32_bf16 v[56:59], v[162:165], v[186:189], v[56:59]
	v_mfma_f32_16x16x32_bf16 v[44:47], v[154:157], v[194:197], v[44:47]
	v_mfma_f32_16x16x32_bf16 v[40:43], v[162:165], v[194:197], v[40:43]
	v_mfma_f32_16x16x32_bf16 v[28:31], v[154:157], v[202:205], v[28:31]
	v_mfma_f32_16x16x32_bf16 v[24:27], v[162:165], v[202:205], v[24:27]
	v_mfma_f32_16x16x32_bf16 v[12:15], v[154:157], v[212:215], v[12:15]
	v_mfma_f32_16x16x32_bf16 v[8:11], v[162:165], v[212:215], v[8:11]
	v_mfma_f32_16x16x32_bf16 v[52:55], v[166:169], v[182:185], v[52:55]
	v_mfma_f32_16x16x32_bf16 v[48:51], v[174:177], v[182:185], v[48:51]
	v_mfma_f32_16x16x32_bf16 v[36:39], v[166:169], v[190:193], v[36:39]
	v_mfma_f32_16x16x32_bf16 v[32:35], v[174:177], v[190:193], v[32:35]
	v_mfma_f32_16x16x32_bf16 v[20:23], v[166:169], v[198:201], v[20:23]
	v_mfma_f32_16x16x32_bf16 v[16:19], v[174:177], v[198:201], v[16:19]
	v_mfma_f32_16x16x32_bf16 v[4:7], v[166:169], v[208:211], v[4:7]
	v_mfma_f32_16x16x32_bf16 v[0:3], v[174:177], v[208:211], v[0:3]
	v_mfma_f32_16x16x32_bf16 v[52:55], v[170:173], v[186:189], v[52:55]
	v_mfma_f32_16x16x32_bf16 v[48:51], v[178:181], v[186:189], v[48:51]
	v_mfma_f32_16x16x32_bf16 v[36:39], v[170:173], v[194:197], v[36:39]
	v_mfma_f32_16x16x32_bf16 v[32:35], v[178:181], v[194:197], v[32:35]
	v_mfma_f32_16x16x32_bf16 v[20:23], v[170:173], v[202:205], v[20:23]
	v_mfma_f32_16x16x32_bf16 v[16:19], v[178:181], v[202:205], v[16:19]
	v_mfma_f32_16x16x32_bf16 v[4:7], v[170:173], v[212:215], v[4:7]
	v_mfma_f32_16x16x32_bf16 v[0:3], v[178:181], v[212:215], v[0:3]
	s_barrier
	s_add_i32 s50, s50, 2
	s_add_u32 s48, s48, 0x100
	s_addc_u32 s49, s49, 0
	s_add_u32 s24, s24, 0x100
	s_addc_u32 s25, s25, 0
	s_cmp_gt_u32 s50, 5
	s_cbranch_scc0 .LBB0_1193
	s_setprio 0
	s_and_b64 vcc, exec, s[12:13]
	s_cbranch_vccz .LBB0_1196
	s_barrier

.LBB0_1364:
	s_ashr_i32 s19, s18, 31
	s_lshl_b64 s[20:21], s[18:19], 19
	s_add_u32 s20, s34, s20
	s_addc_u32 s21, s35, s21
	s_and_b64 s[22:23], s[4:5], exec
	s_cselect_b32 s19, s21, s27
	s_cselect_b32 s49, s20, s26
	s_ashr_i32 s17, s16, 31
	s_lshl_b64 s[22:23], s[16:17], 19
	s_add_u32 s22, s36, s22
	s_addc_u32 s23, s37, s23
	s_and_b64 s[28:29], s[4:5], exec
	s_cselect_b32 s17, s23, s25
	s_cselect_b32 s50, s22, s24
	s_add_u32 s51, s24, 0x100
	s_addc_u32 s52, s25, 0
	s_add_u32 s24, s26, 0x40080
	v_mov_b32_e32 v0, 0
	s_addc_u32 s25, s27, 0
	s_mov_b32 s53, -2
	v_mov_b32_e32 v1, v0
	v_mov_b32_e32 v2, v0
	v_mov_b32_e32 v3, v0
	v_mov_b32_e32 v4, v0
	v_mov_b32_e32 v5, v0
	v_mov_b32_e32 v6, v0
	v_mov_b32_e32 v7, v0
	v_mov_b32_e32 v16, v0
	v_mov_b32_e32 v17, v0
	v_mov_b32_e32 v18, v0
	v_mov_b32_e32 v19, v0
	v_mov_b32_e32 v20, v0
	v_mov_b32_e32 v21, v0
	v_mov_b32_e32 v22, v0
	v_mov_b32_e32 v23, v0
	v_mov_b32_e32 v32, v0
	v_mov_b32_e32 v33, v0
	v_mov_b32_e32 v34, v0
	v_mov_b32_e32 v35, v0
	v_mov_b32_e32 v36, v0
	v_mov_b32_e32 v37, v0
	v_mov_b32_e32 v38, v0
	v_mov_b32_e32 v39, v0
	v_mov_b32_e32 v48, v0
	v_mov_b32_e32 v49, v0
	v_mov_b32_e32 v50, v0
	v_mov_b32_e32 v51, v0
	v_mov_b32_e32 v52, v0
	v_mov_b32_e32 v53, v0
	v_mov_b32_e32 v54, v0
	v_mov_b32_e32 v55, v0
	v_mov_b32_e32 v8, v0
	v_mov_b32_e32 v9, v0
	v_mov_b32_e32 v10, v0
	v_mov_b32_e32 v11, v0
	v_mov_b32_e32 v12, v0
	v_mov_b32_e32 v13, v0
	v_mov_b32_e32 v14, v0
	v_mov_b32_e32 v15, v0
	v_mov_b32_e32 v24, v0
	v_mov_b32_e32 v25, v0
	v_mov_b32_e32 v26, v0
	v_mov_b32_e32 v27, v0
	v_mov_b32_e32 v28, v0
	v_mov_b32_e32 v29, v0
	v_mov_b32_e32 v30, v0
	v_mov_b32_e32 v31, v0
	v_mov_b32_e32 v40, v0
	v_mov_b32_e32 v41, v0
	v_mov_b32_e32 v42, v0
	v_mov_b32_e32 v43, v0
	v_mov_b32_e32 v44, v0
	v_mov_b32_e32 v45, v0
	v_mov_b32_e32 v46, v0
	v_mov_b32_e32 v47, v0
	v_mov_b32_e32 v56, v0
	v_mov_b32_e32 v57, v0
	v_mov_b32_e32 v58, v0
	v_mov_b32_e32 v59, v0
	v_mov_b32_e32 v60, v0
	v_mov_b32_e32 v61, v0
	v_mov_b32_e32 v62, v0
	v_mov_b32_e32 v63, v0
	v_mov_b32_e32 v64, v0
	v_mov_b32_e32 v65, v0
	v_mov_b32_e32 v66, v0
	v_mov_b32_e32 v67, v0
	v_mov_b32_e32 v68, v0
	v_mov_b32_e32 v69, v0
	v_mov_b32_e32 v70, v0
	v_mov_b32_e32 v71, v0
	v_mov_b32_e32 v80, v0
	v_mov_b32_e32 v81, v0
	v_mov_b32_e32 v82, v0
	v_mov_b32_e32 v83, v0
	v_mov_b32_e32 v84, v0
	v_mov_b32_e32 v85, v0
	v_mov_b32_e32 v86, v0
	v_mov_b32_e32 v87, v0
	v_mov_b32_e32 v96, v0
	v_mov_b32_e32 v97, v0
	v_mov_b32_e32 v98, v0
	v_mov_b32_e32 v99, v0
	v_mov_b32_e32 v100, v0
	v_mov_b32_e32 v101, v0
	v_mov_b32_e32 v102, v0
	v_mov_b32_e32 v103, v0
	v_mov_b32_e32 v112, v0
	v_mov_b32_e32 v113, v0
	v_mov_b32_e32 v114, v0
	v_mov_b32_e32 v115, v0
	v_mov_b32_e32 v116, v0
	v_mov_b32_e32 v117, v0
	v_mov_b32_e32 v118, v0
	v_mov_b32_e32 v119, v0
	v_mov_b32_e32 v72, v0
	v_mov_b32_e32 v73, v0
	v_mov_b32_e32 v74, v0
	v_mov_b32_e32 v75, v0
	v_mov_b32_e32 v76, v0
	v_mov_b32_e32 v77, v0
	v_mov_b32_e32 v78, v0
	v_mov_b32_e32 v79, v0
	v_mov_b32_e32 v88, v0
	v_mov_b32_e32 v89, v0
	v_mov_b32_e32 v90, v0
	v_mov_b32_e32 v91, v0
	v_mov_b32_e32 v92, v0
	v_mov_b32_e32 v93, v0
	v_mov_b32_e32 v94, v0
	v_mov_b32_e32 v95, v0
	v_mov_b32_e32 v104, v0
	v_mov_b32_e32 v105, v0
	v_mov_b32_e32 v106, v0
	v_mov_b32_e32 v107, v0
	v_mov_b32_e32 v108, v0
	v_mov_b32_e32 v109, v0
	v_mov_b32_e32 v110, v0
	v_mov_b32_e32 v111, v0
	v_mov_b32_e32 v120, v0
	v_mov_b32_e32 v121, v0
	v_mov_b32_e32 v122, v0
	v_mov_b32_e32 v123, v0
	v_mov_b32_e32 v124, v0
	v_mov_b32_e32 v125, v0
	v_mov_b32_e32 v126, v0
	v_mov_b32_e32 v127, v0
	v_add_u32_e32 v204, 0x80, v128
	v_add_u32_e32 v205, 0x80, v130
	v_add_u32_e32 v220, 0x80, v132
	v_add_u32_e32 v221, 0x80, v134
	v_readfirstlane_b32 s101, v206
	s_nop 3
	s_lshr_b32 s101, s101, 8
	s_cmp_eq_u32 s101, 1
	s_cbranch_scc0 .Lprio_skip_13
	s_setprio 1

.LBB0_1365:
	ds_read_b128 v[144:147], v151
	ds_read_b128 v[156:159], v151 offset:1024
	ds_read_b128 v[160:163], v151 offset:2048
	ds_read_b128 v[164:167], v151 offset:3072
	ds_read_b128 v[168:171], v152
	ds_read_b128 v[172:175], v152 offset:1024
	ds_read_b128 v[176:179], v152 offset:2048
	ds_read_b128 v[180:183], v152 offset:3072
	s_add_u32 s26, s24, 0xfffc0080
	s_addc_u32 s27, s25, -1
	s_cmp_eq_u32 s53, 12
	s_cselect_b32 s29, s19, s27
	s_cselect_b32 s28, s49, s26
	s_cselect_b32 s27, s17, s52
	s_cselect_b32 s26, s50, s51
	s_add_i32 m0, s39, 0xc000
	ds_read_b128 v[184:187], v153
	ds_read_b128 v[188:191], v153 offset:1024
	ds_read_b128 v[192:195], v153 offset:2048
	ds_read_b128 v[196:199], v153 offset:3072
	ds_read_b128 v[200:203], v153 offset:4096
	ds_read_b128 v[208:211], v153 offset:5120
	ds_read_b128 v[212:215], v153 offset:6144
	ds_read_b128 v[216:219], v153 offset:7168
	global_load_lds_dwordx4 v138, s[24:25]
	s_add_i32 m0, s39, 0xe000
	s_nop 0
	global_load_lds_dwordx4 v136, s[24:25]
	s_waitcnt vmcnt(8)
	s_waitcnt lgkmcnt(0)
	s_barrier
	s_waitcnt lgkmcnt(0)
	v_mfma_f32_16x16x32_bf16 v[124:127], v[144:147], v[184:187], v[124:127]
	v_mfma_f32_16x16x32_bf16 v[120:123], v[160:163], v[184:187], v[120:123]
	v_mfma_f32_16x16x32_bf16 v[108:111], v[144:147], v[192:195], v[108:111]
	v_mfma_f32_16x16x32_bf16 v[104:107], v[160:163], v[192:195], v[104:107]
	v_mfma_f32_16x16x32_bf16 v[92:95], v[144:147], v[200:203], v[92:95]
	v_mfma_f32_16x16x32_bf16 v[88:91], v[160:163], v[200:203], v[88:91]
	v_mfma_f32_16x16x32_bf16 v[76:79], v[144:147], v[212:215], v[76:79]
	v_mfma_f32_16x16x32_bf16 v[72:75], v[160:163], v[212:215], v[72:75]
	v_mfma_f32_16x16x32_bf16 v[124:127], v[156:159], v[188:191], v[124:127]
	v_mfma_f32_16x16x32_bf16 v[120:123], v[164:167], v[188:191], v[120:123]
	v_mfma_f32_16x16x32_bf16 v[108:111], v[156:159], v[196:199], v[108:111]
	v_mfma_f32_16x16x32_bf16 v[104:107], v[164:167], v[196:199], v[104:107]
	v_mfma_f32_16x16x32_bf16 v[92:95], v[156:159], v[208:211], v[92:95]
	v_mfma_f32_16x16x32_bf16 v[88:91], v[164:167], v[208:211], v[88:91]
	v_mfma_f32_16x16x32_bf16 v[76:79], v[156:159], v[216:219], v[76:79]
	v_mfma_f32_16x16x32_bf16 v[72:75], v[164:167], v[216:219], v[72:75]
	v_mfma_f32_16x16x32_bf16 v[116:119], v[168:171], v[184:187], v[116:119]
	v_mfma_f32_16x16x32_bf16 v[112:115], v[176:179], v[184:187], v[112:115]
	v_mfma_f32_16x16x32_bf16 v[100:103], v[168:171], v[192:195], v[100:103]
	v_mfma_f32_16x16x32_bf16 v[96:99], v[176:179], v[192:195], v[96:99]
	v_mfma_f32_16x16x32_bf16 v[84:87], v[168:171], v[200:203], v[84:87]
	v_mfma_f32_16x16x32_bf16 v[80:83], v[176:179], v[200:203], v[80:83]
	v_mfma_f32_16x16x32_bf16 v[68:71], v[168:171], v[212:215], v[68:71]
	v_mfma_f32_16x16x32_bf16 v[64:67], v[176:179], v[212:215], v[64:67]
	v_mfma_f32_16x16x32_bf16 v[116:119], v[172:175], v[188:191], v[116:119]
	v_mfma_f32_16x16x32_bf16 v[112:115], v[180:183], v[188:191], v[112:115]
	v_mfma_f32_16x16x32_bf16 v[100:103], v[172:175], v[196:199], v[100:103]
	v_mfma_f32_16x16x32_bf16 v[96:99], v[180:183], v[196:199], v[96:99]
	v_mfma_f32_16x16x32_bf16 v[84:87], v[172:175], v[208:211], v[84:87]
	v_mfma_f32_16x16x32_bf16 v[80:83], v[180:183], v[208:211], v[80:83]
	v_mfma_f32_16x16x32_bf16 v[68:71], v[172:175], v[216:219], v[68:71]
	v_mfma_f32_16x16x32_bf16 v[64:67], v[180:183], v[216:219], v[64:67]
	s_barrier
	s_add_i32 s54, s46, s38
	s_mov_b32 m0, s54
	ds_read_b128 v[184:187], v153 offset:16384
	ds_read_b128 v[188:191], v153 offset:17408
	ds_read_b128 v[192:195], v153 offset:18432
	ds_read_b128 v[196:199], v153 offset:19456
	ds_read_b128 v[200:203], v153 offset:20480
	ds_read_b128 v[208:211], v153 offset:21504
	ds_read_b128 v[212:215], v153 offset:22528
	ds_read_b128 v[216:219], v153 offset:23552
	global_load_lds_dwordx4 v130, s[26:27]
	s_add_i32 m0, s54, 0x2000
	s_add_u32 s54, s26, 0x40000
	s_mov_b64 s[98:99], s[26:27]
	s_addc_u32 s55, s27, 0
	s_add_i32 s56, s47, s38
	global_load_lds_dwordx4 v134, s[26:27]
	s_mov_b32 m0, s56
	s_mov_b64 s[100:101], s[28:29]
	global_load_lds_dwordx4 v130, s[54:55]
	s_add_i32 m0, s56, 0x2000
	s_nop 0
	global_load_lds_dwordx4 v134, s[54:55]
	s_mov_b32 m0, s39
	s_nop 0
	global_load_lds_dwordx4 v128, s[28:29]
	s_mov_b32 m0, s40
	s_nop 0
	global_load_lds_dwordx4 v132, s[28:29]
	s_waitcnt vmcnt(8)
	s_waitcnt lgkmcnt(0)
	s_barrier
	s_waitcnt lgkmcnt(0)
	v_mfma_f32_16x16x32_bf16 v[60:63], v[144:147], v[184:187], v[60:63]
	v_mfma_f32_16x16x32_bf16 v[56:59], v[160:163], v[184:187], v[56:59]
	v_mfma_f32_16x16x32_bf16 v[44:47], v[144:147], v[192:195], v[44:47]
	v_mfma_f32_16x16x32_bf16 v[40:43], v[160:163], v[192:195], v[40:43]
	v_mfma_f32_16x16x32_bf16 v[28:31], v[144:147], v[200:203], v[28:31]
	v_mfma_f32_16x16x32_bf16 v[24:27], v[160:163], v[200:203], v[24:27]
	v_mfma_f32_16x16x32_bf16 v[12:15], v[144:147], v[212:215], v[12:15]
	v_mfma_f32_16x16x32_bf16 v[8:11], v[160:163], v[212:215], v[8:11]
	v_mfma_f32_16x16x32_bf16 v[60:63], v[156:159], v[188:191], v[60:63]
	v_mfma_f32_16x16x32_bf16 v[56:59], v[164:167], v[188:191], v[56:59]
	v_mfma_f32_16x16x32_bf16 v[44:47], v[156:159], v[196:199], v[44:47]
	v_mfma_f32_16x16x32_bf16 v[40:43], v[164:167], v[196:199], v[40:43]
	v_mfma_f32_16x16x32_bf16 v[28:31], v[156:159], v[208:211], v[28:31]
	v_mfma_f32_16x16x32_bf16 v[24:27], v[164:167], v[208:211], v[24:27]
	v_mfma_f32_16x16x32_bf16 v[12:15], v[156:159], v[216:219], v[12:15]
	v_mfma_f32_16x16x32_bf16 v[8:11], v[164:167], v[216:219], v[8:11]
	v_mfma_f32_16x16x32_bf16 v[52:55], v[168:171], v[184:187], v[52:55]
	v_mfma_f32_16x16x32_bf16 v[48:51], v[176:179], v[184:187], v[48:51]
	v_mfma_f32_16x16x32_bf16 v[36:39], v[168:171], v[192:195], v[36:39]
	v_mfma_f32_16x16x32_bf16 v[32:35], v[176:179], v[192:195], v[32:35]
	v_mfma_f32_16x16x32_bf16 v[20:23], v[168:171], v[200:203], v[20:23]
	v_mfma_f32_16x16x32_bf16 v[16:19], v[176:179], v[200:203], v[16:19]
	v_mfma_f32_16x16x32_bf16 v[4:7], v[168:171], v[212:215], v[4:7]
	v_mfma_f32_16x16x32_bf16 v[0:3], v[176:179], v[212:215], v[0:3]
	v_mfma_f32_16x16x32_bf16 v[52:55], v[172:175], v[188:191], v[52:55]
	v_mfma_f32_16x16x32_bf16 v[48:51], v[180:183], v[188:191], v[48:51]
	v_mfma_f32_16x16x32_bf16 v[36:39], v[172:175], v[196:199], v[36:39]
	v_mfma_f32_16x16x32_bf16 v[32:35], v[180:183], v[196:199], v[32:35]
	v_mfma_f32_16x16x32_bf16 v[20:23], v[172:175], v[208:211], v[20:23]
	v_mfma_f32_16x16x32_bf16 v[16:19], v[180:183], v[208:211], v[16:19]
	v_mfma_f32_16x16x32_bf16 v[4:7], v[172:175], v[216:219], v[4:7]
	v_mfma_f32_16x16x32_bf16 v[0:3], v[180:183], v[216:219], v[0:3]
	s_barrier
	s_add_i32 s54, 0, 0x18000
	v_add_u32_e32 v155, s54, v149
	s_add_i32 s55, 0, 0x1c000
	ds_read_b128 v[144:147], v155
	ds_read_b128 v[156:159], v155 offset:1024
	ds_read_b128 v[160:163], v155 offset:2048
	ds_read_b128 v[164:167], v155 offset:3072
	v_add_u32_e32 v155, s55, v149
	ds_read_b128 v[168:171], v155
	ds_read_b128 v[172:175], v155 offset:1024
	ds_read_b128 v[176:179], v155 offset:2048
	ds_read_b128 v[180:183], v155 offset:3072
	s_add_u32 s28, s28, 0x40000
	s_addc_u32 s29, s29, 0
	s_mov_b32 m0, s41
	ds_read_b128 v[184:187], v153 offset:32768
	ds_read_b128 v[188:191], v153 offset:33792
	ds_read_b128 v[192:195], v153 offset:34816
	ds_read_b128 v[196:199], v153 offset:35840
	ds_read_b128 v[200:203], v153 offset:36864
	ds_read_b128 v[208:211], v153 offset:37888
	ds_read_b128 v[212:215], v153 offset:38912
	ds_read_b128 v[216:219], v153 offset:39936
	global_load_lds_dwordx4 v128, s[28:29]
	s_mov_b32 m0, s42
	s_nop 0
	global_load_lds_dwordx4 v132, s[28:29]
	s_waitcnt vmcnt(8)
	s_waitcnt lgkmcnt(0)
	s_barrier
	s_waitcnt lgkmcnt(0)
	v_mfma_f32_16x16x32_bf16 v[124:127], v[144:147], v[184:187], v[124:127]
	v_mfma_f32_16x16x32_bf16 v[120:123], v[160:163], v[184:187], v[120:123]
	v_mfma_f32_16x16x32_bf16 v[108:111], v[144:147], v[192:195], v[108:111]
	v_mfma_f32_16x16x32_bf16 v[104:107], v[160:163], v[192:195], v[104:107]
	v_mfma_f32_16x16x32_bf16 v[92:95], v[144:147], v[200:203], v[92:95]
	v_mfma_f32_16x16x32_bf16 v[88:91], v[160:163], v[200:203], v[88:91]
	v_mfma_f32_16x16x32_bf16 v[76:79], v[144:147], v[212:215], v[76:79]
	v_mfma_f32_16x16x32_bf16 v[72:75], v[160:163], v[212:215], v[72:75]
	v_mfma_f32_16x16x32_bf16 v[124:127], v[156:159], v[188:191], v[124:127]
	v_mfma_f32_16x16x32_bf16 v[120:123], v[164:167], v[188:191], v[120:123]
	v_mfma_f32_16x16x32_bf16 v[108:111], v[156:159], v[196:199], v[108:111]
	v_mfma_f32_16x16x32_bf16 v[104:107], v[164:167], v[196:199], v[104:107]
	v_mfma_f32_16x16x32_bf16 v[92:95], v[156:159], v[208:211], v[92:95]
	v_mfma_f32_16x16x32_bf16 v[88:91], v[164:167], v[208:211], v[88:91]
	v_mfma_f32_16x16x32_bf16 v[76:79], v[156:159], v[216:219], v[76:79]
	v_mfma_f32_16x16x32_bf16 v[72:75], v[164:167], v[216:219], v[72:75]
	v_mfma_f32_16x16x32_bf16 v[116:119], v[168:171], v[184:187], v[116:119]
	v_mfma_f32_16x16x32_bf16 v[112:115], v[176:179], v[184:187], v[112:115]
	v_mfma_f32_16x16x32_bf16 v[100:103], v[168:171], v[192:195], v[100:103]
	v_mfma_f32_16x16x32_bf16 v[96:99], v[176:179], v[192:195], v[96:99]
	v_mfma_f32_16x16x32_bf16 v[84:87], v[168:171], v[200:203], v[84:87]
	v_mfma_f32_16x16x32_bf16 v[80:83], v[176:179], v[200:203], v[80:83]
	v_mfma_f32_16x16x32_bf16 v[68:71], v[168:171], v[212:215], v[68:71]
	v_mfma_f32_16x16x32_bf16 v[64:67], v[176:179], v[212:215], v[64:67]
	v_mfma_f32_16x16x32_bf16 v[116:119], v[172:175], v[188:191], v[116:119]
	v_mfma_f32_16x16x32_bf16 v[112:115], v[180:183], v[188:191], v[112:115]
	v_mfma_f32_16x16x32_bf16 v[100:103], v[172:175], v[196:199], v[100:103]
	v_mfma_f32_16x16x32_bf16 v[96:99], v[180:183], v[196:199], v[96:99]
	v_mfma_f32_16x16x32_bf16 v[84:87], v[172:175], v[208:211], v[84:87]
	v_mfma_f32_16x16x32_bf16 v[80:83], v[180:183], v[208:211], v[80:83]
	v_mfma_f32_16x16x32_bf16 v[68:71], v[172:175], v[216:219], v[68:71]
	v_mfma_f32_16x16x32_bf16 v[64:67], v[180:183], v[216:219], v[64:67]
	s_barrier
	s_add_i32 s28, s54, s38
	s_mov_b32 m0, s28
	ds_read_b128 v[184:187], v153 offset:49152
	ds_read_b128 v[188:191], v153 offset:50176
	ds_read_b128 v[192:195], v153 offset:51200
	ds_read_b128 v[196:199], v153 offset:52224
	ds_read_b128 v[200:203], v153 offset:53248
	ds_read_b128 v[208:211], v153 offset:54272
	ds_read_b128 v[212:215], v153 offset:55296
	ds_read_b128 v[216:219], v153 offset:56320
	global_load_lds_dwordx4 v205, s[26:27]
	s_add_i32 m0, s28, 0x2000
	s_add_u32 s26, s26, 0x40080
	s_addc_u32 s27, s27, 0
	s_add_i32 s28, s55, s38
	global_load_lds_dwordx4 v221, s[98:99]
	s_mov_b32 m0, s28
	s_nop 0
	global_load_lds_dwordx4 v130, s[26:27]
	s_add_i32 m0, s28, 0x2000
	s_nop 0
	global_load_lds_dwordx4 v134, s[26:27]
	s_mov_b32 m0, s44
	s_nop 0
	global_load_lds_dwordx4 v204, s[100:101]
	s_mov_b32 m0, s45
	s_nop 0
	global_load_lds_dwordx4 v220, s[100:101]
	s_waitcnt vmcnt(8)
	s_waitcnt lgkmcnt(0)
	s_barrier
	s_waitcnt lgkmcnt(0)
	v_mfma_f32_16x16x32_bf16 v[60:63], v[144:147], v[184:187], v[60:63]
	v_mfma_f32_16x16x32_bf16 v[56:59], v[160:163], v[184:187], v[56:59]
	v_mfma_f32_16x16x32_bf16 v[44:47], v[144:147], v[192:195], v[44:47]
	v_mfma_f32_16x16x32_bf16 v[40:43], v[160:163], v[192:195], v[40:43]
	v_mfma_f32_16x16x32_bf16 v[28:31], v[144:147], v[200:203], v[28:31]
	v_mfma_f32_16x16x32_bf16 v[24:27], v[160:163], v[200:203], v[24:27]
	v_mfma_f32_16x16x32_bf16 v[12:15], v[144:147], v[212:215], v[12:15]
	v_mfma_f32_16x16x32_bf16 v[8:11], v[160:163], v[212:215], v[8:11]
	v_mfma_f32_16x16x32_bf16 v[60:63], v[156:159], v[188:191], v[60:63]
	v_mfma_f32_16x16x32_bf16 v[56:59], v[164:167], v[188:191], v[56:59]
	v_mfma_f32_16x16x32_bf16 v[44:47], v[156:159], v[196:199], v[44:47]
	v_mfma_f32_16x16x32_bf16 v[40:43], v[164:167], v[196:199], v[40:43]
	v_mfma_f32_16x16x32_bf16 v[28:31], v[156:159], v[208:211], v[28:31]
	v_mfma_f32_16x16x32_bf16 v[24:27], v[164:167], v[208:211], v[24:27]
	v_mfma_f32_16x16x32_bf16 v[12:15], v[156:159], v[216:219], v[12:15]
	v_mfma_f32_16x16x32_bf16 v[8:11], v[164:167], v[216:219], v[8:11]
	v_mfma_f32_16x16x32_bf16 v[52:55], v[168:171], v[184:187], v[52:55]
	v_mfma_f32_16x16x32_bf16 v[48:51], v[176:179], v[184:187], v[48:51]
	v_mfma_f32_16x16x32_bf16 v[36:39], v[168:171], v[192:195], v[36:39]
	v_mfma_f32_16x16x32_bf16 v[32:35], v[176:179], v[192:195], v[32:35]
	v_mfma_f32_16x16x32_bf16 v[20:23], v[168:171], v[200:203], v[20:23]
	v_mfma_f32_16x16x32_bf16 v[16:19], v[176:179], v[200:203], v[16:19]
	v_mfma_f32_16x16x32_bf16 v[4:7], v[168:171], v[212:215], v[4:7]
	v_mfma_f32_16x16x32_bf16 v[0:3], v[176:179], v[212:215], v[0:3]
	v_mfma_f32_16x16x32_bf16 v[52:55], v[172:175], v[188:191], v[52:55]
	v_mfma_f32_16x16x32_bf16 v[48:51], v[180:183], v[188:191], v[48:51]
	v_mfma_f32_16x16x32_bf16 v[36:39], v[172:175], v[196:199], v[36:39]
	v_mfma_f32_16x16x32_bf16 v[32:35], v[180:183], v[196:199], v[32:35]
	v_mfma_f32_16x16x32_bf16 v[20:23], v[172:175], v[208:211], v[20:23]
	v_mfma_f32_16x16x32_bf16 v[16:19], v[180:183], v[208:211], v[16:19]
	v_mfma_f32_16x16x32_bf16 v[4:7], v[172:175], v[216:219], v[4:7]
	v_mfma_f32_16x16x32_bf16 v[0:3], v[180:183], v[216:219], v[0:3]
	s_barrier
	s_add_i32 s53, s53, 2
	s_add_u32 s51, s51, 0x100
	s_addc_u32 s52, s52, 0
	s_add_u32 s24, s24, 0x100
	s_addc_u32 s25, s25, 0
	s_cmp_gt_u32 s53, 13
	s_cbranch_scc0 .LBB0_1365
	s_setprio 0
	s_and_b64 vcc, exec, s[14:15]
	s_cbranch_vccz .LBB0_1368
	s_barrier

.LBB0_1560:
	s_ashr_i32 s29, s28, 31
	s_lshl_b64 s[30:31], s[28:29], 19
	s_add_u32 s30, s12, s30
	s_addc_u32 s31, s13, s31
	s_and_b64 s[34:35], s[6:7], exec
	s_cselect_b32 s3, s31, s39
	s_cselect_b32 s29, s30, s38
	s_ashr_i32 s27, s26, 31
	s_lshl_b64 s[34:35], s[26:27], 19
	s_add_u32 s34, s43, s34
	s_addc_u32 s35, s44, s35
	s_and_b64 s[40:41], s[6:7], exec
	s_cselect_b32 s27, s35, s37
	s_cselect_b32 s58, s34, s36
	s_add_u32 s59, s36, 0x100
	s_addc_u32 s60, s37, 0
	s_add_u32 s36, s38, 0x40080
	v_mov_b32_e32 v0, 0
	s_addc_u32 s37, s39, 0
	s_mov_b32 s61, -2
	v_mov_b32_e32 v1, v0
	v_mov_b32_e32 v2, v0
	v_mov_b32_e32 v3, v0
	v_mov_b32_e32 v4, v0
	v_mov_b32_e32 v5, v0
	v_mov_b32_e32 v6, v0
	v_mov_b32_e32 v7, v0
	v_mov_b32_e32 v16, v0
	v_mov_b32_e32 v17, v0
	v_mov_b32_e32 v18, v0
	v_mov_b32_e32 v19, v0
	v_mov_b32_e32 v20, v0
	v_mov_b32_e32 v21, v0
	v_mov_b32_e32 v22, v0
	v_mov_b32_e32 v23, v0
	v_mov_b32_e32 v32, v0
	v_mov_b32_e32 v33, v0
	v_mov_b32_e32 v34, v0
	v_mov_b32_e32 v35, v0
	v_mov_b32_e32 v36, v0
	v_mov_b32_e32 v37, v0
	v_mov_b32_e32 v38, v0
	v_mov_b32_e32 v39, v0
	v_mov_b32_e32 v48, v0
	v_mov_b32_e32 v49, v0
	v_mov_b32_e32 v50, v0
	v_mov_b32_e32 v51, v0
	v_mov_b32_e32 v52, v0
	v_mov_b32_e32 v53, v0
	v_mov_b32_e32 v54, v0
	v_mov_b32_e32 v55, v0
	v_mov_b32_e32 v8, v0
	v_mov_b32_e32 v9, v0
	v_mov_b32_e32 v10, v0
	v_mov_b32_e32 v11, v0
	v_mov_b32_e32 v12, v0
	v_mov_b32_e32 v13, v0
	v_mov_b32_e32 v14, v0
	v_mov_b32_e32 v15, v0
	v_mov_b32_e32 v24, v0
	v_mov_b32_e32 v25, v0
	v_mov_b32_e32 v26, v0
	v_mov_b32_e32 v27, v0
	v_mov_b32_e32 v28, v0
	v_mov_b32_e32 v29, v0
	v_mov_b32_e32 v30, v0
	v_mov_b32_e32 v31, v0
	v_mov_b32_e32 v40, v0
	v_mov_b32_e32 v41, v0
	v_mov_b32_e32 v42, v0
	v_mov_b32_e32 v43, v0
	v_mov_b32_e32 v44, v0
	v_mov_b32_e32 v45, v0
	v_mov_b32_e32 v46, v0
	v_mov_b32_e32 v47, v0
	v_mov_b32_e32 v56, v0
	v_mov_b32_e32 v57, v0
	v_mov_b32_e32 v58, v0
	v_mov_b32_e32 v59, v0
	v_mov_b32_e32 v60, v0
	v_mov_b32_e32 v61, v0
	v_mov_b32_e32 v62, v0
	v_mov_b32_e32 v63, v0
	v_mov_b32_e32 v64, v0
	v_mov_b32_e32 v65, v0
	v_mov_b32_e32 v66, v0
	v_mov_b32_e32 v67, v0
	v_mov_b32_e32 v68, v0
	v_mov_b32_e32 v69, v0
	v_mov_b32_e32 v70, v0
	v_mov_b32_e32 v71, v0
	v_mov_b32_e32 v80, v0
	v_mov_b32_e32 v81, v0
	v_mov_b32_e32 v82, v0
	v_mov_b32_e32 v83, v0
	v_mov_b32_e32 v84, v0
	v_mov_b32_e32 v85, v0
	v_mov_b32_e32 v86, v0
	v_mov_b32_e32 v87, v0
	v_mov_b32_e32 v96, v0
	v_mov_b32_e32 v97, v0
	v_mov_b32_e32 v98, v0
	v_mov_b32_e32 v99, v0
	v_mov_b32_e32 v100, v0
	v_mov_b32_e32 v101, v0
	v_mov_b32_e32 v102, v0
	v_mov_b32_e32 v103, v0
	v_mov_b32_e32 v112, v0
	v_mov_b32_e32 v113, v0
	v_mov_b32_e32 v114, v0
	v_mov_b32_e32 v115, v0
	v_mov_b32_e32 v116, v0
	v_mov_b32_e32 v117, v0
	v_mov_b32_e32 v118, v0
	v_mov_b32_e32 v119, v0
	v_mov_b32_e32 v72, v0
	v_mov_b32_e32 v73, v0
	v_mov_b32_e32 v74, v0
	v_mov_b32_e32 v75, v0
	v_mov_b32_e32 v76, v0
	v_mov_b32_e32 v77, v0
	v_mov_b32_e32 v78, v0
	v_mov_b32_e32 v79, v0
	v_mov_b32_e32 v88, v0
	v_mov_b32_e32 v89, v0
	v_mov_b32_e32 v90, v0
	v_mov_b32_e32 v91, v0
	v_mov_b32_e32 v92, v0
	v_mov_b32_e32 v93, v0
	v_mov_b32_e32 v94, v0
	v_mov_b32_e32 v95, v0
	v_mov_b32_e32 v104, v0
	v_mov_b32_e32 v105, v0
	v_mov_b32_e32 v106, v0
	v_mov_b32_e32 v107, v0
	v_mov_b32_e32 v108, v0
	v_mov_b32_e32 v109, v0
	v_mov_b32_e32 v110, v0
	v_mov_b32_e32 v111, v0
	v_mov_b32_e32 v120, v0
	v_mov_b32_e32 v121, v0
	v_mov_b32_e32 v122, v0
	v_mov_b32_e32 v123, v0
	v_mov_b32_e32 v124, v0
	v_mov_b32_e32 v125, v0
	v_mov_b32_e32 v126, v0
	v_mov_b32_e32 v127, v0
	v_add_u32_e32 v204, 0x80, v128
	v_add_u32_e32 v205, 0x80, v130
	v_readfirstlane_b32 s101, v206
	s_nop 3
	s_lshr_b32 s101, s101, 8
	s_cmp_eq_u32 s101, 1
	s_cbranch_scc0 .Lprio_skip_11
	s_setprio 1

.LBB0_1561:
	ds_read_b128 v[140:143], v151
	ds_read_b128 v[144:147], v151 offset:1024
	ds_read_b128 v[156:159], v151 offset:2048
	ds_read_b128 v[160:163], v151 offset:3072
	ds_read_b128 v[164:167], v152
	ds_read_b128 v[168:171], v152 offset:1024
	ds_read_b128 v[172:175], v152 offset:2048
	ds_read_b128 v[176:179], v152 offset:3072
	s_add_u32 s38, s36, 0xfffc0080
	s_addc_u32 s39, s37, -1
	s_cmp_eq_u32 s61, 12
	s_cselect_b32 s41, s3, s39
	s_cselect_b32 s40, s29, s38
	s_cselect_b32 s39, s27, s60
	s_cselect_b32 s38, s58, s59
	s_add_i32 m0, s46, 0xc000
	ds_read_b128 v[180:183], v153
	ds_read_b128 v[184:187], v153 offset:1024
	ds_read_b128 v[188:191], v153 offset:2048
	ds_read_b128 v[192:195], v153 offset:3072
	ds_read_b128 v[196:199], v153 offset:4096
	ds_read_b128 v[200:203], v153 offset:5120
	ds_read_b128 v[208:211], v153 offset:6144
	ds_read_b128 v[212:215], v153 offset:7168
	global_load_lds_dwordx4 v134, s[36:37]
	s_add_i32 m0, s46, 0xe000
	s_nop 0
	global_load_lds_dwordx4 v132, s[36:37]
	s_waitcnt vmcnt(8)
	s_waitcnt lgkmcnt(0)
	s_barrier
	s_waitcnt lgkmcnt(0)
	v_mfma_f32_16x16x32_bf16 v[124:127], v[140:143], v[180:183], v[124:127]
	v_mfma_f32_16x16x32_bf16 v[120:123], v[156:159], v[180:183], v[120:123]
	v_mfma_f32_16x16x32_bf16 v[108:111], v[140:143], v[188:191], v[108:111]
	v_mfma_f32_16x16x32_bf16 v[104:107], v[156:159], v[188:191], v[104:107]
	v_mfma_f32_16x16x32_bf16 v[92:95], v[140:143], v[196:199], v[92:95]
	v_mfma_f32_16x16x32_bf16 v[88:91], v[156:159], v[196:199], v[88:91]
	v_mfma_f32_16x16x32_bf16 v[76:79], v[140:143], v[208:211], v[76:79]
	v_mfma_f32_16x16x32_bf16 v[72:75], v[156:159], v[208:211], v[72:75]
	v_mfma_f32_16x16x32_bf16 v[124:127], v[144:147], v[184:187], v[124:127]
	v_mfma_f32_16x16x32_bf16 v[120:123], v[160:163], v[184:187], v[120:123]
	v_mfma_f32_16x16x32_bf16 v[108:111], v[144:147], v[192:195], v[108:111]
	v_mfma_f32_16x16x32_bf16 v[104:107], v[160:163], v[192:195], v[104:107]
	v_mfma_f32_16x16x32_bf16 v[92:95], v[144:147], v[200:203], v[92:95]
	v_mfma_f32_16x16x32_bf16 v[88:91], v[160:163], v[200:203], v[88:91]
	v_mfma_f32_16x16x32_bf16 v[76:79], v[144:147], v[212:215], v[76:79]
	v_mfma_f32_16x16x32_bf16 v[72:75], v[160:163], v[212:215], v[72:75]
	v_mfma_f32_16x16x32_bf16 v[116:119], v[164:167], v[180:183], v[116:119]
	v_mfma_f32_16x16x32_bf16 v[112:115], v[172:175], v[180:183], v[112:115]
	v_mfma_f32_16x16x32_bf16 v[100:103], v[164:167], v[188:191], v[100:103]
	v_mfma_f32_16x16x32_bf16 v[96:99], v[172:175], v[188:191], v[96:99]
	v_mfma_f32_16x16x32_bf16 v[84:87], v[164:167], v[196:199], v[84:87]
	v_mfma_f32_16x16x32_bf16 v[80:83], v[172:175], v[196:199], v[80:83]
	v_mfma_f32_16x16x32_bf16 v[68:71], v[164:167], v[208:211], v[68:71]
	v_mfma_f32_16x16x32_bf16 v[64:67], v[172:175], v[208:211], v[64:67]
	v_mfma_f32_16x16x32_bf16 v[116:119], v[168:171], v[184:187], v[116:119]
	v_mfma_f32_16x16x32_bf16 v[112:115], v[176:179], v[184:187], v[112:115]
	v_mfma_f32_16x16x32_bf16 v[100:103], v[168:171], v[192:195], v[100:103]
	v_mfma_f32_16x16x32_bf16 v[96:99], v[176:179], v[192:195], v[96:99]
	v_mfma_f32_16x16x32_bf16 v[84:87], v[168:171], v[200:203], v[84:87]
	v_mfma_f32_16x16x32_bf16 v[80:83], v[176:179], v[200:203], v[80:83]
	v_mfma_f32_16x16x32_bf16 v[68:71], v[168:171], v[212:215], v[68:71]
	v_mfma_f32_16x16x32_bf16 v[64:67], v[176:179], v[212:215], v[64:67]
	s_barrier
	s_add_i32 s62, s54, s45
	s_mov_b32 m0, s62
	ds_read_b128 v[180:183], v153 offset:16384
	ds_read_b128 v[184:187], v153 offset:17408
	ds_read_b128 v[188:191], v153 offset:18432
	ds_read_b128 v[192:195], v153 offset:19456
	ds_read_b128 v[196:199], v153 offset:20480
	ds_read_b128 v[200:203], v153 offset:21504
	ds_read_b128 v[208:211], v153 offset:22528
	ds_read_b128 v[212:215], v153 offset:23552
	global_load_lds_dwordx4 v128, s[38:39]
	s_add_i32 m0, s62, 0x2000
	s_add_u32 s62, s38, 0x40000
	s_mov_b64 s[98:99], s[38:39]
	s_addc_u32 s63, s39, 0
	s_add_i32 s64, s55, s45
	global_load_lds_dwordx4 v130, s[38:39]
	s_mov_b32 m0, s64
	s_mov_b64 s[100:101], s[40:41]
	global_load_lds_dwordx4 v128, s[62:63]
	s_add_i32 m0, s64, 0x2000
	s_nop 0
	global_load_lds_dwordx4 v130, s[62:63]
	s_mov_b32 m0, s46
	s_nop 0
	global_load_lds_dwordx4 v128, s[40:41]
	s_mov_b32 m0, s47
	s_nop 0
	global_load_lds_dwordx4 v130, s[40:41]
	s_waitcnt vmcnt(8)
	s_waitcnt lgkmcnt(0)
	s_barrier
	s_waitcnt lgkmcnt(0)
	v_mfma_f32_16x16x32_bf16 v[60:63], v[140:143], v[180:183], v[60:63]
	v_mfma_f32_16x16x32_bf16 v[56:59], v[156:159], v[180:183], v[56:59]
	v_mfma_f32_16x16x32_bf16 v[44:47], v[140:143], v[188:191], v[44:47]
	v_mfma_f32_16x16x32_bf16 v[40:43], v[156:159], v[188:191], v[40:43]
	v_mfma_f32_16x16x32_bf16 v[28:31], v[140:143], v[196:199], v[28:31]
	v_mfma_f32_16x16x32_bf16 v[24:27], v[156:159], v[196:199], v[24:27]
	v_mfma_f32_16x16x32_bf16 v[12:15], v[140:143], v[208:211], v[12:15]
	v_mfma_f32_16x16x32_bf16 v[8:11], v[156:159], v[208:211], v[8:11]
	v_mfma_f32_16x16x32_bf16 v[60:63], v[144:147], v[184:187], v[60:63]
	v_mfma_f32_16x16x32_bf16 v[56:59], v[160:163], v[184:187], v[56:59]
	v_mfma_f32_16x16x32_bf16 v[44:47], v[144:147], v[192:195], v[44:47]
	v_mfma_f32_16x16x32_bf16 v[40:43], v[160:163], v[192:195], v[40:43]
	v_mfma_f32_16x16x32_bf16 v[28:31], v[144:147], v[200:203], v[28:31]
	v_mfma_f32_16x16x32_bf16 v[24:27], v[160:163], v[200:203], v[24:27]
	v_mfma_f32_16x16x32_bf16 v[12:15], v[144:147], v[212:215], v[12:15]
	v_mfma_f32_16x16x32_bf16 v[8:11], v[160:163], v[212:215], v[8:11]
	v_mfma_f32_16x16x32_bf16 v[52:55], v[164:167], v[180:183], v[52:55]
	v_mfma_f32_16x16x32_bf16 v[48:51], v[172:175], v[180:183], v[48:51]
	v_mfma_f32_16x16x32_bf16 v[36:39], v[164:167], v[188:191], v[36:39]
	v_mfma_f32_16x16x32_bf16 v[32:35], v[172:175], v[188:191], v[32:35]
	v_mfma_f32_16x16x32_bf16 v[20:23], v[164:167], v[196:199], v[20:23]
	v_mfma_f32_16x16x32_bf16 v[16:19], v[172:175], v[196:199], v[16:19]
	v_mfma_f32_16x16x32_bf16 v[4:7], v[164:167], v[208:211], v[4:7]
	v_mfma_f32_16x16x32_bf16 v[0:3], v[172:175], v[208:211], v[0:3]
	v_mfma_f32_16x16x32_bf16 v[52:55], v[168:171], v[184:187], v[52:55]
	v_mfma_f32_16x16x32_bf16 v[48:51], v[176:179], v[184:187], v[48:51]
	v_mfma_f32_16x16x32_bf16 v[36:39], v[168:171], v[192:195], v[36:39]
	v_mfma_f32_16x16x32_bf16 v[32:35], v[176:179], v[192:195], v[32:35]
	v_mfma_f32_16x16x32_bf16 v[20:23], v[168:171], v[200:203], v[20:23]
	v_mfma_f32_16x16x32_bf16 v[16:19], v[176:179], v[200:203], v[16:19]
	v_mfma_f32_16x16x32_bf16 v[4:7], v[168:171], v[212:215], v[4:7]
	v_mfma_f32_16x16x32_bf16 v[0:3], v[176:179], v[212:215], v[0:3]
	s_barrier
	s_add_i32 s62, 0, 0x18000
	v_add_u32_e32 v155, s62, v149
	s_add_i32 s63, 0, 0x1c000
	ds_read_b128 v[140:143], v155
	ds_read_b128 v[144:147], v155 offset:1024
	ds_read_b128 v[156:159], v155 offset:2048
	ds_read_b128 v[160:163], v155 offset:3072
	v_add_u32_e32 v155, s63, v149
	ds_read_b128 v[164:167], v155
	ds_read_b128 v[168:171], v155 offset:1024
	ds_read_b128 v[172:175], v155 offset:2048
	ds_read_b128 v[176:179], v155 offset:3072
	s_add_u32 s40, s40, 0x40000
	s_addc_u32 s41, s41, 0
	s_mov_b32 m0, s48
	ds_read_b128 v[180:183], v153 offset:32768
	ds_read_b128 v[184:187], v153 offset:33792
	ds_read_b128 v[188:191], v153 offset:34816
	ds_read_b128 v[192:195], v153 offset:35840
	ds_read_b128 v[196:199], v153 offset:36864
	ds_read_b128 v[200:203], v153 offset:37888
	ds_read_b128 v[208:211], v153 offset:38912
	ds_read_b128 v[212:215], v153 offset:39936
	global_load_lds_dwordx4 v128, s[40:41]
	s_mov_b32 m0, s49
	s_nop 0
	global_load_lds_dwordx4 v130, s[40:41]
	s_waitcnt vmcnt(8)
	s_waitcnt lgkmcnt(0)
	s_barrier
	s_waitcnt lgkmcnt(0)
	v_mfma_f32_16x16x32_bf16 v[124:127], v[140:143], v[180:183], v[124:127]
	v_mfma_f32_16x16x32_bf16 v[120:123], v[156:159], v[180:183], v[120:123]
	v_mfma_f32_16x16x32_bf16 v[108:111], v[140:143], v[188:191], v[108:111]
	v_mfma_f32_16x16x32_bf16 v[104:107], v[156:159], v[188:191], v[104:107]
	v_mfma_f32_16x16x32_bf16 v[92:95], v[140:143], v[196:199], v[92:95]
	v_mfma_f32_16x16x32_bf16 v[88:91], v[156:159], v[196:199], v[88:91]
	v_mfma_f32_16x16x32_bf16 v[76:79], v[140:143], v[208:211], v[76:79]
	v_mfma_f32_16x16x32_bf16 v[72:75], v[156:159], v[208:211], v[72:75]
	v_mfma_f32_16x16x32_bf16 v[124:127], v[144:147], v[184:187], v[124:127]
	v_mfma_f32_16x16x32_bf16 v[120:123], v[160:163], v[184:187], v[120:123]
	v_mfma_f32_16x16x32_bf16 v[108:111], v[144:147], v[192:195], v[108:111]
	v_mfma_f32_16x16x32_bf16 v[104:107], v[160:163], v[192:195], v[104:107]
	v_mfma_f32_16x16x32_bf16 v[92:95], v[144:147], v[200:203], v[92:95]
	v_mfma_f32_16x16x32_bf16 v[88:91], v[160:163], v[200:203], v[88:91]
	v_mfma_f32_16x16x32_bf16 v[76:79], v[144:147], v[212:215], v[76:79]
	v_mfma_f32_16x16x32_bf16 v[72:75], v[160:163], v[212:215], v[72:75]
	v_mfma_f32_16x16x32_bf16 v[116:119], v[164:167], v[180:183], v[116:119]
	v_mfma_f32_16x16x32_bf16 v[112:115], v[172:175], v[180:183], v[112:115]
	v_mfma_f32_16x16x32_bf16 v[100:103], v[164:167], v[188:191], v[100:103]
	v_mfma_f32_16x16x32_bf16 v[96:99], v[172:175], v[188:191], v[96:99]
	v_mfma_f32_16x16x32_bf16 v[84:87], v[164:167], v[196:199], v[84:87]
	v_mfma_f32_16x16x32_bf16 v[80:83], v[172:175], v[196:199], v[80:83]
	v_mfma_f32_16x16x32_bf16 v[68:71], v[164:167], v[208:211], v[68:71]
	v_mfma_f32_16x16x32_bf16 v[64:67], v[172:175], v[208:211], v[64:67]
	v_mfma_f32_16x16x32_bf16 v[116:119], v[168:171], v[184:187], v[116:119]
	v_mfma_f32_16x16x32_bf16 v[112:115], v[176:179], v[184:187], v[112:115]
	v_mfma_f32_16x16x32_bf16 v[100:103], v[168:171], v[192:195], v[100:103]
	v_mfma_f32_16x16x32_bf16 v[96:99], v[176:179], v[192:195], v[96:99]
	v_mfma_f32_16x16x32_bf16 v[84:87], v[168:171], v[200:203], v[84:87]
	v_mfma_f32_16x16x32_bf16 v[80:83], v[176:179], v[200:203], v[80:83]
	v_mfma_f32_16x16x32_bf16 v[68:71], v[168:171], v[212:215], v[68:71]
	v_mfma_f32_16x16x32_bf16 v[64:67], v[176:179], v[212:215], v[64:67]
	s_barrier
	s_add_i32 s40, s62, s45
	s_mov_b32 m0, s40
	ds_read_b128 v[180:183], v153 offset:49152
	ds_read_b128 v[184:187], v153 offset:50176
	ds_read_b128 v[188:191], v153 offset:51200
	ds_read_b128 v[192:195], v153 offset:52224
	ds_read_b128 v[196:199], v153 offset:53248
	ds_read_b128 v[200:203], v153 offset:54272
	ds_read_b128 v[208:211], v153 offset:55296
	ds_read_b128 v[212:215], v153 offset:56320
	global_load_lds_dwordx4 v204, s[38:39]
	s_add_i32 m0, s40, 0x2000
	s_add_u32 s38, s38, 0x40080
	s_addc_u32 s39, s39, 0
	s_add_i32 s40, s63, s45
	global_load_lds_dwordx4 v205, s[98:99]
	s_mov_b32 m0, s40
	s_nop 0
	global_load_lds_dwordx4 v128, s[38:39]
	s_add_i32 m0, s40, 0x2000
	s_nop 0
	global_load_lds_dwordx4 v130, s[38:39]
	s_mov_b32 m0, s51
	s_nop 0
	global_load_lds_dwordx4 v204, s[100:101]
	s_mov_b32 m0, s52
	s_nop 0
	global_load_lds_dwordx4 v205, s[100:101]
	s_waitcnt vmcnt(8)
	s_waitcnt lgkmcnt(0)
	s_barrier
	s_waitcnt lgkmcnt(0)
	v_mfma_f32_16x16x32_bf16 v[60:63], v[140:143], v[180:183], v[60:63]
	v_mfma_f32_16x16x32_bf16 v[56:59], v[156:159], v[180:183], v[56:59]
	v_mfma_f32_16x16x32_bf16 v[44:47], v[140:143], v[188:191], v[44:47]
	v_mfma_f32_16x16x32_bf16 v[40:43], v[156:159], v[188:191], v[40:43]
	v_mfma_f32_16x16x32_bf16 v[28:31], v[140:143], v[196:199], v[28:31]
	v_mfma_f32_16x16x32_bf16 v[24:27], v[156:159], v[196:199], v[24:27]
	v_mfma_f32_16x16x32_bf16 v[12:15], v[140:143], v[208:211], v[12:15]
	v_mfma_f32_16x16x32_bf16 v[8:11], v[156:159], v[208:211], v[8:11]
	v_mfma_f32_16x16x32_bf16 v[60:63], v[144:147], v[184:187], v[60:63]
	v_mfma_f32_16x16x32_bf16 v[56:59], v[160:163], v[184:187], v[56:59]
	v_mfma_f32_16x16x32_bf16 v[44:47], v[144:147], v[192:195], v[44:47]
	v_mfma_f32_16x16x32_bf16 v[40:43], v[160:163], v[192:195], v[40:43]
	v_mfma_f32_16x16x32_bf16 v[28:31], v[144:147], v[200:203], v[28:31]
	v_mfma_f32_16x16x32_bf16 v[24:27], v[160:163], v[200:203], v[24:27]
	v_mfma_f32_16x16x32_bf16 v[12:15], v[144:147], v[212:215], v[12:15]
	v_mfma_f32_16x16x32_bf16 v[8:11], v[160:163], v[212:215], v[8:11]
	v_mfma_f32_16x16x32_bf16 v[52:55], v[164:167], v[180:183], v[52:55]
	v_mfma_f32_16x16x32_bf16 v[48:51], v[172:175], v[180:183], v[48:51]
	v_mfma_f32_16x16x32_bf16 v[36:39], v[164:167], v[188:191], v[36:39]
	v_mfma_f32_16x16x32_bf16 v[32:35], v[172:175], v[188:191], v[32:35]
	v_mfma_f32_16x16x32_bf16 v[20:23], v[164:167], v[196:199], v[20:23]
	v_mfma_f32_16x16x32_bf16 v[16:19], v[172:175], v[196:199], v[16:19]
	v_mfma_f32_16x16x32_bf16 v[4:7], v[164:167], v[208:211], v[4:7]
	v_mfma_f32_16x16x32_bf16 v[0:3], v[172:175], v[208:211], v[0:3]
	v_mfma_f32_16x16x32_bf16 v[52:55], v[168:171], v[184:187], v[52:55]
	v_mfma_f32_16x16x32_bf16 v[48:51], v[176:179], v[184:187], v[48:51]
	v_mfma_f32_16x16x32_bf16 v[36:39], v[168:171], v[192:195], v[36:39]
	v_mfma_f32_16x16x32_bf16 v[32:35], v[176:179], v[192:195], v[32:35]
	v_mfma_f32_16x16x32_bf16 v[20:23], v[168:171], v[200:203], v[20:23]
	v_mfma_f32_16x16x32_bf16 v[16:19], v[176:179], v[200:203], v[16:19]
	v_mfma_f32_16x16x32_bf16 v[4:7], v[168:171], v[212:215], v[4:7]
	v_mfma_f32_16x16x32_bf16 v[0:3], v[176:179], v[212:215], v[0:3]
	s_barrier
	s_add_i32 s61, s61, 2
	s_add_u32 s59, s59, 0x100
	s_addc_u32 s60, s60, 0
	s_add_u32 s36, s36, 0x100
	s_addc_u32 s37, s37, 0
	s_cmp_gt_u32 s61, 13
	s_cbranch_scc0 .LBB0_1561
	s_setprio 0
	s_and_b64 vcc, exec, s[24:25]
	s_cbranch_vccz .LBB0_1564
	s_barrier

.LBB0_1645:
	s_ashr_i32 s19, s18, 31
	s_lshl_b64 s[20:21], s[18:19], 19
	s_add_u32 s20, s8, s20
	s_addc_u32 s21, s9, s21
	s_and_b64 s[22:23], s[4:5], exec
	s_cselect_b32 s19, s21, s27
	s_cselect_b32 s50, s20, s26
	s_ashr_i32 s17, s16, 31
	s_lshl_b64 s[22:23], s[16:17], 19
	s_add_u32 s22, s31, s22
	s_addc_u32 s23, s34, s23
	s_and_b64 s[28:29], s[4:5], exec
	s_cselect_b32 s17, s23, s25
	s_cselect_b32 s51, s22, s24
	s_add_u32 s52, s24, 0x100
	s_addc_u32 s53, s25, 0
	s_add_u32 s24, s26, 0x40080
	v_mov_b32_e32 v0, 0
	s_addc_u32 s25, s27, 0
	s_mov_b32 s54, -2
	v_mov_b32_e32 v1, v0
	v_mov_b32_e32 v2, v0
	v_mov_b32_e32 v3, v0
	v_mov_b32_e32 v4, v0
	v_mov_b32_e32 v5, v0
	v_mov_b32_e32 v6, v0
	v_mov_b32_e32 v7, v0
	v_mov_b32_e32 v16, v0
	v_mov_b32_e32 v17, v0
	v_mov_b32_e32 v18, v0
	v_mov_b32_e32 v19, v0
	v_mov_b32_e32 v20, v0
	v_mov_b32_e32 v21, v0
	v_mov_b32_e32 v22, v0
	v_mov_b32_e32 v23, v0
	v_mov_b32_e32 v32, v0
	v_mov_b32_e32 v33, v0
	v_mov_b32_e32 v34, v0
	v_mov_b32_e32 v35, v0
	v_mov_b32_e32 v36, v0
	v_mov_b32_e32 v37, v0
	v_mov_b32_e32 v38, v0
	v_mov_b32_e32 v39, v0
	v_mov_b32_e32 v48, v0
	v_mov_b32_e32 v49, v0
	v_mov_b32_e32 v50, v0
	v_mov_b32_e32 v51, v0
	v_mov_b32_e32 v52, v0
	v_mov_b32_e32 v53, v0
	v_mov_b32_e32 v54, v0
	v_mov_b32_e32 v55, v0
	v_mov_b32_e32 v8, v0
	v_mov_b32_e32 v9, v0
	v_mov_b32_e32 v10, v0
	v_mov_b32_e32 v11, v0
	v_mov_b32_e32 v12, v0
	v_mov_b32_e32 v13, v0
	v_mov_b32_e32 v14, v0
	v_mov_b32_e32 v15, v0
	v_mov_b32_e32 v24, v0
	v_mov_b32_e32 v25, v0
	v_mov_b32_e32 v26, v0
	v_mov_b32_e32 v27, v0
	v_mov_b32_e32 v28, v0
	v_mov_b32_e32 v29, v0
	v_mov_b32_e32 v30, v0
	v_mov_b32_e32 v31, v0
	v_mov_b32_e32 v40, v0
	v_mov_b32_e32 v41, v0
	v_mov_b32_e32 v42, v0
	v_mov_b32_e32 v43, v0
	v_mov_b32_e32 v44, v0
	v_mov_b32_e32 v45, v0
	v_mov_b32_e32 v46, v0
	v_mov_b32_e32 v47, v0
	v_mov_b32_e32 v56, v0
	v_mov_b32_e32 v57, v0
	v_mov_b32_e32 v58, v0
	v_mov_b32_e32 v59, v0
	v_mov_b32_e32 v60, v0
	v_mov_b32_e32 v61, v0
	v_mov_b32_e32 v62, v0
	v_mov_b32_e32 v63, v0
	v_mov_b32_e32 v64, v0
	v_mov_b32_e32 v65, v0
	v_mov_b32_e32 v66, v0
	v_mov_b32_e32 v67, v0
	v_mov_b32_e32 v68, v0
	v_mov_b32_e32 v69, v0
	v_mov_b32_e32 v70, v0
	v_mov_b32_e32 v71, v0
	v_mov_b32_e32 v80, v0
	v_mov_b32_e32 v81, v0
	v_mov_b32_e32 v82, v0
	v_mov_b32_e32 v83, v0
	v_mov_b32_e32 v84, v0
	v_mov_b32_e32 v85, v0
	v_mov_b32_e32 v86, v0
	v_mov_b32_e32 v87, v0
	v_mov_b32_e32 v96, v0
	v_mov_b32_e32 v97, v0
	v_mov_b32_e32 v98, v0
	v_mov_b32_e32 v99, v0
	v_mov_b32_e32 v100, v0
	v_mov_b32_e32 v101, v0
	v_mov_b32_e32 v102, v0
	v_mov_b32_e32 v103, v0
	v_mov_b32_e32 v112, v0
	v_mov_b32_e32 v113, v0
	v_mov_b32_e32 v114, v0
	v_mov_b32_e32 v115, v0
	v_mov_b32_e32 v116, v0
	v_mov_b32_e32 v117, v0
	v_mov_b32_e32 v118, v0
	v_mov_b32_e32 v119, v0
	v_mov_b32_e32 v72, v0
	v_mov_b32_e32 v73, v0
	v_mov_b32_e32 v74, v0
	v_mov_b32_e32 v75, v0
	v_mov_b32_e32 v76, v0
	v_mov_b32_e32 v77, v0
	v_mov_b32_e32 v78, v0
	v_mov_b32_e32 v79, v0
	v_mov_b32_e32 v88, v0
	v_mov_b32_e32 v89, v0
	v_mov_b32_e32 v90, v0
	v_mov_b32_e32 v91, v0
	v_mov_b32_e32 v92, v0
	v_mov_b32_e32 v93, v0
	v_mov_b32_e32 v94, v0
	v_mov_b32_e32 v95, v0
	v_mov_b32_e32 v104, v0
	v_mov_b32_e32 v105, v0
	v_mov_b32_e32 v106, v0
	v_mov_b32_e32 v107, v0
	v_mov_b32_e32 v108, v0
	v_mov_b32_e32 v109, v0
	v_mov_b32_e32 v110, v0
	v_mov_b32_e32 v111, v0
	v_mov_b32_e32 v120, v0
	v_mov_b32_e32 v121, v0
	v_mov_b32_e32 v122, v0
	v_mov_b32_e32 v123, v0
	v_mov_b32_e32 v124, v0
	v_mov_b32_e32 v125, v0
	v_mov_b32_e32 v126, v0
	v_mov_b32_e32 v127, v0
	v_add_u32_e32 v204, 0x80, v128
	v_add_u32_e32 v205, 0x80, v130
	v_add_u32_e32 v220, 0x80, v132
	v_add_u32_e32 v221, 0x80, v134
	v_readfirstlane_b32 s101, v206
	s_nop 3
	s_lshr_b32 s101, s101, 8
	s_cmp_eq_u32 s101, 1
	s_cbranch_scc0 .Lprio_skip_10
	s_setprio 1

.LBB0_1646:
	ds_read_b128 v[144:147], v151
	ds_read_b128 v[156:159], v151 offset:1024
	ds_read_b128 v[160:163], v151 offset:2048
	ds_read_b128 v[164:167], v151 offset:3072
	ds_read_b128 v[168:171], v152
	ds_read_b128 v[172:175], v152 offset:1024
	ds_read_b128 v[176:179], v152 offset:2048
	ds_read_b128 v[180:183], v152 offset:3072
	s_add_u32 s26, s24, 0xfffc0080
	s_addc_u32 s27, s25, -1
	s_cmp_eq_u32 s54, 12
	s_cselect_b32 s29, s19, s27
	s_cselect_b32 s28, s50, s26
	s_cselect_b32 s27, s17, s53
	s_cselect_b32 s26, s51, s52
	s_add_i32 m0, s38, 0xc000
	ds_read_b128 v[184:187], v153
	ds_read_b128 v[188:191], v153 offset:1024
	ds_read_b128 v[192:195], v153 offset:2048
	ds_read_b128 v[196:199], v153 offset:3072
	ds_read_b128 v[200:203], v153 offset:4096
	ds_read_b128 v[208:211], v153 offset:5120
	ds_read_b128 v[212:215], v153 offset:6144
	ds_read_b128 v[216:219], v153 offset:7168
	global_load_lds_dwordx4 v138, s[24:25]
	s_add_i32 m0, s38, 0xe000
	s_nop 0
	global_load_lds_dwordx4 v136, s[24:25]
	s_waitcnt vmcnt(8)
	s_waitcnt lgkmcnt(0)
	s_barrier
	s_waitcnt lgkmcnt(0)
	v_mfma_f32_16x16x32_bf16 v[124:127], v[144:147], v[184:187], v[124:127]
	v_mfma_f32_16x16x32_bf16 v[120:123], v[160:163], v[184:187], v[120:123]
	v_mfma_f32_16x16x32_bf16 v[108:111], v[144:147], v[192:195], v[108:111]
	v_mfma_f32_16x16x32_bf16 v[104:107], v[160:163], v[192:195], v[104:107]
	v_mfma_f32_16x16x32_bf16 v[92:95], v[144:147], v[200:203], v[92:95]
	v_mfma_f32_16x16x32_bf16 v[88:91], v[160:163], v[200:203], v[88:91]
	v_mfma_f32_16x16x32_bf16 v[76:79], v[144:147], v[212:215], v[76:79]
	v_mfma_f32_16x16x32_bf16 v[72:75], v[160:163], v[212:215], v[72:75]
	v_mfma_f32_16x16x32_bf16 v[124:127], v[156:159], v[188:191], v[124:127]
	v_mfma_f32_16x16x32_bf16 v[120:123], v[164:167], v[188:191], v[120:123]
	v_mfma_f32_16x16x32_bf16 v[108:111], v[156:159], v[196:199], v[108:111]
	v_mfma_f32_16x16x32_bf16 v[104:107], v[164:167], v[196:199], v[104:107]
	v_mfma_f32_16x16x32_bf16 v[92:95], v[156:159], v[208:211], v[92:95]
	v_mfma_f32_16x16x32_bf16 v[88:91], v[164:167], v[208:211], v[88:91]
	v_mfma_f32_16x16x32_bf16 v[76:79], v[156:159], v[216:219], v[76:79]
	v_mfma_f32_16x16x32_bf16 v[72:75], v[164:167], v[216:219], v[72:75]
	v_mfma_f32_16x16x32_bf16 v[116:119], v[168:171], v[184:187], v[116:119]
	v_mfma_f32_16x16x32_bf16 v[112:115], v[176:179], v[184:187], v[112:115]
	v_mfma_f32_16x16x32_bf16 v[100:103], v[168:171], v[192:195], v[100:103]
	v_mfma_f32_16x16x32_bf16 v[96:99], v[176:179], v[192:195], v[96:99]
	v_mfma_f32_16x16x32_bf16 v[84:87], v[168:171], v[200:203], v[84:87]
	v_mfma_f32_16x16x32_bf16 v[80:83], v[176:179], v[200:203], v[80:83]
	v_mfma_f32_16x16x32_bf16 v[68:71], v[168:171], v[212:215], v[68:71]
	v_mfma_f32_16x16x32_bf16 v[64:67], v[176:179], v[212:215], v[64:67]
	v_mfma_f32_16x16x32_bf16 v[116:119], v[172:175], v[188:191], v[116:119]
	v_mfma_f32_16x16x32_bf16 v[112:115], v[180:183], v[188:191], v[112:115]
	v_mfma_f32_16x16x32_bf16 v[100:103], v[172:175], v[196:199], v[100:103]
	v_mfma_f32_16x16x32_bf16 v[96:99], v[180:183], v[196:199], v[96:99]
	v_mfma_f32_16x16x32_bf16 v[84:87], v[172:175], v[208:211], v[84:87]
	v_mfma_f32_16x16x32_bf16 v[80:83], v[180:183], v[208:211], v[80:83]
	v_mfma_f32_16x16x32_bf16 v[68:71], v[172:175], v[216:219], v[68:71]
	v_mfma_f32_16x16x32_bf16 v[64:67], v[180:183], v[216:219], v[64:67]
	s_barrier
	s_add_i32 s55, s47, s35
	s_mov_b32 m0, s55
	ds_read_b128 v[184:187], v153 offset:16384
	ds_read_b128 v[188:191], v153 offset:17408
	ds_read_b128 v[192:195], v153 offset:18432
	ds_read_b128 v[196:199], v153 offset:19456
	ds_read_b128 v[200:203], v153 offset:20480
	ds_read_b128 v[208:211], v153 offset:21504
	ds_read_b128 v[212:215], v153 offset:22528
	ds_read_b128 v[216:219], v153 offset:23552
	global_load_lds_dwordx4 v132, s[26:27]
	s_add_i32 m0, s55, 0x2000
	s_add_u32 s56, s26, 0x40000
	s_mov_b64 s[98:99], s[26:27]
	s_addc_u32 s57, s27, 0
	s_add_i32 s55, s48, s35
	global_load_lds_dwordx4 v128, s[26:27]
	s_mov_b32 m0, s55
	s_mov_b64 s[100:101], s[28:29]
	global_load_lds_dwordx4 v132, s[56:57]
	s_add_i32 m0, s55, 0x2000
	s_nop 0
	global_load_lds_dwordx4 v128, s[56:57]
	s_mov_b32 m0, s38
	s_nop 0
	global_load_lds_dwordx4 v134, s[28:29]
	s_mov_b32 m0, s39
	s_nop 0
	global_load_lds_dwordx4 v130, s[28:29]
	s_waitcnt vmcnt(8)
	s_waitcnt lgkmcnt(0)
	s_barrier
	s_waitcnt lgkmcnt(0)
	v_mfma_f32_16x16x32_bf16 v[60:63], v[144:147], v[184:187], v[60:63]
	v_mfma_f32_16x16x32_bf16 v[56:59], v[160:163], v[184:187], v[56:59]
	v_mfma_f32_16x16x32_bf16 v[44:47], v[144:147], v[192:195], v[44:47]
	v_mfma_f32_16x16x32_bf16 v[40:43], v[160:163], v[192:195], v[40:43]
	v_mfma_f32_16x16x32_bf16 v[28:31], v[144:147], v[200:203], v[28:31]
	v_mfma_f32_16x16x32_bf16 v[24:27], v[160:163], v[200:203], v[24:27]
	v_mfma_f32_16x16x32_bf16 v[12:15], v[144:147], v[212:215], v[12:15]
	v_mfma_f32_16x16x32_bf16 v[8:11], v[160:163], v[212:215], v[8:11]
	v_mfma_f32_16x16x32_bf16 v[60:63], v[156:159], v[188:191], v[60:63]
	v_mfma_f32_16x16x32_bf16 v[56:59], v[164:167], v[188:191], v[56:59]
	v_mfma_f32_16x16x32_bf16 v[44:47], v[156:159], v[196:199], v[44:47]
	v_mfma_f32_16x16x32_bf16 v[40:43], v[164:167], v[196:199], v[40:43]
	v_mfma_f32_16x16x32_bf16 v[28:31], v[156:159], v[208:211], v[28:31]
	v_mfma_f32_16x16x32_bf16 v[24:27], v[164:167], v[208:211], v[24:27]
	v_mfma_f32_16x16x32_bf16 v[12:15], v[156:159], v[216:219], v[12:15]
	v_mfma_f32_16x16x32_bf16 v[8:11], v[164:167], v[216:219], v[8:11]
	v_mfma_f32_16x16x32_bf16 v[52:55], v[168:171], v[184:187], v[52:55]
	v_mfma_f32_16x16x32_bf16 v[48:51], v[176:179], v[184:187], v[48:51]
	v_mfma_f32_16x16x32_bf16 v[36:39], v[168:171], v[192:195], v[36:39]
	v_mfma_f32_16x16x32_bf16 v[32:35], v[176:179], v[192:195], v[32:35]
	v_mfma_f32_16x16x32_bf16 v[20:23], v[168:171], v[200:203], v[20:23]
	v_mfma_f32_16x16x32_bf16 v[16:19], v[176:179], v[200:203], v[16:19]
	v_mfma_f32_16x16x32_bf16 v[4:7], v[168:171], v[212:215], v[4:7]
	v_mfma_f32_16x16x32_bf16 v[0:3], v[176:179], v[212:215], v[0:3]
	v_mfma_f32_16x16x32_bf16 v[52:55], v[172:175], v[188:191], v[52:55]
	v_mfma_f32_16x16x32_bf16 v[48:51], v[180:183], v[188:191], v[48:51]
	v_mfma_f32_16x16x32_bf16 v[36:39], v[172:175], v[196:199], v[36:39]
	v_mfma_f32_16x16x32_bf16 v[32:35], v[180:183], v[196:199], v[32:35]
	v_mfma_f32_16x16x32_bf16 v[20:23], v[172:175], v[208:211], v[20:23]
	v_mfma_f32_16x16x32_bf16 v[16:19], v[180:183], v[208:211], v[16:19]
	v_mfma_f32_16x16x32_bf16 v[4:7], v[172:175], v[216:219], v[4:7]
	v_mfma_f32_16x16x32_bf16 v[0:3], v[180:183], v[216:219], v[0:3]
	s_barrier
	s_add_i32 s55, 0, 0x18000
	s_add_i32 s56, 0, 0x1c000
	v_add_u32_e32 v164, s55, v149
	v_add_u32_e32 v180, s56, v149
	ds_read_b128 v[144:147], v164
	ds_read_b128 v[156:159], v164 offset:1024
	ds_read_b128 v[160:163], v164 offset:2048
	ds_read_b128 v[164:167], v164 offset:3072
	ds_read_b128 v[168:171], v180
	ds_read_b128 v[172:175], v180 offset:1024
	ds_read_b128 v[176:179], v180 offset:2048
	ds_read_b128 v[180:183], v180 offset:3072
	s_add_u32 s28, s28, 0x40000
	s_addc_u32 s29, s29, 0
	s_mov_b32 m0, s40
	ds_read_b128 v[184:187], v153 offset:32768
	ds_read_b128 v[188:191], v153 offset:33792
	ds_read_b128 v[192:195], v153 offset:34816
	ds_read_b128 v[196:199], v153 offset:35840
	ds_read_b128 v[200:203], v153 offset:36864
	ds_read_b128 v[208:211], v153 offset:37888
	ds_read_b128 v[212:215], v153 offset:38912
	ds_read_b128 v[216:219], v153 offset:39936
	global_load_lds_dwordx4 v134, s[28:29]
	s_mov_b32 m0, s41
	s_nop 0
	global_load_lds_dwordx4 v130, s[28:29]
	s_waitcnt vmcnt(8)
	s_waitcnt lgkmcnt(0)
	s_barrier
	s_waitcnt lgkmcnt(0)
	v_mfma_f32_16x16x32_bf16 v[124:127], v[144:147], v[184:187], v[124:127]
	v_mfma_f32_16x16x32_bf16 v[120:123], v[160:163], v[184:187], v[120:123]
	v_mfma_f32_16x16x32_bf16 v[108:111], v[144:147], v[192:195], v[108:111]
	v_mfma_f32_16x16x32_bf16 v[104:107], v[160:163], v[192:195], v[104:107]
	v_mfma_f32_16x16x32_bf16 v[92:95], v[144:147], v[200:203], v[92:95]
	v_mfma_f32_16x16x32_bf16 v[88:91], v[160:163], v[200:203], v[88:91]
	v_mfma_f32_16x16x32_bf16 v[76:79], v[144:147], v[212:215], v[76:79]
	v_mfma_f32_16x16x32_bf16 v[72:75], v[160:163], v[212:215], v[72:75]
	v_mfma_f32_16x16x32_bf16 v[124:127], v[156:159], v[188:191], v[124:127]
	v_mfma_f32_16x16x32_bf16 v[120:123], v[164:167], v[188:191], v[120:123]
	v_mfma_f32_16x16x32_bf16 v[108:111], v[156:159], v[196:199], v[108:111]
	v_mfma_f32_16x16x32_bf16 v[104:107], v[164:167], v[196:199], v[104:107]
	v_mfma_f32_16x16x32_bf16 v[92:95], v[156:159], v[208:211], v[92:95]
	v_mfma_f32_16x16x32_bf16 v[88:91], v[164:167], v[208:211], v[88:91]
	v_mfma_f32_16x16x32_bf16 v[76:79], v[156:159], v[216:219], v[76:79]
	v_mfma_f32_16x16x32_bf16 v[72:75], v[164:167], v[216:219], v[72:75]
	v_mfma_f32_16x16x32_bf16 v[116:119], v[168:171], v[184:187], v[116:119]
	v_mfma_f32_16x16x32_bf16 v[112:115], v[176:179], v[184:187], v[112:115]
	v_mfma_f32_16x16x32_bf16 v[100:103], v[168:171], v[192:195], v[100:103]
	v_mfma_f32_16x16x32_bf16 v[96:99], v[176:179], v[192:195], v[96:99]
	v_mfma_f32_16x16x32_bf16 v[84:87], v[168:171], v[200:203], v[84:87]
	v_mfma_f32_16x16x32_bf16 v[80:83], v[176:179], v[200:203], v[80:83]
	v_mfma_f32_16x16x32_bf16 v[68:71], v[168:171], v[212:215], v[68:71]
	v_mfma_f32_16x16x32_bf16 v[64:67], v[176:179], v[212:215], v[64:67]
	v_mfma_f32_16x16x32_bf16 v[116:119], v[172:175], v[188:191], v[116:119]
	v_mfma_f32_16x16x32_bf16 v[112:115], v[180:183], v[188:191], v[112:115]
	v_mfma_f32_16x16x32_bf16 v[100:103], v[172:175], v[196:199], v[100:103]
	v_mfma_f32_16x16x32_bf16 v[96:99], v[180:183], v[196:199], v[96:99]
	v_mfma_f32_16x16x32_bf16 v[84:87], v[172:175], v[208:211], v[84:87]
	v_mfma_f32_16x16x32_bf16 v[80:83], v[180:183], v[208:211], v[80:83]
	v_mfma_f32_16x16x32_bf16 v[68:71], v[172:175], v[216:219], v[68:71]
	v_mfma_f32_16x16x32_bf16 v[64:67], v[180:183], v[216:219], v[64:67]
	s_barrier
	s_add_i32 s28, s55, s35
	s_mov_b32 m0, s28
	ds_read_b128 v[184:187], v153 offset:49152
	ds_read_b128 v[188:191], v153 offset:50176
	ds_read_b128 v[192:195], v153 offset:51200
	ds_read_b128 v[196:199], v153 offset:52224
	ds_read_b128 v[200:203], v153 offset:53248
	ds_read_b128 v[208:211], v153 offset:54272
	ds_read_b128 v[212:215], v153 offset:55296
	ds_read_b128 v[216:219], v153 offset:56320
	global_load_lds_dwordx4 v220, s[26:27]
	s_add_i32 m0, s28, 0x2000
	s_add_u32 s26, s26, 0x40080
	s_addc_u32 s27, s27, 0
	s_add_i32 s28, s56, s35
	global_load_lds_dwordx4 v204, s[98:99]
	s_mov_b32 m0, s28
	s_nop 0
	global_load_lds_dwordx4 v132, s[26:27]
	s_add_i32 m0, s28, 0x2000
	s_nop 0
	global_load_lds_dwordx4 v128, s[26:27]
	s_mov_b32 m0, s45
	s_nop 0
	global_load_lds_dwordx4 v221, s[100:101]
	s_mov_b32 m0, s46
	s_nop 0
	global_load_lds_dwordx4 v205, s[100:101]
	s_waitcnt vmcnt(8)
	s_waitcnt lgkmcnt(0)
	s_barrier
	s_waitcnt lgkmcnt(0)
	v_mfma_f32_16x16x32_bf16 v[60:63], v[144:147], v[184:187], v[60:63]
	v_mfma_f32_16x16x32_bf16 v[56:59], v[160:163], v[184:187], v[56:59]
	v_mfma_f32_16x16x32_bf16 v[44:47], v[144:147], v[192:195], v[44:47]
	v_mfma_f32_16x16x32_bf16 v[40:43], v[160:163], v[192:195], v[40:43]
	v_mfma_f32_16x16x32_bf16 v[28:31], v[144:147], v[200:203], v[28:31]
	v_mfma_f32_16x16x32_bf16 v[24:27], v[160:163], v[200:203], v[24:27]
	v_mfma_f32_16x16x32_bf16 v[12:15], v[144:147], v[212:215], v[12:15]
	v_mfma_f32_16x16x32_bf16 v[8:11], v[160:163], v[212:215], v[8:11]
	v_mfma_f32_16x16x32_bf16 v[60:63], v[156:159], v[188:191], v[60:63]
	v_mfma_f32_16x16x32_bf16 v[56:59], v[164:167], v[188:191], v[56:59]
	v_mfma_f32_16x16x32_bf16 v[44:47], v[156:159], v[196:199], v[44:47]
	v_mfma_f32_16x16x32_bf16 v[40:43], v[164:167], v[196:199], v[40:43]
	v_mfma_f32_16x16x32_bf16 v[28:31], v[156:159], v[208:211], v[28:31]
	v_mfma_f32_16x16x32_bf16 v[24:27], v[164:167], v[208:211], v[24:27]
	v_mfma_f32_16x16x32_bf16 v[12:15], v[156:159], v[216:219], v[12:15]
	v_mfma_f32_16x16x32_bf16 v[8:11], v[164:167], v[216:219], v[8:11]
	v_mfma_f32_16x16x32_bf16 v[52:55], v[168:171], v[184:187], v[52:55]
	v_mfma_f32_16x16x32_bf16 v[48:51], v[176:179], v[184:187], v[48:51]
	v_mfma_f32_16x16x32_bf16 v[36:39], v[168:171], v[192:195], v[36:39]
	v_mfma_f32_16x16x32_bf16 v[32:35], v[176:179], v[192:195], v[32:35]
	v_mfma_f32_16x16x32_bf16 v[20:23], v[168:171], v[200:203], v[20:23]
	v_mfma_f32_16x16x32_bf16 v[16:19], v[176:179], v[200:203], v[16:19]
	v_mfma_f32_16x16x32_bf16 v[4:7], v[168:171], v[212:215], v[4:7]
	v_mfma_f32_16x16x32_bf16 v[0:3], v[176:179], v[212:215], v[0:3]
	v_mfma_f32_16x16x32_bf16 v[52:55], v[172:175], v[188:191], v[52:55]
	v_mfma_f32_16x16x32_bf16 v[48:51], v[180:183], v[188:191], v[48:51]
	v_mfma_f32_16x16x32_bf16 v[36:39], v[172:175], v[196:199], v[36:39]
	v_mfma_f32_16x16x32_bf16 v[32:35], v[180:183], v[196:199], v[32:35]
	v_mfma_f32_16x16x32_bf16 v[20:23], v[172:175], v[208:211], v[20:23]
	v_mfma_f32_16x16x32_bf16 v[16:19], v[180:183], v[208:211], v[16:19]
	v_mfma_f32_16x16x32_bf16 v[4:7], v[172:175], v[216:219], v[4:7]
	v_mfma_f32_16x16x32_bf16 v[0:3], v[180:183], v[216:219], v[0:3]
	s_barrier
	s_add_i32 s54, s54, 2
	s_add_u32 s52, s52, 0x100
	s_addc_u32 s53, s53, 0
	s_add_u32 s24, s24, 0x100
	s_addc_u32 s25, s25, 0
	s_cmp_gt_u32 s54, 13
	s_cbranch_scc0 .LBB0_1646
	s_setprio 0
	s_and_b64 vcc, exec, s[14:15]
	s_cbranch_vccz .LBB0_1649
	s_barrier

.LBB0_3040:
	s_ashr_i32 s29, s28, 31
	s_lshl_b64 s[30:31], s[28:29], 19
	s_add_u32 s30, s8, s30
	s_addc_u32 s31, s9, s31
	s_and_b64 s[34:35], s[6:7], exec
	s_cselect_b32 s3, s31, s39
	s_cselect_b32 s29, s30, s38
	s_ashr_i32 s27, s26, 31
	s_lshl_b64 s[34:35], s[26:27], 19
	s_add_u32 s34, s43, s34
	s_addc_u32 s35, s44, s35
	s_and_b64 s[40:41], s[6:7], exec
	s_cselect_b32 s27, s35, s37
	s_cselect_b32 s58, s34, s36
	s_add_u32 s59, s36, 0x100
	s_addc_u32 s60, s37, 0
	s_add_u32 s36, s38, 0x40080
	v_mov_b32_e32 v0, 0
	s_addc_u32 s37, s39, 0
	s_mov_b32 s61, -2
	v_mov_b32_e32 v1, v0
	v_mov_b32_e32 v2, v0
	v_mov_b32_e32 v3, v0
	v_mov_b32_e32 v4, v0
	v_mov_b32_e32 v5, v0
	v_mov_b32_e32 v6, v0
	v_mov_b32_e32 v7, v0
	v_mov_b32_e32 v16, v0
	v_mov_b32_e32 v17, v0
	v_mov_b32_e32 v18, v0
	v_mov_b32_e32 v19, v0
	v_mov_b32_e32 v20, v0
	v_mov_b32_e32 v21, v0
	v_mov_b32_e32 v22, v0
	v_mov_b32_e32 v23, v0
	v_mov_b32_e32 v32, v0
	v_mov_b32_e32 v33, v0
	v_mov_b32_e32 v34, v0
	v_mov_b32_e32 v35, v0
	v_mov_b32_e32 v36, v0
	v_mov_b32_e32 v37, v0
	v_mov_b32_e32 v38, v0
	v_mov_b32_e32 v39, v0
	v_mov_b32_e32 v48, v0
	v_mov_b32_e32 v49, v0
	v_mov_b32_e32 v50, v0
	v_mov_b32_e32 v51, v0
	v_mov_b32_e32 v52, v0
	v_mov_b32_e32 v53, v0
	v_mov_b32_e32 v54, v0
	v_mov_b32_e32 v55, v0
	v_mov_b32_e32 v8, v0
	v_mov_b32_e32 v9, v0
	v_mov_b32_e32 v10, v0
	v_mov_b32_e32 v11, v0
	v_mov_b32_e32 v12, v0
	v_mov_b32_e32 v13, v0
	v_mov_b32_e32 v14, v0
	v_mov_b32_e32 v15, v0
	v_mov_b32_e32 v24, v0
	v_mov_b32_e32 v25, v0
	v_mov_b32_e32 v26, v0
	v_mov_b32_e32 v27, v0
	v_mov_b32_e32 v28, v0
	v_mov_b32_e32 v29, v0
	v_mov_b32_e32 v30, v0
	v_mov_b32_e32 v31, v0
	v_mov_b32_e32 v40, v0
	v_mov_b32_e32 v41, v0
	v_mov_b32_e32 v42, v0
	v_mov_b32_e32 v43, v0
	v_mov_b32_e32 v44, v0
	v_mov_b32_e32 v45, v0
	v_mov_b32_e32 v46, v0
	v_mov_b32_e32 v47, v0
	v_mov_b32_e32 v56, v0
	v_mov_b32_e32 v57, v0
	v_mov_b32_e32 v58, v0
	v_mov_b32_e32 v59, v0
	v_mov_b32_e32 v60, v0
	v_mov_b32_e32 v61, v0
	v_mov_b32_e32 v62, v0
	v_mov_b32_e32 v63, v0
	v_mov_b32_e32 v64, v0
	v_mov_b32_e32 v65, v0
	v_mov_b32_e32 v66, v0
	v_mov_b32_e32 v67, v0
	v_mov_b32_e32 v68, v0
	v_mov_b32_e32 v69, v0
	v_mov_b32_e32 v70, v0
	v_mov_b32_e32 v71, v0
	v_mov_b32_e32 v80, v0
	v_mov_b32_e32 v81, v0
	v_mov_b32_e32 v82, v0
	v_mov_b32_e32 v83, v0
	v_mov_b32_e32 v84, v0
	v_mov_b32_e32 v85, v0
	v_mov_b32_e32 v86, v0
	v_mov_b32_e32 v87, v0
	v_mov_b32_e32 v96, v0
	v_mov_b32_e32 v97, v0
	v_mov_b32_e32 v98, v0
	v_mov_b32_e32 v99, v0
	v_mov_b32_e32 v100, v0
	v_mov_b32_e32 v101, v0
	v_mov_b32_e32 v102, v0
	v_mov_b32_e32 v103, v0
	v_mov_b32_e32 v112, v0
	v_mov_b32_e32 v113, v0
	v_mov_b32_e32 v114, v0
	v_mov_b32_e32 v115, v0
	v_mov_b32_e32 v116, v0
	v_mov_b32_e32 v117, v0
	v_mov_b32_e32 v118, v0
	v_mov_b32_e32 v119, v0
	v_mov_b32_e32 v72, v0
	v_mov_b32_e32 v73, v0
	v_mov_b32_e32 v74, v0
	v_mov_b32_e32 v75, v0
	v_mov_b32_e32 v76, v0
	v_mov_b32_e32 v77, v0
	v_mov_b32_e32 v78, v0
	v_mov_b32_e32 v79, v0
	v_mov_b32_e32 v88, v0
	v_mov_b32_e32 v89, v0
	v_mov_b32_e32 v90, v0
	v_mov_b32_e32 v91, v0
	v_mov_b32_e32 v92, v0
	v_mov_b32_e32 v93, v0
	v_mov_b32_e32 v94, v0
	v_mov_b32_e32 v95, v0
	v_mov_b32_e32 v104, v0
	v_mov_b32_e32 v105, v0
	v_mov_b32_e32 v106, v0
	v_mov_b32_e32 v107, v0
	v_mov_b32_e32 v108, v0
	v_mov_b32_e32 v109, v0
	v_mov_b32_e32 v110, v0
	v_mov_b32_e32 v111, v0
	v_mov_b32_e32 v120, v0
	v_mov_b32_e32 v121, v0
	v_mov_b32_e32 v122, v0
	v_mov_b32_e32 v123, v0
	v_mov_b32_e32 v124, v0
	v_mov_b32_e32 v125, v0
	v_mov_b32_e32 v126, v0
	v_mov_b32_e32 v127, v0
	v_add_u32_e32 v204, 0x80, v128
	v_add_u32_e32 v205, 0x80, v130
	v_readfirstlane_b32 s101, v206
	s_nop 3
	s_lshr_b32 s101, s101, 8
	s_cmp_eq_u32 s101, 1
	s_cbranch_scc0 .Lprio_skip_0
	s_setprio 1
